# strategy 4: per-segment s_setprio flips removed from the six GEMM K-loops, one static s_setprio 1 for waves 4-7 at GEMM entry, reset after the phase
# speedup vs baseline: 1.0165x; 1.0044x over previous
; #define PG8_WAIT_V(n) asm volatile("s_waitcnt vmcnt(" #n ")" ::: "memory")
; #define PG8_BAR __builtin_amdgcn_s_barrier()
; template <class Epi, class Sched, bool ALIGN_EPI = false, bool SP2 = false>
; __device__ __forceinline__ void gemm_phase(LAS unsigned char* lds, const Gemm g, const Sched& S, const Epi& E, const int tid_) {
;     const int tid = tid_, wid = __builtin_amdgcn_readfirstlane(tid >> 6), lane = tid & 63, wr = wid >> 2, wc = wid & 3, fr = lane & 15, fq = lane >> 4;
;     const int K = g.K, nt = K / BK;
;     unsigned voffA[2], voffB[2];
; #pragma unroll
;     for (int i = 0; i < 2; ++i) { int R, C; stage_rc(tid * 16 + i * 8192, R, C); const int Rb = Epi::PERM ? ((R & ~31) + perm32(R & 31)) : R;
;         voffA[i] = (unsigned)(R * K + C) * 2u; voffB[i] = (unsigned)(Rb * K + C) * 2u; }
;     const size_t kstep = (size_t)(BK * 2);
;     const size_t hstep = (size_t)HALF * K * 2;
;     const size_t tstep = 2 * hstep;
;     const unsigned ldsw = (unsigned)wid * 1024u;
;     const int aoff = lds_byte(wr * 64 + fr, fq * 8), boff = lds_byte(wc * 32 + fr, fq * 8);
;     ...
;     Unit cur, nxt; int ui = 0;
;     if (!S.next(0, cur)) return;
;     f32x4 acc[2][2][4][2];
; #pragma unroll
;     for (int a = 0; a < 2; ++a)
; #pragma unroll
;         for (int b = 0; b < 2; ++b)
; #pragma unroll
;             for (int m = 0; m < 4; ++m)
; #pragma unroll
;                 for (int n = 0; n < 2; ++n) acc[a][b][m][n] = (f32x4){0.f, 0.f, 0.f, 0.f};
;     bf16x8 At[4][2], B0[2][2], B1[2][2];
;     const char* cA = (const char*)g.A + (size_t)cur.pm * tstep; const char* cB = (const char*)g.Bt + (size_t)cur.pn * tstep;
;     S.a_ready(cur);
;     if constexpr (SP2) {
;         PG8_STAGE(PG8_SB(0, 0), cB, voffB); PG8_STAGE(PG8_SB(0, 1), cB + hstep, voffB); PG8_STAGE(PG8_SA(0, 0), cA, voffA); PG8_STAGE(PG8_SA(0, 1), cA + hstep, voffA);
;         if (wr == 1) PG8_BAR;
;         PG8_WAIT_V(2); PG8_BAR;
;         PG8_STAGE(PG8_SB(1, 0), cB + kstep, voffB); PG8_STAGE(PG8_SA(1, 0), cA + kstep, voffA); PG8_STAGE(PG8_SB(1, 1), cB + hstep + kstep, voffB);
;         PG8_WAIT_V(6); PG8_BAR;
;     } else {
;         PG8_STAGE(PG8_SB(0, 0), cB, voffB); PG8_STAGE(PG8_SA(0, 0), cA, voffA); PG8_STAGE(PG8_SB(0, 1), cB + hstep, voffB); PG8_STAGE(PG8_SA(0, 1), cA + hstep, voffA);
;         if (wr == 1) PG8_BAR;
.LBB0_21:
	v_ashrrev_i32_e32 v0, 31, v198
	v_lshrrev_b32_e32 v0, 26, v0
	v_add_u32_e32 v0, v198, v0
	v_ashrrev_i32_e32 v10, 6, v0
	v_bfe_i32 v0, v198, 27, 1
	v_lshlrev_b32_e32 v2, 4, v198
	v_lshrrev_b32_e32 v0, 22, v0
	v_add_u32_e32 v0, v2, v0
	v_and_b32_e32 v0, 0xfffffc00, v0
	v_sub_u32_e32 v0, v2, v0
	v_lshrrev_b32_e32 v3, 4, v0
	v_bitop3_b32 v0, v3, v0, 32 bitop3:0x6c
	v_ashrrev_i32_e32 v4, 31, v0
	v_lshrrev_b32_e32 v4, 26, v4
	v_add_u32_e32 v4, v0, v4
	v_lshlrev_b32_e32 v3, 3, v10
	v_ashrrev_i32_e32 v11, 6, v4
	v_and_b32_e32 v4, 0xc0, v4
	v_and_b32_e32 v3, -16, v3
	v_sub_u32_e32 v0, v0, v4
	v_add_u32_e32 v3, v11, v3
	v_ashrrev_i16_sdwa v0, v230, sext(v0) dst_sel:DWORD dst_unused:UNUSED_PAD src0_sel:DWORD src1_sel:BYTE_0
	v_lshlrev_b32_e32 v5, 5, v10
	v_bfe_i32 v12, v0, 0, 16
	v_lshlrev_b32_e32 v0, 1, v3
	v_lshrrev_b32_e32 v4, 2, v3
	v_and_b32_e32 v6, 3, v11
	s_mov_b32 s9, 0xfffe0
	v_and_b32_e32 v5, 32, v5
	v_and_b32_e32 v0, 24, v0
	v_and_b32_e32 v4, 4, v4
	v_and_or_b32 v6, v3, s9, v6
	v_or3_b32 v0, v6, v4, v0
	v_add_lshl_u32 v4, v5, v12, 1
	v_add_u32_e32 v2, 0x2000, v2
	v_lshl_add_u32 v130, v3, 12, v4
	v_ashrrev_i32_e32 v3, 31, v2
	v_lshrrev_b32_e32 v3, 22, v3
	v_add_u32_e32 v3, v2, v3
	v_ashrrev_i32_e32 v13, 10, v3
	v_mul_i32_i24_e32 v3, 0x400, v13
	v_sub_u32_e32 v2, v2, v3
	v_lshrrev_b32_e32 v3, 4, v2
	v_bitop3_b32 v2, v3, v2, 32 bitop3:0x6c
	s_ashr_i32 s8, s11, 3
	v_lshl_add_u32 v0, v0, 12, v4
	v_ashrrev_i32_e32 v4, 31, v2
	s_add_u32 s29, s4, 0x9800000
	v_lshrrev_b32_e32 v4, 26, v4
	s_addc_u32 s30, s5, 0
	v_lshlrev_b32_e32 v3, 3, v13
	v_add_u32_e32 v4, v2, v4
	s_add_u32 s31, s4, 0x1800000
	v_and_b32_e32 v3, -16, v3
	v_ashrrev_i32_e32 v14, 6, v4
	s_addc_u32 s54, s5, 0
	v_add_u32_e32 v3, v14, v3
	v_and_b32_e32 v6, 3, v14
	s_add_i32 s8, s10, s8
	v_and_or_b32 v6, v3, s9, v6
	s_ashr_i32 s9, s8, 31
	s_lshr_b32 s9, s9, 24
	s_add_i32 s9, s8, s9
	s_ashr_i32 s10, s9, 8
	s_and_b32 s9, s9, 0xff00
	s_sub_i32 s8, s8, s9
	s_sext_i32_i16 s9, s8
	s_bfe_u32 s9, s9, 0x3001c
	s_add_i32 s9, s8, s9
	s_lshl_b32 s11, s10, 3
	s_sext_i32_i16 s10, s9
	s_and_b32 s9, s9, 0xfff8
	s_sub_i32 s8, s8, s9
	s_sext_i32_i16 s8, s8
	s_lshr_b32 s10, s10, 3
	s_add_i32 s44, s11, s8
	v_and_b32_e32 v4, 0xc0, v4
	s_ashr_i32 s14, s12, 6
	s_ashr_i32 s45, s44, 31
	s_bfe_i64 s[16:17], s[10:11], 0x100000
	s_ashr_i32 s13, s12, 8
	v_sub_u32_e32 v2, v2, v4
	s_lshl_b32 s55, s14, 10
	s_lshl_b64 s[8:9], s[44:45], 20
	s_lshl_b64 s[16:17], s[16:17], 20
	v_ashrrev_i16_sdwa v2, v230, sext(v2) dst_sel:DWORD dst_unused:UNUSED_PAD src0_sel:DWORD src1_sel:BYTE_0
	s_add_u32 s48, s31, s16
	v_lshlrev_b32_e32 v5, 5, v13
	v_bfe_i32 v15, v2, 0, 16
	v_lshlrev_b32_e32 v2, 1, v3
	v_lshrrev_b32_e32 v4, 2, v3
	s_addc_u32 s49, s54, s17
	s_add_i32 s45, s55, 0
	v_and_b32_e32 v5, 32, v5
	v_and_b32_e32 v2, 24, v2
	v_and_b32_e32 v4, 4, v4
	s_add_i32 m0, s45, 0x10000
	v_or3_b32 v2, v6, v4, v2
	v_add_lshl_u32 v4, v5, v15, 1
	global_load_lds_dwordx4 v0, s[48:49]
	s_add_i32 m0, s45, 0x12000
	v_lshl_add_u32 v134, v2, 12, v4
	s_add_u32 s16, s48, 0x80000
	global_load_lds_dwordx4 v134, s[48:49]
	s_addc_u32 s17, s49, 0
	s_add_i32 m0, s45, 0x14000
	v_lshl_add_u32 v132, v3, 12, v4
	global_load_lds_dwordx4 v0, s[16:17]
	s_add_i32 m0, s45, 0x16000
	s_add_u32 s46, s29, s8
	s_addc_u32 s47, s30, s9
	s_add_i32 s56, s45, 0x2000
	global_load_lds_dwordx4 v134, s[16:17]
	s_mov_b32 m0, s45
	s_add_u32 s8, s46, 0x80000
	global_load_lds_dwordx4 v130, s[46:47]
	s_mov_b32 m0, s56
	s_addc_u32 s9, s47, 0
	s_add_i32 s57, s45, 0x4000
	global_load_lds_dwordx4 v132, s[46:47]
	s_mov_b32 m0, s57
	s_add_i32 s58, s45, 0x6000
	global_load_lds_dwordx4 v130, s[8:9]
	s_mov_b32 m0, s58
	s_load_dword s59, s[94:95], 0x0
	global_load_lds_dwordx4 v132, s[8:9]
	v_mov_b32_e32 v135, v1
	v_mov_b32_e32 v131, v1
	v_mov_b32_e32 v133, v1
	s_cmp_eq_u32 s13, 1
	v_lshl_add_u64 v[8:9], s[48:49], 0, v[0:1]
	v_lshl_add_u64 v[6:7], s[48:49], 0, v[134:135]
	v_lshl_add_u64 v[2:3], s[46:47], 0, v[130:131]
	s_cselect_b64 s[8:9], -1, 0
	s_cmp_lg_u32 s13, 1
	v_lshl_add_u64 v[4:5], s[46:47], 0, v[132:133]
	s_cbranch_scc1 .LBB0_23
	s_setprio 1
	s_barrier

; #define PG8_STAGE(bufoff, gbase, voff) do { _Pragma("unroll") for (int _i = 0; _i < 2; ++_i) \
;         __builtin_amdgcn_global_load_lds((const unsigned*)((const char*)(gbase) + (voff)[_i]), (LAS unsigned*)(lds + (bufoff) + ldsw + _i * 8192), 16, 0, 0); } while (0)
; #define PG8_LDA(dst, b, h) do { _Pragma("unroll") for (int m = 0; m < 4; ++m) _Pragma("unroll") for (int k = 0; k < 2; ++k) dst[m][k] = *(const LAS bf16x8*)(lds + PG8_SA(b, h) + aoff + m * 2048 + k * 1024); } while (0)
; #define PG8_LDB(dst, b, h) do { _Pragma("unroll") for (int n = 0; n < 2; ++n) _Pragma("unroll") for (int k = 0; k < 2; ++k) dst[n][k] = *(const LAS bf16x8*)(lds + PG8_SB(b, h) + boff + n * 2048 + k * 1024); } while (0)
; #define PG8_MMA(ai, bj, At, Bt) do { __builtin_amdgcn_s_setprio(1); _Pragma("unroll") for (int m = 0; m < 4; ++m) _Pragma("unroll") for (int n = 0; n < 2; ++n) _Pragma("unroll") for (int k = 0; k < 2; ++k) \
;         acc[ai][bj][m][n] = __builtin_amdgcn_mfma_f32_16x16x32_bf16(Bt[n][k], At[m][k], acc[ai][bj][m][n], 0, 0, 0); __builtin_amdgcn_s_setprio(0); } while (0)
; #define PG8_BAR __builtin_amdgcn_s_barrier()
; template <class Epi, class Sched, bool ALIGN_EPI = false, bool SP2 = false>
; __device__ __forceinline__ void gemm_phase(LAS unsigned char* lds, const Gemm g, const Sched& S, const Epi& E, const int tid_) {
;     ...
;         const bool has_next = S.next(ui + 1, nxt);
;         const char* nA = has_next ? (const char*)g.A + (size_t)nxt.pm * tstep : cA; const char* nB = has_next ? (const char*)g.Bt + (size_t)nxt.pn * tstep : cB;
;         for (int t = 0; t < nt; t += 2) {
;             const bool last = (t == nt - 2);
;             const char* a1 = cA + (size_t)(t + 1) * kstep;
;             const char* a2 = last ? nA : cA + (size_t)(t + 2) * kstep; const char* b2 = last ? nB : cB + (size_t)(t + 2) * kstep;
;             const char* a3 = a2 + kstep; const char* b3 = b2 + kstep;
;             if (last && has_next) S.a_ready(nxt);
;             if constexpr (SP2) {
;             PG8_LDB(B0, 0, 0); PG8_LDB(B1, 0, 1); PG8_SCHED; PG8_LDA(At, 0, 0); PG8_STAGE(PG8_SA(1, 1), a1 + hstep, voffA);
;             PG8_WAIT_V(8); PG8_WAIT_L(0); PG8_BAR; PG8_MMA(0, 0, At, B0); PG8_MMA(0, 1, At, B1); PG8_BAR; PG8_SCHED;
;             PG8_LDA(At, 0, 1); PG8_STAGE(PG8_SB(0, 0), b2, voffB); PG8_STAGE(PG8_SB(0, 1), b2 + hstep, voffB); PG8_STAGE(PG8_SA(0, 0), a2, voffA);
.LBB0_34:
	s_add_u32 s48, s46, 0xfff80080
	s_addc_u32 s49, s47, -1
	s_add_i32 s68, 0, 0x10000
	s_cmp_eq_u32 s67, 28
	s_cselect_b32 s51, s17, s49
	s_cselect_b32 s50, s21, s48
	v_add_u32_e32 v140, s68, v143
	s_cselect_b32 s49, s15, s66
	s_cselect_b32 s48, s64, s65
	s_add_i32 s70, 0, 0x14000
	s_nop 0
	ds_read_b128 v[146:149], v140
	ds_read_b128 v[150:153], v140 offset:1024
	ds_read_b128 v[154:157], v140 offset:2048
	ds_read_b128 v[158:161], v140 offset:3072
	v_add_u32_e32 v140, s70, v143
	ds_read_b128 v[162:165], v140
	ds_read_b128 v[166:169], v140 offset:1024
	ds_read_b128 v[170:173], v140 offset:2048
	ds_read_b128 v[174:177], v140 offset:3072
	s_add_i32 m0, s45, 0xc000
	ds_read_b128 v[178:181], v145
	ds_read_b128 v[182:185], v145 offset:1024
	ds_read_b128 v[200:203], v145 offset:2048
	ds_read_b128 v[204:207], v145 offset:3072
	ds_read_b128 v[208:211], v145 offset:4096
	ds_read_b128 v[212:215], v145 offset:5120
	ds_read_b128 v[216:219], v145 offset:6144
	ds_read_b128 v[220:223], v145 offset:7168
	global_load_lds_dwordx4 v136, s[46:47]
	s_add_i32 m0, s45, 0xe000
	s_nop 0
	global_load_lds_dwordx4 v138, s[46:47]
	s_waitcnt vmcnt(8)
	s_waitcnt lgkmcnt(0)
	s_barrier
	s_waitcnt lgkmcnt(0)
	v_mfma_f32_16x16x32_bf16 v[126:129], v[146:149], v[178:181], v[126:129]
	v_mfma_f32_16x16x32_bf16 v[122:125], v[154:157], v[178:181], v[122:125]
	v_mfma_f32_16x16x32_bf16 v[110:113], v[146:149], v[200:203], v[110:113]
	v_mfma_f32_16x16x32_bf16 v[106:109], v[154:157], v[200:203], v[106:109]
	v_mfma_f32_16x16x32_bf16 v[94:97], v[146:149], v[208:211], v[94:97]
	v_mfma_f32_16x16x32_bf16 v[90:93], v[154:157], v[208:211], v[90:93]
	v_mfma_f32_16x16x32_bf16 v[78:81], v[146:149], v[216:219], v[78:81]
	v_mfma_f32_16x16x32_bf16 v[74:77], v[154:157], v[216:219], v[74:77]
	v_mfma_f32_16x16x32_bf16 v[126:129], v[150:153], v[182:185], v[126:129]
	v_mfma_f32_16x16x32_bf16 v[122:125], v[158:161], v[182:185], v[122:125]
	v_mfma_f32_16x16x32_bf16 v[110:113], v[150:153], v[204:207], v[110:113]
	v_mfma_f32_16x16x32_bf16 v[106:109], v[158:161], v[204:207], v[106:109]
	v_mfma_f32_16x16x32_bf16 v[94:97], v[150:153], v[212:215], v[94:97]
	v_mfma_f32_16x16x32_bf16 v[90:93], v[158:161], v[212:215], v[90:93]
	v_mfma_f32_16x16x32_bf16 v[78:81], v[150:153], v[220:223], v[78:81]
	v_mfma_f32_16x16x32_bf16 v[74:77], v[158:161], v[220:223], v[74:77]
	v_mfma_f32_16x16x32_bf16 v[118:121], v[162:165], v[178:181], v[118:121]
	v_mfma_f32_16x16x32_bf16 v[114:117], v[170:173], v[178:181], v[114:117]
	v_mfma_f32_16x16x32_bf16 v[102:105], v[162:165], v[200:203], v[102:105]
	v_mfma_f32_16x16x32_bf16 v[98:101], v[170:173], v[200:203], v[98:101]
	v_mfma_f32_16x16x32_bf16 v[86:89], v[162:165], v[208:211], v[86:89]
	v_mfma_f32_16x16x32_bf16 v[82:85], v[170:173], v[208:211], v[82:85]
	v_mfma_f32_16x16x32_bf16 v[70:73], v[162:165], v[216:219], v[70:73]
	v_mfma_f32_16x16x32_bf16 v[66:69], v[170:173], v[216:219], v[66:69]
	v_mfma_f32_16x16x32_bf16 v[118:121], v[166:169], v[182:185], v[118:121]
	v_mfma_f32_16x16x32_bf16 v[114:117], v[174:177], v[182:185], v[114:117]
	v_mfma_f32_16x16x32_bf16 v[102:105], v[166:169], v[204:207], v[102:105]
	v_mfma_f32_16x16x32_bf16 v[98:101], v[174:177], v[204:207], v[98:101]
	v_mfma_f32_16x16x32_bf16 v[86:89], v[166:169], v[212:215], v[86:89]
	v_mfma_f32_16x16x32_bf16 v[82:85], v[174:177], v[212:215], v[82:85]
	v_mfma_f32_16x16x32_bf16 v[70:73], v[166:169], v[220:223], v[70:73]
	v_mfma_f32_16x16x32_bf16 v[66:69], v[174:177], v[220:223], v[66:69]
	s_barrier
	s_add_i32 s68, s68, s55
	s_mov_b32 m0, s68
	ds_read_b128 v[178:181], v145 offset:16384
	ds_read_b128 v[182:185], v145 offset:17408
	ds_read_b128 v[200:203], v145 offset:18432
	ds_read_b128 v[204:207], v145 offset:19456
	ds_read_b128 v[208:211], v145 offset:20480
	ds_read_b128 v[212:215], v145 offset:21504
	ds_read_b128 v[216:219], v145 offset:22528
	ds_read_b128 v[220:223], v145 offset:23552
	global_load_lds_dwordx4 v0, s[48:49]
	s_add_i32 m0, s68, 0x2000
	s_add_u32 s68, s48, 0x80000
	v_lshl_add_u64 v[192:193], s[48:49], 0, v[134:135]
	s_addc_u32 s69, s49, 0
	s_add_i32 s70, s70, s55
	global_load_lds_dwordx4 v134, s[48:49]
	s_mov_b32 m0, s70
	v_lshl_add_u64 v[236:237], s[50:51], 0, v[132:133]
	global_load_lds_dwordx4 v0, s[68:69]
	s_add_i32 m0, s70, 0x2000
	s_nop 0
	global_load_lds_dwordx4 v134, s[68:69]
	v_lshl_add_u64 v[224:225], s[50:51], 0, v[130:131]
	s_mov_b32 m0, s45
	s_nop 0
	global_load_lds_dwordx4 v130, s[50:51]
	s_mov_b32 m0, s56
	s_nop 0
	global_load_lds_dwordx4 v132, s[50:51]
	s_waitcnt vmcnt(8)
	s_waitcnt lgkmcnt(0)
	s_barrier
; #define PG8_STAGE(bufoff, gbase, voff) do { _Pragma("unroll") for (int _i = 0; _i < 2; ++_i) \
;         __builtin_amdgcn_global_load_lds((const unsigned*)((const char*)(gbase) + (voff)[_i]), (LAS unsigned*)(lds + (bufoff) + ldsw + _i * 8192), 16, 0, 0); } while (0)
; #define PG8_LDA(dst, b, h) do { _Pragma("unroll") for (int m = 0; m < 4; ++m) _Pragma("unroll") for (int k = 0; k < 2; ++k) dst[m][k] = *(const LAS bf16x8*)(lds + PG8_SA(b, h) + aoff + m * 2048 + k * 1024); } while (0)
; #define PG8_LDB(dst, b, h) do { _Pragma("unroll") for (int n = 0; n < 2; ++n) _Pragma("unroll") for (int k = 0; k < 2; ++k) dst[n][k] = *(const LAS bf16x8*)(lds + PG8_SB(b, h) + boff + n * 2048 + k * 1024); } while (0)
; #define PG8_MMA(ai, bj, At, Bt) do { __builtin_amdgcn_s_setprio(1); _Pragma("unroll") for (int m = 0; m < 4; ++m) _Pragma("unroll") for (int n = 0; n < 2; ++n) _Pragma("unroll") for (int k = 0; k < 2; ++k) \
;         acc[ai][bj][m][n] = __builtin_amdgcn_mfma_f32_16x16x32_bf16(Bt[n][k], At[m][k], acc[ai][bj][m][n], 0, 0, 0); __builtin_amdgcn_s_setprio(0); } while (0)
; #define PG8_WAIT_V(n) asm volatile("s_waitcnt vmcnt(" #n ")" ::: "memory")
; #define PG8_WAIT_L(n) asm volatile("s_waitcnt lgkmcnt(" #n ")" ::: "memory")
; #define PG8_BAR __builtin_amdgcn_s_barrier()
; #define PG8_SCHED __builtin_amdgcn_sched_barrier(0)
; template <class Epi, class Sched, bool ALIGN_EPI = false, bool SP2 = false>
; __device__ __forceinline__ void gemm_phase(LAS unsigned char* lds, const Gemm g, const Sched& S, const Epi& E, const int tid_) {
;     ...
;             PG8_WAIT_V(8); PG8_WAIT_L(0); PG8_BAR; PG8_MMA(1, 0, At, B0); PG8_MMA(1, 1, At, B1); PG8_BAR; PG8_SCHED;
;             PG8_LDB(B0, 1, 0); PG8_LDB(B1, 1, 1); PG8_SCHED; PG8_LDA(At, 1, 0); PG8_STAGE(PG8_SA(0, 1), a2 + hstep, voffA);
;             PG8_WAIT_V(8); PG8_WAIT_L(0); PG8_BAR; PG8_MMA(0, 0, At, B0); PG8_MMA(0, 1, At, B1); PG8_BAR; PG8_SCHED;
	s_waitcnt lgkmcnt(0)
	v_mfma_f32_16x16x32_bf16 v[62:65], v[146:149], v[178:181], v[62:65]
	v_mfma_f32_16x16x32_bf16 v[58:61], v[154:157], v[178:181], v[58:61]
	v_mfma_f32_16x16x32_bf16 v[46:49], v[146:149], v[200:203], v[46:49]
	v_mfma_f32_16x16x32_bf16 v[42:45], v[154:157], v[200:203], v[42:45]
	v_mfma_f32_16x16x32_bf16 v[30:33], v[146:149], v[208:211], v[30:33]
	v_mfma_f32_16x16x32_bf16 v[26:29], v[154:157], v[208:211], v[26:29]
	v_mfma_f32_16x16x32_bf16 v[14:17], v[146:149], v[216:219], v[14:17]
	v_mfma_f32_16x16x32_bf16 v[10:13], v[154:157], v[216:219], v[10:13]
	v_mfma_f32_16x16x32_bf16 v[62:65], v[150:153], v[182:185], v[62:65]
	v_mfma_f32_16x16x32_bf16 v[58:61], v[158:161], v[182:185], v[58:61]
	v_mfma_f32_16x16x32_bf16 v[46:49], v[150:153], v[204:207], v[46:49]
	v_mfma_f32_16x16x32_bf16 v[42:45], v[158:161], v[204:207], v[42:45]
	v_mfma_f32_16x16x32_bf16 v[30:33], v[150:153], v[212:215], v[30:33]
	v_mfma_f32_16x16x32_bf16 v[26:29], v[158:161], v[212:215], v[26:29]
	v_mfma_f32_16x16x32_bf16 v[14:17], v[150:153], v[220:223], v[14:17]
	v_mfma_f32_16x16x32_bf16 v[10:13], v[158:161], v[220:223], v[10:13]
	v_mfma_f32_16x16x32_bf16 v[54:57], v[162:165], v[178:181], v[54:57]
	v_mfma_f32_16x16x32_bf16 v[50:53], v[170:173], v[178:181], v[50:53]
	v_mfma_f32_16x16x32_bf16 v[38:41], v[162:165], v[200:203], v[38:41]
	v_mfma_f32_16x16x32_bf16 v[34:37], v[170:173], v[200:203], v[34:37]
	v_mfma_f32_16x16x32_bf16 v[22:25], v[162:165], v[208:211], v[22:25]
	v_mfma_f32_16x16x32_bf16 v[18:21], v[170:173], v[208:211], v[18:21]
	v_mfma_f32_16x16x32_bf16 v[6:9], v[162:165], v[216:219], v[6:9]
	v_mfma_f32_16x16x32_bf16 v[2:5], v[170:173], v[216:219], v[2:5]
	v_mfma_f32_16x16x32_bf16 v[54:57], v[166:169], v[182:185], v[54:57]
	v_mfma_f32_16x16x32_bf16 v[50:53], v[174:177], v[182:185], v[50:53]
	v_mfma_f32_16x16x32_bf16 v[38:41], v[166:169], v[204:207], v[38:41]
	v_mfma_f32_16x16x32_bf16 v[34:37], v[174:177], v[204:207], v[34:37]
	v_mfma_f32_16x16x32_bf16 v[22:25], v[166:169], v[212:215], v[22:25]
	v_mfma_f32_16x16x32_bf16 v[18:21], v[174:177], v[212:215], v[18:21]
	v_mfma_f32_16x16x32_bf16 v[6:9], v[166:169], v[220:223], v[6:9]
	v_mfma_f32_16x16x32_bf16 v[2:5], v[174:177], v[220:223], v[2:5]
	s_barrier
	s_add_i32 s68, 0, 0x18000
	s_add_i32 s69, 0, 0x1c000
	v_add_u32_e32 v158, s68, v143
	v_add_u32_e32 v174, s69, v143
	ds_read_b128 v[146:149], v158
	ds_read_b128 v[150:153], v158 offset:1024
	ds_read_b128 v[154:157], v158 offset:2048
	ds_read_b128 v[158:161], v158 offset:3072
	ds_read_b128 v[162:165], v174
	ds_read_b128 v[166:169], v174 offset:1024
	ds_read_b128 v[170:173], v174 offset:2048
	ds_read_b128 v[174:177], v174 offset:3072
	s_add_u32 s50, s50, 0x80000
	s_addc_u32 s51, s51, 0
	s_mov_b32 m0, s57
	ds_read_b128 v[178:181], v145 offset:32768
	ds_read_b128 v[182:185], v145 offset:33792
	ds_read_b128 v[200:203], v145 offset:34816
	ds_read_b128 v[204:207], v145 offset:35840
	ds_read_b128 v[208:211], v145 offset:36864
	ds_read_b128 v[212:215], v145 offset:37888
	ds_read_b128 v[216:219], v145 offset:38912
	ds_read_b128 v[220:223], v145 offset:39936
	global_load_lds_dwordx4 v130, s[50:51]
	s_mov_b32 m0, s58
	s_nop 0
	global_load_lds_dwordx4 v132, s[50:51]
	s_waitcnt vmcnt(8)
	s_waitcnt lgkmcnt(0)
	s_barrier
	s_waitcnt lgkmcnt(0)
	v_mfma_f32_16x16x32_bf16 v[126:129], v[146:149], v[178:181], v[126:129]
	v_mfma_f32_16x16x32_bf16 v[122:125], v[154:157], v[178:181], v[122:125]
	v_mfma_f32_16x16x32_bf16 v[110:113], v[146:149], v[200:203], v[110:113]
	v_mfma_f32_16x16x32_bf16 v[106:109], v[154:157], v[200:203], v[106:109]
	v_mfma_f32_16x16x32_bf16 v[94:97], v[146:149], v[208:211], v[94:97]
	v_mfma_f32_16x16x32_bf16 v[90:93], v[154:157], v[208:211], v[90:93]
	v_mfma_f32_16x16x32_bf16 v[78:81], v[146:149], v[216:219], v[78:81]
	v_mfma_f32_16x16x32_bf16 v[74:77], v[154:157], v[216:219], v[74:77]
	v_mfma_f32_16x16x32_bf16 v[126:129], v[150:153], v[182:185], v[126:129]
	v_mfma_f32_16x16x32_bf16 v[122:125], v[158:161], v[182:185], v[122:125]
	v_mfma_f32_16x16x32_bf16 v[110:113], v[150:153], v[204:207], v[110:113]
	v_mfma_f32_16x16x32_bf16 v[106:109], v[158:161], v[204:207], v[106:109]
	v_mfma_f32_16x16x32_bf16 v[94:97], v[150:153], v[212:215], v[94:97]
	v_mfma_f32_16x16x32_bf16 v[90:93], v[158:161], v[212:215], v[90:93]
	v_mfma_f32_16x16x32_bf16 v[78:81], v[150:153], v[220:223], v[78:81]
	v_mfma_f32_16x16x32_bf16 v[74:77], v[158:161], v[220:223], v[74:77]
	v_mfma_f32_16x16x32_bf16 v[118:121], v[162:165], v[178:181], v[118:121]
	v_mfma_f32_16x16x32_bf16 v[114:117], v[170:173], v[178:181], v[114:117]
	v_mfma_f32_16x16x32_bf16 v[102:105], v[162:165], v[200:203], v[102:105]
	v_mfma_f32_16x16x32_bf16 v[98:101], v[170:173], v[200:203], v[98:101]
	v_mfma_f32_16x16x32_bf16 v[86:89], v[162:165], v[208:211], v[86:89]
	v_mfma_f32_16x16x32_bf16 v[82:85], v[170:173], v[208:211], v[82:85]
	v_mfma_f32_16x16x32_bf16 v[70:73], v[162:165], v[216:219], v[70:73]
	v_mfma_f32_16x16x32_bf16 v[66:69], v[170:173], v[216:219], v[66:69]
	v_mfma_f32_16x16x32_bf16 v[118:121], v[166:169], v[182:185], v[118:121]
	v_mfma_f32_16x16x32_bf16 v[114:117], v[174:177], v[182:185], v[114:117]
	v_mfma_f32_16x16x32_bf16 v[102:105], v[166:169], v[204:207], v[102:105]
	v_mfma_f32_16x16x32_bf16 v[98:101], v[174:177], v[204:207], v[98:101]
	v_mfma_f32_16x16x32_bf16 v[86:89], v[166:169], v[212:215], v[86:89]
	v_mfma_f32_16x16x32_bf16 v[82:85], v[174:177], v[212:215], v[82:85]
	v_mfma_f32_16x16x32_bf16 v[70:73], v[166:169], v[220:223], v[70:73]
	v_mfma_f32_16x16x32_bf16 v[66:69], v[174:177], v[220:223], v[66:69]
	s_barrier
; #define PG8_STAGE(bufoff, gbase, voff) do { _Pragma("unroll") for (int _i = 0; _i < 2; ++_i) \
;         __builtin_amdgcn_global_load_lds((const unsigned*)((const char*)(gbase) + (voff)[_i]), (LAS unsigned*)(lds + (bufoff) + ldsw + _i * 8192), 16, 0, 0); } while (0)
; #define PG8_LDA(dst, b, h) do { _Pragma("unroll") for (int m = 0; m < 4; ++m) _Pragma("unroll") for (int k = 0; k < 2; ++k) dst[m][k] = *(const LAS bf16x8*)(lds + PG8_SA(b, h) + aoff + m * 2048 + k * 1024); } while (0)
; #define PG8_MMA(ai, bj, At, Bt) do { __builtin_amdgcn_s_setprio(1); _Pragma("unroll") for (int m = 0; m < 4; ++m) _Pragma("unroll") for (int n = 0; n < 2; ++n) _Pragma("unroll") for (int k = 0; k < 2; ++k) \
;         acc[ai][bj][m][n] = __builtin_amdgcn_mfma_f32_16x16x32_bf16(Bt[n][k], At[m][k], acc[ai][bj][m][n], 0, 0, 0); __builtin_amdgcn_s_setprio(0); } while (0)
; #define PG8_WAIT_V(n) asm volatile("s_waitcnt vmcnt(" #n ")" ::: "memory")
; #define PG8_WAIT_L(n) asm volatile("s_waitcnt lgkmcnt(" #n ")" ::: "memory")
; #define PG8_BAR __builtin_amdgcn_s_barrier()
; #define PG8_SCHED __builtin_amdgcn_sched_barrier(0)
; template <class Epi, class Sched, bool ALIGN_EPI = false, bool SP2 = false>
; __device__ __forceinline__ void gemm_phase(LAS unsigned char* lds, const Gemm g, const Sched& S, const Epi& E, const int tid_) {
;     ...
;             PG8_LDA(At, 1, 1); PG8_STAGE(PG8_SB(1, 0), b3, voffB); PG8_STAGE(PG8_SB(1, 1), b3 + hstep, voffB); PG8_STAGE(PG8_SA(1, 0), a3, voffA);
;             PG8_WAIT_V(8); PG8_WAIT_L(0); PG8_BAR; PG8_MMA(1, 0, At, B0); PG8_MMA(1, 1, At, B1); PG8_BAR; PG8_SCHED;
	s_add_i32 s50, s68, s55
	s_add_i32 m0, s50, 0xffffff80
	ds_read_b128 v[178:181], v145 offset:49152
	ds_read_b128 v[182:185], v145 offset:50176
	ds_read_b128 v[200:203], v145 offset:51200
	ds_read_b128 v[204:207], v145 offset:52224
	ds_read_b128 v[208:211], v145 offset:53248
	ds_read_b128 v[212:215], v145 offset:54272
	ds_read_b128 v[216:219], v145 offset:55296
	ds_read_b128 v[220:223], v145 offset:56320
	global_load_lds_dwordx4 v0, s[48:49] offset:128
	s_add_i32 m0, s50, 0x2000
	s_add_u32 s48, s48, 0x80080
	v_lshl_add_u64 v[140:141], v[192:193], 0, s[96:97]
	s_addc_u32 s49, s49, 0
	s_add_i32 s50, s69, s55
	global_load_lds_dwordx4 v[140:141], off
	s_mov_b32 m0, s50
	s_nop 0
	global_load_lds_dwordx4 v0, s[48:49]
	s_add_i32 m0, s50, 0x2000
	s_nop 0
	global_load_lds_dwordx4 v134, s[48:49]
	v_lshl_add_u64 v[140:141], v[224:225], 0, s[96:97]
	s_mov_b32 m0, s60
	s_nop 0
	global_load_lds_dwordx4 v[140:141], off
	v_lshl_add_u64 v[140:141], v[236:237], 0, s[96:97]
	s_mov_b32 m0, s61
	s_nop 0
	global_load_lds_dwordx4 v[140:141], off
	s_waitcnt vmcnt(8)
	s_waitcnt lgkmcnt(0)
	s_barrier
	s_waitcnt lgkmcnt(0)
	v_mfma_f32_16x16x32_bf16 v[62:65], v[146:149], v[178:181], v[62:65]
	v_mfma_f32_16x16x32_bf16 v[58:61], v[154:157], v[178:181], v[58:61]
	v_mfma_f32_16x16x32_bf16 v[46:49], v[146:149], v[200:203], v[46:49]
	v_mfma_f32_16x16x32_bf16 v[42:45], v[154:157], v[200:203], v[42:45]
	v_mfma_f32_16x16x32_bf16 v[30:33], v[146:149], v[208:211], v[30:33]
	v_mfma_f32_16x16x32_bf16 v[26:29], v[154:157], v[208:211], v[26:29]
	v_mfma_f32_16x16x32_bf16 v[14:17], v[146:149], v[216:219], v[14:17]
	v_mfma_f32_16x16x32_bf16 v[10:13], v[154:157], v[216:219], v[10:13]
	v_mfma_f32_16x16x32_bf16 v[62:65], v[150:153], v[182:185], v[62:65]
	v_mfma_f32_16x16x32_bf16 v[58:61], v[158:161], v[182:185], v[58:61]
	v_mfma_f32_16x16x32_bf16 v[46:49], v[150:153], v[204:207], v[46:49]
	v_mfma_f32_16x16x32_bf16 v[42:45], v[158:161], v[204:207], v[42:45]
	v_mfma_f32_16x16x32_bf16 v[30:33], v[150:153], v[212:215], v[30:33]
	v_mfma_f32_16x16x32_bf16 v[26:29], v[158:161], v[212:215], v[26:29]
	v_mfma_f32_16x16x32_bf16 v[14:17], v[150:153], v[220:223], v[14:17]
	v_mfma_f32_16x16x32_bf16 v[10:13], v[158:161], v[220:223], v[10:13]
	v_mfma_f32_16x16x32_bf16 v[54:57], v[162:165], v[178:181], v[54:57]
	v_mfma_f32_16x16x32_bf16 v[50:53], v[170:173], v[178:181], v[50:53]
	v_mfma_f32_16x16x32_bf16 v[38:41], v[162:165], v[200:203], v[38:41]
	v_mfma_f32_16x16x32_bf16 v[34:37], v[170:173], v[200:203], v[34:37]
	v_mfma_f32_16x16x32_bf16 v[22:25], v[162:165], v[208:211], v[22:25]
	v_mfma_f32_16x16x32_bf16 v[18:21], v[170:173], v[208:211], v[18:21]
	v_mfma_f32_16x16x32_bf16 v[6:9], v[162:165], v[216:219], v[6:9]
	v_mfma_f32_16x16x32_bf16 v[2:5], v[170:173], v[216:219], v[2:5]
	v_mfma_f32_16x16x32_bf16 v[54:57], v[166:169], v[182:185], v[54:57]
	v_mfma_f32_16x16x32_bf16 v[50:53], v[174:177], v[182:185], v[50:53]
	v_mfma_f32_16x16x32_bf16 v[38:41], v[166:169], v[204:207], v[38:41]
	v_mfma_f32_16x16x32_bf16 v[34:37], v[174:177], v[204:207], v[34:37]
	v_mfma_f32_16x16x32_bf16 v[22:25], v[166:169], v[212:215], v[22:25]
	v_mfma_f32_16x16x32_bf16 v[18:21], v[174:177], v[212:215], v[18:21]
	v_mfma_f32_16x16x32_bf16 v[6:9], v[166:169], v[220:223], v[6:9]
	v_mfma_f32_16x16x32_bf16 v[2:5], v[174:177], v[220:223], v[2:5]
	s_barrier
	s_add_i32 s67, s67, 2
	s_add_u32 s46, s46, 0x100
	s_addc_u32 s47, s47, 0
	s_add_u32 s65, s65, 0x100
	s_addc_u32 s66, s66, 0
	s_cmp_gt_u32 s67, 29
	s_cbranch_scc0 .LBB0_34
	s_andn2_b64 vcc, s[12:13], s[40:41]
	s_cbranch_vccz .LBB0_37
	s_barrier

; #define PG8_WAIT_V(n) asm volatile("s_waitcnt vmcnt(" #n ")" ::: "memory")
; #define PG8_BAR __builtin_amdgcn_s_barrier()
; template <class Epi, class Sched, bool ALIGN_EPI = false, bool SP2 = false>
; __device__ __forceinline__ void gemm_phase(LAS unsigned char* lds, const Gemm g, const Sched& S, const Epi& E, const int tid_) {
;     ...
;     PG8_WAIT_V(0);
;     if constexpr (!ALIGN_EPI) { if (wr == 0) PG8_BAR; }
;     PG8_BAR;
.LBB0_42:
	s_waitcnt vmcnt(0)
	s_barrier
	s_setprio 0

; #define PG8_WAIT_V(n) asm volatile("s_waitcnt vmcnt(" #n ")" ::: "memory")
; #define PG8_BAR __builtin_amdgcn_s_barrier()
; template <class Epi, class Sched, bool ALIGN_EPI = false, bool SP2 = false>
; __device__ __forceinline__ void gemm_phase(LAS unsigned char* lds, const Gemm g, const Sched& S, const Epi& E, const int tid_) {
;     const int tid = tid_, wid = __builtin_amdgcn_readfirstlane(tid >> 6), lane = tid & 63, wr = wid >> 2, wc = wid & 3, fr = lane & 15, fq = lane >> 4;
;     const int K = g.K, nt = K / BK;
;     unsigned voffA[2], voffB[2];
; #pragma unroll
;     for (int i = 0; i < 2; ++i) { int R, C; stage_rc(tid * 16 + i * 8192, R, C); const int Rb = Epi::PERM ? ((R & ~31) + perm32(R & 31)) : R;
;         voffA[i] = (unsigned)(R * K + C) * 2u; voffB[i] = (unsigned)(Rb * K + C) * 2u; }
;     const size_t kstep = (size_t)(BK * 2);
;     const size_t hstep = (size_t)HALF * K * 2;
;     const size_t tstep = 2 * hstep;
;     const unsigned ldsw = (unsigned)wid * 1024u;
;     const int aoff = lds_byte(wr * 64 + fr, fq * 8), boff = lds_byte(wc * 32 + fr, fq * 8);
;     ...
;     Unit cur, nxt; int ui = 0;
;     if (!S.next(0, cur)) return;
;     f32x4 acc[2][2][4][2];
; #pragma unroll
;     for (int a = 0; a < 2; ++a)
; #pragma unroll
;         for (int b = 0; b < 2; ++b)
; #pragma unroll
;             for (int m = 0; m < 4; ++m)
; #pragma unroll
;                 for (int n = 0; n < 2; ++n) acc[a][b][m][n] = (f32x4){0.f, 0.f, 0.f, 0.f};
;     bf16x8 At[4][2], B0[2][2], B1[2][2];
;     const char* cA = (const char*)g.A + (size_t)cur.pm * tstep; const char* cB = (const char*)g.Bt + (size_t)cur.pn * tstep;
;     S.a_ready(cur);
;     if constexpr (SP2) {
;         PG8_STAGE(PG8_SB(0, 0), cB, voffB); PG8_STAGE(PG8_SB(0, 1), cB + hstep, voffB); PG8_STAGE(PG8_SA(0, 0), cA, voffA); PG8_STAGE(PG8_SA(0, 1), cA + hstep, voffA);
;         if (wr == 1) PG8_BAR;
;         PG8_WAIT_V(2); PG8_BAR;
;         PG8_STAGE(PG8_SB(1, 0), cB + kstep, voffB); PG8_STAGE(PG8_SA(1, 0), cA + kstep, voffA); PG8_STAGE(PG8_SB(1, 1), cB + hstep + kstep, voffB);
;         PG8_WAIT_V(6); PG8_BAR;
;     } else {
;         PG8_STAGE(PG8_SB(0, 0), cB, voffB); PG8_STAGE(PG8_SA(0, 0), cA, voffA); PG8_STAGE(PG8_SB(0, 1), cB + hstep, voffB); PG8_STAGE(PG8_SA(0, 1), cA + hstep, voffA);
;         if (wr == 1) PG8_BAR;
.LBB0_58:
	v_ashrrev_i32_e32 v0, 31, v198
	v_lshrrev_b32_e32 v0, 26, v0
	v_add_u32_e32 v0, v198, v0
	v_ashrrev_i32_e32 v10, 6, v0
	v_bfe_i32 v0, v198, 27, 1
	v_lshlrev_b32_e32 v2, 4, v198
	v_lshrrev_b32_e32 v0, 22, v0
	s_ashr_i32 s11, s11, 3
	v_add_u32_e32 v0, v2, v0
	s_add_u32 s29, s4, 0x9800000
	v_readlane_b32 s8, v255, 27
	v_and_b32_e32 v0, 0xfffffc00, v0
	s_addc_u32 s30, s5, 0
	v_readlane_b32 s9, v255, 28
	v_sub_u32_e32 v0, v2, v0
	s_and_b64 s[8:9], s[8:9], exec
	v_lshrrev_b32_e32 v3, 4, v0
	s_brev_b32 s8, 16
	v_bitop3_b32 v0, v3, v0, 32 bitop3:0x6c
	s_cselect_b32 s8, 0x800000, s8
	v_ashrrev_i32_e32 v4, 31, v0
	s_add_u32 s31, s4, s8
	v_lshrrev_b32_e32 v4, 26, v4
	s_addc_u32 s56, s5, 0
	v_add_u32_e32 v4, v0, v4
	s_add_i32 s8, s10, s11
	v_lshlrev_b32_e32 v3, 3, v10
	v_ashrrev_i32_e32 v11, 6, v4
	v_and_b32_e32 v4, 0xc0, v4
	s_ashr_i32 s9, s8, 31
	v_and_b32_e32 v3, 0xffff0, v3
	v_lshlrev_b32_e32 v5, 5, v10
	v_sub_u32_e32 v0, v0, v4
	s_lshr_b32 s9, s9, 26
	v_add_u32_e32 v3, v11, v3
	v_and_b32_e32 v12, 32, v5
	v_ashrrev_i16_sdwa v0, v230, sext(v0) dst_sel:DWORD dst_unused:UNUSED_PAD src0_sel:DWORD src1_sel:BYTE_0
	v_add_u32_e32 v2, 0x2000, v2
	s_add_i32 s9, s8, s9
	v_bfe_i32 v13, v0, 0, 16
	v_lshl_or_b32 v0, v3, 11, v12
	v_ashrrev_i32_e32 v3, 31, v2
	s_ashr_i32 s10, s9, 6
	s_and_b32 s9, s9, 0xffc0
	v_lshrrev_b32_e32 v3, 22, v3
	s_sub_i32 s8, s8, s9
	v_add_u32_e32 v3, v2, v3
	s_bfe_i32 s9, s8, 0x80000
	v_ashrrev_i32_e32 v14, 10, v3
	s_bfe_u32 s9, s9, 0x3000c
	v_mul_i32_i24_e32 v3, 0x400, v14
	s_add_i32 s9, s8, s9
	v_sub_u32_e32 v2, v2, v3
	s_bfe_i32 s11, s9, 0x80000
	s_and_b32 s9, s9, 0xf8
	v_lshrrev_b32_e32 v3, 4, v2
	s_sub_i32 s8, s8, s9
	v_bitop3_b32 v2, v3, v2, 32 bitop3:0x6c
	s_lshl_b32 s10, s10, 3
	s_sext_i32_i16 s11, s11
	s_sext_i32_i8 s8, s8
	v_ashrrev_i32_e32 v4, 31, v2
	s_lshr_b32 s12, s11, 3
	s_add_i32 s44, s10, s8
	v_lshrrev_b32_e32 v4, 26, v4
	s_ashr_i32 s15, s13, 6
	s_ashr_i32 s45, s44, 31
	s_bfe_i64 s[10:11], s[12:13], 0x100000
	s_ashr_i32 s14, s13, 8
	v_add_u32_e32 v4, v2, v4
	s_lshl_b32 s57, s15, 10
	s_lshl_b64 s[8:9], s[44:45], 20
	s_lshl_b64 s[10:11], s[10:11], 20
	v_lshlrev_b32_e32 v3, 3, v14
	v_ashrrev_i32_e32 v15, 6, v4
	v_and_b32_e32 v4, 0xc0, v4
	s_add_u32 s48, s31, s10
	v_and_b32_e32 v3, 0xffff0, v3
	v_lshlrev_b32_e32 v5, 5, v14
	v_sub_u32_e32 v2, v2, v4
	s_addc_u32 s49, s56, s11
	s_add_i32 s45, s57, 0
	v_add_lshl_u32 v0, v0, v13, 1
	v_add_u32_e32 v3, v15, v3
	v_and_b32_e32 v16, 32, v5
	v_ashrrev_i16_sdwa v2, v230, sext(v2) dst_sel:DWORD dst_unused:UNUSED_PAD src0_sel:DWORD src1_sel:BYTE_0
	s_add_i32 m0, s45, 0x10000
	v_bfe_i32 v17, v2, 0, 16
	v_lshl_or_b32 v2, v3, 11, v16
	global_load_lds_dwordx4 v0, s[48:49]
	s_add_i32 m0, s45, 0x12000
	v_add_lshl_u32 v142, v2, v17, 1
	s_add_u32 s10, s48, 0x80000
	global_load_lds_dwordx4 v142, s[48:49]
	s_addc_u32 s11, s49, 0
	s_add_i32 m0, s45, 0x14000
	v_mov_b32_e32 v143, v1
	global_load_lds_dwordx4 v0, s[10:11]
	s_add_i32 m0, s45, 0x16000
	s_add_u32 s46, s29, s8
	s_addc_u32 s47, s30, s9
	s_add_i32 s58, s45, 0x2000
	global_load_lds_dwordx4 v142, s[10:11]
	s_mov_b32 m0, s45
	s_add_u32 s8, s46, 0x80000
	global_load_lds_dwordx4 v0, s[46:47]
	s_mov_b32 m0, s58
	s_addc_u32 s9, s47, 0
	s_add_i32 s59, s45, 0x4000
	global_load_lds_dwordx4 v142, s[46:47]
	s_mov_b32 m0, s59
	s_add_i32 s60, s45, 0x6000
	global_load_lds_dwordx4 v0, s[8:9]
	s_mov_b32 m0, s60
	s_cmp_eq_u32 s14, 1
	global_load_lds_dwordx4 v142, s[8:9]
	s_load_dword s61, s[94:95], 0x0
	s_load_dwordx2 s[8:9], s[2:3], 0xa8
	v_lshl_add_u64 v[8:9], s[48:49], 0, v[0:1]
	v_lshl_add_u64 v[6:7], s[48:49], 0, v[142:143]
	v_lshl_add_u64 v[2:3], s[46:47], 0, v[0:1]
	s_cselect_b64 s[10:11], -1, 0
	s_cmp_lg_u32 s14, 1
	v_lshl_add_u64 v[4:5], s[46:47], 0, v[142:143]
	s_cbranch_scc1 .LBB0_60
	s_setprio 1
	s_barrier

; #define PG8_STAGE(bufoff, gbase, voff) do { _Pragma("unroll") for (int _i = 0; _i < 2; ++_i) \
;         __builtin_amdgcn_global_load_lds((const unsigned*)((const char*)(gbase) + (voff)[_i]), (LAS unsigned*)(lds + (bufoff) + ldsw + _i * 8192), 16, 0, 0); } while (0)
; #define PG8_LDA(dst, b, h) do { _Pragma("unroll") for (int m = 0; m < 4; ++m) _Pragma("unroll") for (int k = 0; k < 2; ++k) dst[m][k] = *(const LAS bf16x8*)(lds + PG8_SA(b, h) + aoff + m * 2048 + k * 1024); } while (0)
; #define PG8_LDB(dst, b, h) do { _Pragma("unroll") for (int n = 0; n < 2; ++n) _Pragma("unroll") for (int k = 0; k < 2; ++k) dst[n][k] = *(const LAS bf16x8*)(lds + PG8_SB(b, h) + boff + n * 2048 + k * 1024); } while (0)
; #define PG8_MMA(ai, bj, At, Bt) do { __builtin_amdgcn_s_setprio(1); _Pragma("unroll") for (int m = 0; m < 4; ++m) _Pragma("unroll") for (int n = 0; n < 2; ++n) _Pragma("unroll") for (int k = 0; k < 2; ++k) \
;         acc[ai][bj][m][n] = __builtin_amdgcn_mfma_f32_16x16x32_bf16(Bt[n][k], At[m][k], acc[ai][bj][m][n], 0, 0, 0); __builtin_amdgcn_s_setprio(0); } while (0)
; #define PG8_WAIT_V(n) asm volatile("s_waitcnt vmcnt(" #n ")" ::: "memory")
; #define PG8_WAIT_L(n) asm volatile("s_waitcnt lgkmcnt(" #n ")" ::: "memory")
; #define PG8_BAR __builtin_amdgcn_s_barrier()
; #define PG8_SCHED __builtin_amdgcn_sched_barrier(0)
; template <class Epi, class Sched, bool ALIGN_EPI = false, bool SP2 = false>
; __device__ __forceinline__ void gemm_phase(LAS unsigned char* lds, const Gemm g, const Sched& S, const Epi& E, const int tid_) {
;     ...
;             PG8_LDB(B0, 0, 0); PG8_LDB(B1, 0, 1); PG8_SCHED; PG8_LDA(At, 0, 0); PG8_STAGE(PG8_SA(1, 1), a1 + hstep, voffA);
;             PG8_WAIT_V(8); PG8_WAIT_L(0); PG8_BAR; PG8_MMA(0, 0, At, B0); PG8_MMA(0, 1, At, B1); PG8_BAR; PG8_SCHED;
;             PG8_LDA(At, 0, 1); PG8_STAGE(PG8_SB(0, 0), b2, voffB); PG8_STAGE(PG8_SB(0, 1), b2 + hstep, voffB); PG8_STAGE(PG8_SA(0, 0), a2, voffA);
;             PG8_WAIT_V(8); PG8_WAIT_L(0); PG8_BAR; PG8_MMA(1, 0, At, B0); PG8_MMA(1, 1, At, B1); PG8_BAR; PG8_SCHED;
;             PG8_LDB(B0, 1, 0); PG8_LDB(B1, 1, 1); PG8_SCHED; PG8_LDA(At, 1, 0); PG8_STAGE(PG8_SA(0, 1), a2 + hstep, voffA);
.LBB0_70:
	s_add_u32 s48, s46, 0x100
	s_addc_u32 s49, s47, 0
	s_add_i32 s70, 0, 0x10000
	s_cmp_eq_u32 s69, 28
	s_cselect_b32 s55, s17, s49
	s_cselect_b32 s54, s21, s48
	s_cselect_b32 s51, s15, s68
	s_cselect_b32 s50, s66, s67
	s_add_i32 s71, 0, 0x14000
	v_add_u32_e32 v148, s70, v157
	v_add_u32_e32 v168, s71, v157
	ds_read_b128 v[130:133], v148
	ds_read_b128 v[134:137], v148 offset:1024
	ds_read_b128 v[138:141], v148 offset:2048
	ds_read_b128 v[148:151], v148 offset:3072
	ds_read_b128 v[152:155], v168
	ds_read_b128 v[160:163], v168 offset:1024
	ds_read_b128 v[164:167], v168 offset:2048
	ds_read_b128 v[168:171], v168 offset:3072
	s_add_i32 m0, s45, 0xc000
	ds_read_b128 v[172:175], v159
	ds_read_b128 v[176:179], v159 offset:1024
	ds_read_b128 v[180:183], v159 offset:2048
	ds_read_b128 v[200:203], v159 offset:3072
	ds_read_b128 v[204:207], v159 offset:4096
	ds_read_b128 v[208:211], v159 offset:5120
	ds_read_b128 v[212:215], v159 offset:6144
	ds_read_b128 v[216:219], v159 offset:7168
	global_load_lds_dwordx4 v144, s[46:47]
	s_add_i32 m0, s45, 0xe000
	s_nop 0
	global_load_lds_dwordx4 v146, s[46:47]
	s_waitcnt vmcnt(8)
	s_waitcnt lgkmcnt(0)
	s_barrier
	s_waitcnt lgkmcnt(0)
	v_mfma_f32_16x16x32_bf16 v[126:129], v[130:133], v[172:175], v[126:129]
	v_mfma_f32_16x16x32_bf16 v[122:125], v[138:141], v[172:175], v[122:125]
	v_mfma_f32_16x16x32_bf16 v[118:121], v[130:133], v[180:183], v[118:121]
	v_mfma_f32_16x16x32_bf16 v[106:109], v[138:141], v[180:183], v[106:109]
	v_mfma_f32_16x16x32_bf16 v[102:105], v[130:133], v[204:207], v[102:105]
	v_mfma_f32_16x16x32_bf16 v[90:93], v[138:141], v[204:207], v[90:93]
	v_mfma_f32_16x16x32_bf16 v[86:89], v[130:133], v[212:215], v[86:89]
	v_mfma_f32_16x16x32_bf16 v[74:77], v[138:141], v[212:215], v[74:77]
	v_mfma_f32_16x16x32_bf16 v[126:129], v[134:137], v[176:179], v[126:129]
	v_mfma_f32_16x16x32_bf16 v[122:125], v[148:151], v[176:179], v[122:125]
	v_mfma_f32_16x16x32_bf16 v[118:121], v[134:137], v[200:203], v[118:121]
	v_mfma_f32_16x16x32_bf16 v[106:109], v[148:151], v[200:203], v[106:109]
	v_mfma_f32_16x16x32_bf16 v[102:105], v[134:137], v[208:211], v[102:105]
	v_mfma_f32_16x16x32_bf16 v[90:93], v[148:151], v[208:211], v[90:93]
	v_mfma_f32_16x16x32_bf16 v[86:89], v[134:137], v[216:219], v[86:89]
	v_mfma_f32_16x16x32_bf16 v[74:77], v[148:151], v[216:219], v[74:77]
	v_mfma_f32_16x16x32_bf16 v[114:117], v[152:155], v[172:175], v[114:117]
	v_mfma_f32_16x16x32_bf16 v[110:113], v[164:167], v[172:175], v[110:113]
	v_mfma_f32_16x16x32_bf16 v[98:101], v[152:155], v[180:183], v[98:101]
	v_mfma_f32_16x16x32_bf16 v[94:97], v[164:167], v[180:183], v[94:97]
	v_mfma_f32_16x16x32_bf16 v[82:85], v[152:155], v[204:207], v[82:85]
	v_mfma_f32_16x16x32_bf16 v[78:81], v[164:167], v[204:207], v[78:81]
	v_mfma_f32_16x16x32_bf16 v[70:73], v[152:155], v[212:215], v[70:73]
	v_mfma_f32_16x16x32_bf16 v[66:69], v[164:167], v[212:215], v[66:69]
	v_mfma_f32_16x16x32_bf16 v[114:117], v[160:163], v[176:179], v[114:117]
	v_mfma_f32_16x16x32_bf16 v[110:113], v[168:171], v[176:179], v[110:113]
	v_mfma_f32_16x16x32_bf16 v[98:101], v[160:163], v[200:203], v[98:101]
	v_mfma_f32_16x16x32_bf16 v[94:97], v[168:171], v[200:203], v[94:97]
	v_mfma_f32_16x16x32_bf16 v[82:85], v[160:163], v[208:211], v[82:85]
	v_mfma_f32_16x16x32_bf16 v[78:81], v[168:171], v[208:211], v[78:81]
	v_mfma_f32_16x16x32_bf16 v[70:73], v[160:163], v[216:219], v[70:73]
	v_mfma_f32_16x16x32_bf16 v[66:69], v[168:171], v[216:219], v[66:69]
	s_barrier
	s_add_i32 s46, s70, s57
	s_mov_b32 m0, s46
	ds_read_b128 v[172:175], v159 offset:16384
	ds_read_b128 v[176:179], v159 offset:17408
	ds_read_b128 v[180:183], v159 offset:18432
	ds_read_b128 v[200:203], v159 offset:19456
	ds_read_b128 v[204:207], v159 offset:20480
	ds_read_b128 v[208:211], v159 offset:21504
	ds_read_b128 v[212:215], v159 offset:22528
	ds_read_b128 v[216:219], v159 offset:23552
	global_load_lds_dwordx4 v0, s[50:51]
	s_add_i32 m0, s46, 0x2000
	s_add_u32 s46, s50, 0x80000
	v_lshl_add_u64 v[192:193], s[50:51], 0, v[142:143]
	s_addc_u32 s47, s51, 0
	s_add_i32 s70, s71, s57
	global_load_lds_dwordx4 v142, s[50:51]
	s_mov_b32 m0, s70
	s_nop 0
	global_load_lds_dwordx4 v0, s[46:47]
	s_add_i32 m0, s70, 0x2000
	s_nop 0
	global_load_lds_dwordx4 v142, s[46:47]
	s_mov_b32 m0, s45
	s_nop 0
	global_load_lds_dwordx4 v0, s[54:55]
	s_mov_b32 m0, s58
	s_nop 0
	global_load_lds_dwordx4 v142, s[54:55]
	s_waitcnt vmcnt(8)
	s_waitcnt lgkmcnt(0)
	s_barrier
	s_waitcnt lgkmcnt(0)
	v_mfma_f32_16x16x32_bf16 v[62:65], v[130:133], v[172:175], v[62:65]
	v_mfma_f32_16x16x32_bf16 v[58:61], v[138:141], v[172:175], v[58:61]
	v_mfma_f32_16x16x32_bf16 v[54:57], v[130:133], v[180:183], v[54:57]
	v_mfma_f32_16x16x32_bf16 v[42:45], v[138:141], v[180:183], v[42:45]
	v_mfma_f32_16x16x32_bf16 v[38:41], v[130:133], v[204:207], v[38:41]
	v_mfma_f32_16x16x32_bf16 v[26:29], v[138:141], v[204:207], v[26:29]
	v_mfma_f32_16x16x32_bf16 v[22:25], v[130:133], v[212:215], v[22:25]
	v_mfma_f32_16x16x32_bf16 v[10:13], v[138:141], v[212:215], v[10:13]
	v_mfma_f32_16x16x32_bf16 v[62:65], v[134:137], v[176:179], v[62:65]
	v_mfma_f32_16x16x32_bf16 v[58:61], v[148:151], v[176:179], v[58:61]
	v_mfma_f32_16x16x32_bf16 v[54:57], v[134:137], v[200:203], v[54:57]
	v_mfma_f32_16x16x32_bf16 v[42:45], v[148:151], v[200:203], v[42:45]
	v_mfma_f32_16x16x32_bf16 v[38:41], v[134:137], v[208:211], v[38:41]
	v_mfma_f32_16x16x32_bf16 v[26:29], v[148:151], v[208:211], v[26:29]
	v_mfma_f32_16x16x32_bf16 v[22:25], v[134:137], v[216:219], v[22:25]
	v_mfma_f32_16x16x32_bf16 v[10:13], v[148:151], v[216:219], v[10:13]
	v_mfma_f32_16x16x32_bf16 v[50:53], v[152:155], v[172:175], v[50:53]
	v_mfma_f32_16x16x32_bf16 v[46:49], v[164:167], v[172:175], v[46:49]
	v_mfma_f32_16x16x32_bf16 v[34:37], v[152:155], v[180:183], v[34:37]
	v_mfma_f32_16x16x32_bf16 v[30:33], v[164:167], v[180:183], v[30:33]
	v_mfma_f32_16x16x32_bf16 v[18:21], v[152:155], v[204:207], v[18:21]
	v_mfma_f32_16x16x32_bf16 v[14:17], v[164:167], v[204:207], v[14:17]
	v_mfma_f32_16x16x32_bf16 v[6:9], v[152:155], v[212:215], v[6:9]
	v_mfma_f32_16x16x32_bf16 v[2:5], v[164:167], v[212:215], v[2:5]
	v_mfma_f32_16x16x32_bf16 v[50:53], v[160:163], v[176:179], v[50:53]
	v_mfma_f32_16x16x32_bf16 v[46:49], v[168:171], v[176:179], v[46:49]
	v_mfma_f32_16x16x32_bf16 v[34:37], v[160:163], v[200:203], v[34:37]
	v_mfma_f32_16x16x32_bf16 v[30:33], v[168:171], v[200:203], v[30:33]
	v_mfma_f32_16x16x32_bf16 v[18:21], v[160:163], v[208:211], v[18:21]
	v_mfma_f32_16x16x32_bf16 v[14:17], v[168:171], v[208:211], v[14:17]
	v_mfma_f32_16x16x32_bf16 v[6:9], v[160:163], v[216:219], v[6:9]
	v_mfma_f32_16x16x32_bf16 v[2:5], v[168:171], v[216:219], v[2:5]
	s_barrier
; #define PG8_STAGE(bufoff, gbase, voff) do { _Pragma("unroll") for (int _i = 0; _i < 2; ++_i) \
;         __builtin_amdgcn_global_load_lds((const unsigned*)((const char*)(gbase) + (voff)[_i]), (LAS unsigned*)(lds + (bufoff) + ldsw + _i * 8192), 16, 0, 0); } while (0)
; #define PG8_LDA(dst, b, h) do { _Pragma("unroll") for (int m = 0; m < 4; ++m) _Pragma("unroll") for (int k = 0; k < 2; ++k) dst[m][k] = *(const LAS bf16x8*)(lds + PG8_SA(b, h) + aoff + m * 2048 + k * 1024); } while (0)
; #define PG8_MMA(ai, bj, At, Bt) do { __builtin_amdgcn_s_setprio(1); _Pragma("unroll") for (int m = 0; m < 4; ++m) _Pragma("unroll") for (int n = 0; n < 2; ++n) _Pragma("unroll") for (int k = 0; k < 2; ++k) \
;         acc[ai][bj][m][n] = __builtin_amdgcn_mfma_f32_16x16x32_bf16(Bt[n][k], At[m][k], acc[ai][bj][m][n], 0, 0, 0); __builtin_amdgcn_s_setprio(0); } while (0)
; #define PG8_WAIT_V(n) asm volatile("s_waitcnt vmcnt(" #n ")" ::: "memory")
; #define PG8_WAIT_L(n) asm volatile("s_waitcnt lgkmcnt(" #n ")" ::: "memory")
; #define PG8_BAR __builtin_amdgcn_s_barrier()
; #define PG8_SCHED __builtin_amdgcn_sched_barrier(0)
; template <class Epi, class Sched, bool ALIGN_EPI = false, bool SP2 = false>
; __device__ __forceinline__ void gemm_phase(LAS unsigned char* lds, const Gemm g, const Sched& S, const Epi& E, const int tid_) {
;     ...
;             PG8_WAIT_V(8); PG8_WAIT_L(0); PG8_BAR; PG8_MMA(0, 0, At, B0); PG8_MMA(0, 1, At, B1); PG8_BAR; PG8_SCHED;
;             PG8_LDA(At, 1, 1); PG8_STAGE(PG8_SB(1, 0), b3, voffB); PG8_STAGE(PG8_SB(1, 1), b3 + hstep, voffB); PG8_STAGE(PG8_SA(1, 0), a3, voffA);
;             PG8_WAIT_V(8); PG8_WAIT_L(0); PG8_BAR; PG8_MMA(1, 0, At, B0); PG8_MMA(1, 1, At, B1); PG8_BAR; PG8_SCHED;
	s_add_i32 s70, 0, 0x18000
	s_add_i32 s71, 0, 0x1c000
	v_add_u32_e32 v148, s70, v157
	v_add_u32_e32 v168, s71, v157
	ds_read_b128 v[130:133], v148
	ds_read_b128 v[134:137], v148 offset:1024
	ds_read_b128 v[138:141], v148 offset:2048
	ds_read_b128 v[148:151], v148 offset:3072
	ds_read_b128 v[152:155], v168
	ds_read_b128 v[160:163], v168 offset:1024
	ds_read_b128 v[164:167], v168 offset:2048
	ds_read_b128 v[168:171], v168 offset:3072
	s_add_u32 s46, s54, 0x80000
	s_addc_u32 s47, s55, 0
	s_mov_b32 m0, s59
	ds_read_b128 v[172:175], v159 offset:32768
	ds_read_b128 v[176:179], v159 offset:33792
	ds_read_b128 v[180:183], v159 offset:34816
	ds_read_b128 v[200:203], v159 offset:35840
	ds_read_b128 v[204:207], v159 offset:36864
	ds_read_b128 v[208:211], v159 offset:37888
	ds_read_b128 v[212:215], v159 offset:38912
	ds_read_b128 v[216:219], v159 offset:39936
	global_load_lds_dwordx4 v0, s[46:47]
	s_mov_b32 m0, s60
	s_nop 0
	global_load_lds_dwordx4 v142, s[46:47]
	s_waitcnt vmcnt(8)
	s_waitcnt lgkmcnt(0)
	s_barrier
	s_waitcnt lgkmcnt(0)
	v_mfma_f32_16x16x32_bf16 v[126:129], v[130:133], v[172:175], v[126:129]
	v_mfma_f32_16x16x32_bf16 v[122:125], v[138:141], v[172:175], v[122:125]
	v_mfma_f32_16x16x32_bf16 v[118:121], v[130:133], v[180:183], v[118:121]
	v_mfma_f32_16x16x32_bf16 v[106:109], v[138:141], v[180:183], v[106:109]
	v_mfma_f32_16x16x32_bf16 v[102:105], v[130:133], v[204:207], v[102:105]
	v_mfma_f32_16x16x32_bf16 v[90:93], v[138:141], v[204:207], v[90:93]
	v_mfma_f32_16x16x32_bf16 v[86:89], v[130:133], v[212:215], v[86:89]
	v_mfma_f32_16x16x32_bf16 v[74:77], v[138:141], v[212:215], v[74:77]
	v_mfma_f32_16x16x32_bf16 v[126:129], v[134:137], v[176:179], v[126:129]
	v_mfma_f32_16x16x32_bf16 v[122:125], v[148:151], v[176:179], v[122:125]
	v_mfma_f32_16x16x32_bf16 v[118:121], v[134:137], v[200:203], v[118:121]
	v_mfma_f32_16x16x32_bf16 v[106:109], v[148:151], v[200:203], v[106:109]
	v_mfma_f32_16x16x32_bf16 v[102:105], v[134:137], v[208:211], v[102:105]
	v_mfma_f32_16x16x32_bf16 v[90:93], v[148:151], v[208:211], v[90:93]
	v_mfma_f32_16x16x32_bf16 v[86:89], v[134:137], v[216:219], v[86:89]
	v_mfma_f32_16x16x32_bf16 v[74:77], v[148:151], v[216:219], v[74:77]
	v_mfma_f32_16x16x32_bf16 v[114:117], v[152:155], v[172:175], v[114:117]
	v_mfma_f32_16x16x32_bf16 v[110:113], v[164:167], v[172:175], v[110:113]
	v_mfma_f32_16x16x32_bf16 v[98:101], v[152:155], v[180:183], v[98:101]
	v_mfma_f32_16x16x32_bf16 v[94:97], v[164:167], v[180:183], v[94:97]
	v_mfma_f32_16x16x32_bf16 v[82:85], v[152:155], v[204:207], v[82:85]
	v_mfma_f32_16x16x32_bf16 v[78:81], v[164:167], v[204:207], v[78:81]
	v_mfma_f32_16x16x32_bf16 v[70:73], v[152:155], v[212:215], v[70:73]
	v_mfma_f32_16x16x32_bf16 v[66:69], v[164:167], v[212:215], v[66:69]
	v_mfma_f32_16x16x32_bf16 v[114:117], v[160:163], v[176:179], v[114:117]
	v_mfma_f32_16x16x32_bf16 v[110:113], v[168:171], v[176:179], v[110:113]
	v_mfma_f32_16x16x32_bf16 v[98:101], v[160:163], v[200:203], v[98:101]
	v_mfma_f32_16x16x32_bf16 v[94:97], v[168:171], v[200:203], v[94:97]
	v_mfma_f32_16x16x32_bf16 v[82:85], v[160:163], v[208:211], v[82:85]
	v_mfma_f32_16x16x32_bf16 v[78:81], v[168:171], v[208:211], v[78:81]
	v_mfma_f32_16x16x32_bf16 v[70:73], v[160:163], v[216:219], v[70:73]
	v_mfma_f32_16x16x32_bf16 v[66:69], v[168:171], v[216:219], v[66:69]
	s_barrier
	s_add_i32 s46, s70, s57
	s_add_i32 m0, s46, 0xffffff80
	ds_read_b128 v[172:175], v159 offset:49152
	ds_read_b128 v[176:179], v159 offset:50176
	ds_read_b128 v[180:183], v159 offset:51200
	ds_read_b128 v[200:203], v159 offset:52224
	ds_read_b128 v[204:207], v159 offset:53248
	ds_read_b128 v[208:211], v159 offset:54272
	ds_read_b128 v[212:215], v159 offset:55296
	ds_read_b128 v[216:219], v159 offset:56320
	global_load_lds_dwordx4 v0, s[50:51] offset:128
	s_add_i32 m0, s46, 0x2000
	s_add_u32 s46, s50, 0x80080
	v_lshl_add_u64 v[184:185], v[192:193], 0, s[96:97]
	s_addc_u32 s47, s51, 0
	s_add_i32 s50, s71, s57
	global_load_lds_dwordx4 v[184:185], off
	s_mov_b32 m0, s50
	s_nop 0
	global_load_lds_dwordx4 v0, s[46:47]
	s_add_i32 m0, s50, 0x2000
	s_nop 0
	global_load_lds_dwordx4 v142, s[46:47]
	s_add_i32 m0, s62, 0xffffff80
	s_nop 0
	global_load_lds_dwordx4 v0, s[54:55] offset:128
	s_add_i32 m0, s63, 0xffffff80
	s_nop 0
	global_load_lds_dwordx4 v142, s[54:55] offset:128
	s_waitcnt vmcnt(8)
	s_waitcnt lgkmcnt(0)
	s_barrier
	s_waitcnt lgkmcnt(0)
	v_mfma_f32_16x16x32_bf16 v[62:65], v[130:133], v[172:175], v[62:65]
	v_mfma_f32_16x16x32_bf16 v[58:61], v[138:141], v[172:175], v[58:61]
	v_mfma_f32_16x16x32_bf16 v[54:57], v[130:133], v[180:183], v[54:57]
	v_mfma_f32_16x16x32_bf16 v[42:45], v[138:141], v[180:183], v[42:45]
	v_mfma_f32_16x16x32_bf16 v[38:41], v[130:133], v[204:207], v[38:41]
	v_mfma_f32_16x16x32_bf16 v[26:29], v[138:141], v[204:207], v[26:29]
	v_mfma_f32_16x16x32_bf16 v[22:25], v[130:133], v[212:215], v[22:25]
	v_mfma_f32_16x16x32_bf16 v[10:13], v[138:141], v[212:215], v[10:13]
	v_mfma_f32_16x16x32_bf16 v[62:65], v[134:137], v[176:179], v[62:65]
	v_mfma_f32_16x16x32_bf16 v[58:61], v[148:151], v[176:179], v[58:61]
	v_mfma_f32_16x16x32_bf16 v[54:57], v[134:137], v[200:203], v[54:57]
	v_mfma_f32_16x16x32_bf16 v[42:45], v[148:151], v[200:203], v[42:45]
	v_mfma_f32_16x16x32_bf16 v[38:41], v[134:137], v[208:211], v[38:41]
	v_mfma_f32_16x16x32_bf16 v[26:29], v[148:151], v[208:211], v[26:29]
	v_mfma_f32_16x16x32_bf16 v[22:25], v[134:137], v[216:219], v[22:25]
	v_mfma_f32_16x16x32_bf16 v[10:13], v[148:151], v[216:219], v[10:13]
	v_mfma_f32_16x16x32_bf16 v[50:53], v[152:155], v[172:175], v[50:53]
	v_mfma_f32_16x16x32_bf16 v[46:49], v[164:167], v[172:175], v[46:49]
	v_mfma_f32_16x16x32_bf16 v[34:37], v[152:155], v[180:183], v[34:37]
	v_mfma_f32_16x16x32_bf16 v[30:33], v[164:167], v[180:183], v[30:33]
	v_mfma_f32_16x16x32_bf16 v[18:21], v[152:155], v[204:207], v[18:21]
	v_mfma_f32_16x16x32_bf16 v[14:17], v[164:167], v[204:207], v[14:17]
	v_mfma_f32_16x16x32_bf16 v[6:9], v[152:155], v[212:215], v[6:9]
	v_mfma_f32_16x16x32_bf16 v[2:5], v[164:167], v[212:215], v[2:5]
	v_mfma_f32_16x16x32_bf16 v[50:53], v[160:163], v[176:179], v[50:53]
	v_mfma_f32_16x16x32_bf16 v[46:49], v[168:171], v[176:179], v[46:49]
	v_mfma_f32_16x16x32_bf16 v[34:37], v[160:163], v[200:203], v[34:37]
	v_mfma_f32_16x16x32_bf16 v[30:33], v[168:171], v[200:203], v[30:33]
	v_mfma_f32_16x16x32_bf16 v[18:21], v[160:163], v[208:211], v[18:21]
	v_mfma_f32_16x16x32_bf16 v[14:17], v[168:171], v[208:211], v[14:17]
	v_mfma_f32_16x16x32_bf16 v[6:9], v[160:163], v[216:219], v[6:9]
	v_mfma_f32_16x16x32_bf16 v[2:5], v[168:171], v[216:219], v[2:5]
	s_barrier
	s_add_i32 s69, s69, 2
	s_add_u32 s67, s67, 0x100
	s_addc_u32 s68, s68, 0
	s_cmp_gt_u32 s69, 29
	s_mov_b64 s[46:47], s[48:49]
	s_cbranch_scc0 .LBB0_70
	s_andn2_b64 vcc, s[12:13], s[40:41]
	s_cbranch_vccz .LBB0_73
	s_barrier

; #define PG8_WAIT_V(n) asm volatile("s_waitcnt vmcnt(" #n ")" ::: "memory")
; #define PG8_BAR __builtin_amdgcn_s_barrier()
; template <class Epi, class Sched, bool ALIGN_EPI = false, bool SP2 = false>
; __device__ __forceinline__ void gemm_phase(LAS unsigned char* lds, const Gemm g, const Sched& S, const Epi& E, const int tid_) {
;     const int tid = tid_, wid = __builtin_amdgcn_readfirstlane(tid >> 6), lane = tid & 63, wr = wid >> 2, wc = wid & 3, fr = lane & 15, fq = lane >> 4;
;     const int K = g.K, nt = K / BK;
;     unsigned voffA[2], voffB[2];
; #pragma unroll
;     for (int i = 0; i < 2; ++i) { int R, C; stage_rc(tid * 16 + i * 8192, R, C); const int Rb = Epi::PERM ? ((R & ~31) + perm32(R & 31)) : R;
;         voffA[i] = (unsigned)(R * K + C) * 2u; voffB[i] = (unsigned)(Rb * K + C) * 2u; }
;     const size_t kstep = (size_t)(BK * 2);
;     const size_t hstep = (size_t)HALF * K * 2;
;     const size_t tstep = 2 * hstep;
;     const unsigned ldsw = (unsigned)wid * 1024u;
;     const int aoff = lds_byte(wr * 64 + fr, fq * 8), boff = lds_byte(wc * 32 + fr, fq * 8);
;     ...
;     Unit cur, nxt; int ui = 0;
;     if (!S.next(0, cur)) return;
;     f32x4 acc[2][2][4][2];
; #pragma unroll
;     for (int a = 0; a < 2; ++a)
; #pragma unroll
;         for (int b = 0; b < 2; ++b)
; #pragma unroll
;             for (int m = 0; m < 4; ++m)
; #pragma unroll
;                 for (int n = 0; n < 2; ++n) acc[a][b][m][n] = (f32x4){0.f, 0.f, 0.f, 0.f};
;     bf16x8 At[4][2], B0[2][2], B1[2][2];
;     const char* cA = (const char*)g.A + (size_t)cur.pm * tstep; const char* cB = (const char*)g.Bt + (size_t)cur.pn * tstep;
;     S.a_ready(cur);
;     if constexpr (SP2) {
;         PG8_STAGE(PG8_SB(0, 0), cB, voffB); PG8_STAGE(PG8_SB(0, 1), cB + hstep, voffB); PG8_STAGE(PG8_SA(0, 0), cA, voffA); PG8_STAGE(PG8_SA(0, 1), cA + hstep, voffA);
;         if (wr == 1) PG8_BAR;
;         PG8_WAIT_V(2); PG8_BAR;
;         PG8_STAGE(PG8_SB(1, 0), cB + kstep, voffB); PG8_STAGE(PG8_SA(1, 0), cA + kstep, voffA); PG8_STAGE(PG8_SB(1, 1), cB + hstep + kstep, voffB);
;         PG8_WAIT_V(6); PG8_BAR;
;     } else {
;         PG8_STAGE(PG8_SB(0, 0), cB, voffB); PG8_STAGE(PG8_SA(0, 0), cA, voffA); PG8_STAGE(PG8_SB(0, 1), cB + hstep, voffB); PG8_STAGE(PG8_SA(0, 1), cA + hstep, voffA);
;         if (wr == 1) PG8_BAR;
.LBB0_84:
	s_ashr_i32 s13, s13, 3
	s_add_u32 s30, s4, 0xd800000
	v_readlane_b32 s10, v255, 27
	s_addc_u32 s31, s5, 0
	v_readlane_b32 s11, v255, 28
	s_and_b64 s[10:11], s[10:11], exec
	s_mov_b32 s10, 0x1000000
	s_cselect_b32 s10, s10, 0x8800000
	s_add_u32 s58, s4, s10
	s_addc_u32 s59, s5, 0
	s_add_i32 s10, s12, s13
	s_ashr_i32 s11, s10, 31
	s_lshr_b32 s11, s11, 26
	s_add_i32 s11, s10, s11
	s_ashr_i32 s12, s11, 6
	s_and_b32 s11, s11, 0xffc0
	s_sub_i32 s10, s10, s11
	s_bfe_i32 s11, s10, 0x80000
	s_bfe_u32 s11, s11, 0x3000c
	s_add_i32 s11, s10, s11
	s_lshl_b32 s13, s12, 3
	s_bfe_i32 s12, s11, 0x80000
	s_and_b32 s11, s11, 0xf8
	s_sub_i32 s10, s10, s11
	s_sext_i32_i16 s12, s12
	s_sext_i32_i8 s10, s10
	s_lshr_b32 s12, s12, 3
	s_add_i32 s48, s13, s10
	s_ashr_i32 s15, s14, 6
	s_ashr_i32 s49, s48, 31
	s_bfe_i64 s[18:19], s[12:13], 0x100000
	s_ashr_i32 s16, s14, 8
	s_lshl_b32 s60, s15, 10
	s_lshl_b64 s[10:11], s[48:49], 19
	s_lshl_b64 s[18:19], s[18:19], 19
	s_add_u32 s54, s58, s18
	s_addc_u32 s55, s59, s19
	s_add_i32 s49, s60, 0
	s_add_i32 m0, s49, 0x10000
	v_mov_b32_e32 v205, v1
	global_load_lds_dwordx4 v0, s[54:55]
	s_add_i32 m0, s49, 0x12000
	s_add_u32 s18, s54, 0x40000
	global_load_lds_dwordx4 v204, s[54:55]
	s_addc_u32 s19, s55, 0
	s_add_i32 m0, s49, 0x14000
	v_mov_b32_e32 v201, v1
	global_load_lds_dwordx4 v0, s[18:19]
	s_add_i32 m0, s49, 0x16000
	s_add_u32 s50, s30, s10
	s_addc_u32 s51, s31, s11
	s_add_i32 s61, s49, 0x2000
	global_load_lds_dwordx4 v204, s[18:19]
	s_mov_b32 m0, s49
	s_add_u32 s10, s50, 0x40000
	global_load_lds_dwordx4 v200, s[50:51]
	s_mov_b32 m0, s61
	s_addc_u32 s11, s51, 0
	s_add_i32 s62, s49, 0x4000
	global_load_lds_dwordx4 v202, s[50:51]
	s_mov_b32 m0, s62
	s_add_i32 s63, s49, 0x6000
	global_load_lds_dwordx4 v200, s[10:11]
	s_mov_b32 m0, s63
	v_mov_b32_e32 v203, v1
	global_load_lds_dwordx4 v202, s[10:11]
	s_cmp_eq_u32 s16, 1
	v_lshl_add_u64 v[8:9], s[54:55], 0, v[0:1]
	v_lshl_add_u64 v[6:7], s[54:55], 0, v[204:205]
	v_lshl_add_u64 v[2:3], s[50:51], 0, v[200:201]
	s_cselect_b64 s[10:11], -1, 0
	s_cmp_lg_u32 s16, 1
	v_lshl_add_u64 v[4:5], s[50:51], 0, v[202:203]
	s_cbranch_scc1 .LBB0_86
	s_setprio 1
	s_barrier

; #define PG8_STAGE(bufoff, gbase, voff) do { _Pragma("unroll") for (int _i = 0; _i < 2; ++_i) \
;         __builtin_amdgcn_global_load_lds((const unsigned*)((const char*)(gbase) + (voff)[_i]), (LAS unsigned*)(lds + (bufoff) + ldsw + _i * 8192), 16, 0, 0); } while (0)
; #define PG8_LDA(dst, b, h) do { _Pragma("unroll") for (int m = 0; m < 4; ++m) _Pragma("unroll") for (int k = 0; k < 2; ++k) dst[m][k] = *(const LAS bf16x8*)(lds + PG8_SA(b, h) + aoff + m * 2048 + k * 1024); } while (0)
; #define PG8_LDB(dst, b, h) do { _Pragma("unroll") for (int n = 0; n < 2; ++n) _Pragma("unroll") for (int k = 0; k < 2; ++k) dst[n][k] = *(const LAS bf16x8*)(lds + PG8_SB(b, h) + boff + n * 2048 + k * 1024); } while (0)
; #define PG8_MMA(ai, bj, At, Bt) do { __builtin_amdgcn_s_setprio(1); _Pragma("unroll") for (int m = 0; m < 4; ++m) _Pragma("unroll") for (int n = 0; n < 2; ++n) _Pragma("unroll") for (int k = 0; k < 2; ++k) \
;         acc[ai][bj][m][n] = __builtin_amdgcn_mfma_f32_16x16x32_bf16(Bt[n][k], At[m][k], acc[ai][bj][m][n], 0, 0, 0); __builtin_amdgcn_s_setprio(0); } while (0)
; #define PG8_WAIT_V(n) asm volatile("s_waitcnt vmcnt(" #n ")" ::: "memory")
; #define PG8_WAIT_L(n) asm volatile("s_waitcnt lgkmcnt(" #n ")" ::: "memory")
; #define PG8_BAR __builtin_amdgcn_s_barrier()
; #define PG8_SCHED __builtin_amdgcn_sched_barrier(0)
; template <class Epi, class Sched, bool ALIGN_EPI = false, bool SP2 = false>
; __device__ __forceinline__ void gemm_phase(LAS unsigned char* lds, const Gemm g, const Sched& S, const Epi& E, const int tid_) {
;     ...
;             PG8_LDB(B0, 0, 0); PG8_LDB(B1, 0, 1); PG8_SCHED; PG8_LDA(At, 0, 0); PG8_STAGE(PG8_SA(1, 1), a1 + hstep, voffA);
;             PG8_WAIT_V(8); PG8_WAIT_L(0); PG8_BAR; PG8_MMA(0, 0, At, B0); PG8_MMA(0, 1, At, B1); PG8_BAR; PG8_SCHED;
;             PG8_LDA(At, 0, 1); PG8_STAGE(PG8_SB(0, 0), b2, voffB); PG8_STAGE(PG8_SB(0, 1), b2 + hstep, voffB); PG8_STAGE(PG8_SA(0, 0), a2, voffA);
.LBB0_96:
	s_add_u32 s54, s50, 0xfffc0080
	s_addc_u32 s55, s51, -1
	s_add_i32 s72, 0, 0x10000
	s_cmp_eq_u32 s71, 12
	s_cselect_b32 s57, s19, s55
	s_cselect_b32 s56, s20, s54
	s_cselect_b32 s55, s17, s70
	s_cselect_b32 s54, s21, s69
	s_add_i32 s74, 0, 0x14000
	v_add_u32_e32 v142, s72, v177
	v_add_u32_e32 v162, s74, v177
	ds_read_b128 v[130:133], v142
	ds_read_b128 v[134:137], v142 offset:1024
	ds_read_b128 v[138:141], v142 offset:2048
	ds_read_b128 v[142:145], v142 offset:3072
	s_nop 0
	ds_read_b128 v[146:149], v162
	ds_read_b128 v[154:157], v162 offset:1024
	ds_read_b128 v[158:161], v162 offset:2048
	ds_read_b128 v[162:165], v162 offset:3072
	s_add_i32 m0, s49, 0xc000
	ds_read_b128 v[180:183], v179
	ds_read_b128 v[206:209], v179 offset:1024
	ds_read_b128 v[210:213], v179 offset:2048
	ds_read_b128 v[214:217], v179 offset:3072
	ds_read_b128 v[218:221], v179 offset:4096
	ds_read_b128 v[222:225], v179 offset:5120
	ds_read_b128 v[242:245], v179 offset:6144
	ds_read_b128 v[246:249], v179 offset:7168
	global_load_lds_dwordx4 v150, s[50:51]
	s_add_i32 m0, s49, 0xe000
	s_nop 0
	global_load_lds_dwordx4 v152, s[50:51]
	s_waitcnt vmcnt(8)
	s_waitcnt lgkmcnt(0)
	s_barrier
	s_waitcnt lgkmcnt(0)
	v_mfma_f32_16x16x32_bf16 v[126:129], v[130:133], v[180:183], v[126:129]
	v_mfma_f32_16x16x32_bf16 v[122:125], v[138:141], v[180:183], v[122:125]
	v_mfma_f32_16x16x32_bf16 v[118:121], v[130:133], v[210:213], v[118:121]
	v_mfma_f32_16x16x32_bf16 v[114:117], v[138:141], v[210:213], v[114:117]
	v_mfma_f32_16x16x32_bf16 v[98:101], v[130:133], v[218:221], v[98:101]
	v_mfma_f32_16x16x32_bf16 v[90:93], v[138:141], v[218:221], v[90:93]
	v_mfma_f32_16x16x32_bf16 v[82:85], v[130:133], v[242:245], v[82:85]
	v_mfma_f32_16x16x32_bf16 v[74:77], v[138:141], v[242:245], v[74:77]
	v_mfma_f32_16x16x32_bf16 v[126:129], v[134:137], v[206:209], v[126:129]
	v_mfma_f32_16x16x32_bf16 v[122:125], v[142:145], v[206:209], v[122:125]
	v_mfma_f32_16x16x32_bf16 v[118:121], v[134:137], v[214:217], v[118:121]
	v_mfma_f32_16x16x32_bf16 v[114:117], v[142:145], v[214:217], v[114:117]
	v_mfma_f32_16x16x32_bf16 v[98:101], v[134:137], v[222:225], v[98:101]
	v_mfma_f32_16x16x32_bf16 v[90:93], v[142:145], v[222:225], v[90:93]
	v_mfma_f32_16x16x32_bf16 v[82:85], v[134:137], v[246:249], v[82:85]
	v_mfma_f32_16x16x32_bf16 v[74:77], v[142:145], v[246:249], v[74:77]
	v_mfma_f32_16x16x32_bf16 v[110:113], v[146:149], v[180:183], v[110:113]
	v_mfma_f32_16x16x32_bf16 v[106:109], v[158:161], v[180:183], v[106:109]
	v_mfma_f32_16x16x32_bf16 v[102:105], v[146:149], v[210:213], v[102:105]
	v_mfma_f32_16x16x32_bf16 v[94:97], v[158:161], v[210:213], v[94:97]
	v_mfma_f32_16x16x32_bf16 v[86:89], v[146:149], v[218:221], v[86:89]
	v_mfma_f32_16x16x32_bf16 v[78:81], v[158:161], v[218:221], v[78:81]
	v_mfma_f32_16x16x32_bf16 v[70:73], v[146:149], v[242:245], v[70:73]
	v_mfma_f32_16x16x32_bf16 v[66:69], v[158:161], v[242:245], v[66:69]
	v_mfma_f32_16x16x32_bf16 v[110:113], v[154:157], v[206:209], v[110:113]
	v_mfma_f32_16x16x32_bf16 v[106:109], v[162:165], v[206:209], v[106:109]
	v_mfma_f32_16x16x32_bf16 v[102:105], v[154:157], v[214:217], v[102:105]
	v_mfma_f32_16x16x32_bf16 v[94:97], v[162:165], v[214:217], v[94:97]
	v_mfma_f32_16x16x32_bf16 v[86:89], v[154:157], v[222:225], v[86:89]
	v_mfma_f32_16x16x32_bf16 v[78:81], v[162:165], v[222:225], v[78:81]
	v_mfma_f32_16x16x32_bf16 v[70:73], v[154:157], v[246:249], v[70:73]
	v_mfma_f32_16x16x32_bf16 v[66:69], v[162:165], v[246:249], v[66:69]
	s_barrier
	s_add_i32 s72, s72, s60
	s_mov_b32 m0, s72
	ds_read_b128 v[180:183], v179 offset:16384
	ds_read_b128 v[206:209], v179 offset:17408
	ds_read_b128 v[210:213], v179 offset:18432
	ds_read_b128 v[214:217], v179 offset:19456
	ds_read_b128 v[218:221], v179 offset:20480
	ds_read_b128 v[222:225], v179 offset:21504
	ds_read_b128 v[242:245], v179 offset:22528
	ds_read_b128 v[246:249], v179 offset:23552
	global_load_lds_dwordx4 v0, s[54:55]
	s_add_i32 m0, s72, 0x2000
	s_add_u32 s72, s54, 0x40000
	v_lshl_add_u64 v[236:237], s[54:55], 0, v[204:205]
	s_addc_u32 s73, s55, 0
	s_add_i32 s74, s74, s60
	global_load_lds_dwordx4 v204, s[54:55]
	s_mov_b32 m0, s74
	v_lshl_add_u64 v[252:253], s[56:57], 0, v[202:203]
	global_load_lds_dwordx4 v0, s[72:73]
	s_add_i32 m0, s74, 0x2000
	s_nop 0
	global_load_lds_dwordx4 v204, s[72:73]
	v_lshl_add_u64 v[250:251], s[56:57], 0, v[200:201]
	s_mov_b32 m0, s49
	s_nop 0
	global_load_lds_dwordx4 v200, s[56:57]
	s_mov_b32 m0, s61
	s_nop 0
	global_load_lds_dwordx4 v202, s[56:57]
	s_waitcnt vmcnt(8)
	s_waitcnt lgkmcnt(0)
	s_barrier
; #define PG8_STAGE(bufoff, gbase, voff) do { _Pragma("unroll") for (int _i = 0; _i < 2; ++_i) \
;         __builtin_amdgcn_global_load_lds((const unsigned*)((const char*)(gbase) + (voff)[_i]), (LAS unsigned*)(lds + (bufoff) + ldsw + _i * 8192), 16, 0, 0); } while (0)
; #define PG8_LDA(dst, b, h) do { _Pragma("unroll") for (int m = 0; m < 4; ++m) _Pragma("unroll") for (int k = 0; k < 2; ++k) dst[m][k] = *(const LAS bf16x8*)(lds + PG8_SA(b, h) + aoff + m * 2048 + k * 1024); } while (0)
; #define PG8_LDB(dst, b, h) do { _Pragma("unroll") for (int n = 0; n < 2; ++n) _Pragma("unroll") for (int k = 0; k < 2; ++k) dst[n][k] = *(const LAS bf16x8*)(lds + PG8_SB(b, h) + boff + n * 2048 + k * 1024); } while (0)
; #define PG8_MMA(ai, bj, At, Bt) do { __builtin_amdgcn_s_setprio(1); _Pragma("unroll") for (int m = 0; m < 4; ++m) _Pragma("unroll") for (int n = 0; n < 2; ++n) _Pragma("unroll") for (int k = 0; k < 2; ++k) \
;         acc[ai][bj][m][n] = __builtin_amdgcn_mfma_f32_16x16x32_bf16(Bt[n][k], At[m][k], acc[ai][bj][m][n], 0, 0, 0); __builtin_amdgcn_s_setprio(0); } while (0)
; #define PG8_WAIT_V(n) asm volatile("s_waitcnt vmcnt(" #n ")" ::: "memory")
; #define PG8_WAIT_L(n) asm volatile("s_waitcnt lgkmcnt(" #n ")" ::: "memory")
; #define PG8_BAR __builtin_amdgcn_s_barrier()
; #define PG8_SCHED __builtin_amdgcn_sched_barrier(0)
; template <class Epi, class Sched, bool ALIGN_EPI = false, bool SP2 = false>
; __device__ __forceinline__ void gemm_phase(LAS unsigned char* lds, const Gemm g, const Sched& S, const Epi& E, const int tid_) {
;     ...
;             PG8_WAIT_V(8); PG8_WAIT_L(0); PG8_BAR; PG8_MMA(1, 0, At, B0); PG8_MMA(1, 1, At, B1); PG8_BAR; PG8_SCHED;
;             PG8_LDB(B0, 1, 0); PG8_LDB(B1, 1, 1); PG8_SCHED; PG8_LDA(At, 1, 0); PG8_STAGE(PG8_SA(0, 1), a2 + hstep, voffA);
;             PG8_WAIT_V(8); PG8_WAIT_L(0); PG8_BAR; PG8_MMA(0, 0, At, B0); PG8_MMA(0, 1, At, B1); PG8_BAR; PG8_SCHED;
	s_waitcnt lgkmcnt(0)
	v_mfma_f32_16x16x32_bf16 v[62:65], v[130:133], v[180:183], v[62:65]
	v_mfma_f32_16x16x32_bf16 v[58:61], v[138:141], v[180:183], v[58:61]
	v_mfma_f32_16x16x32_bf16 v[50:53], v[130:133], v[210:213], v[50:53]
	v_mfma_f32_16x16x32_bf16 v[42:45], v[138:141], v[210:213], v[42:45]
	v_mfma_f32_16x16x32_bf16 v[34:37], v[130:133], v[218:221], v[34:37]
	v_mfma_f32_16x16x32_bf16 v[26:29], v[138:141], v[218:221], v[26:29]
	v_mfma_f32_16x16x32_bf16 v[18:21], v[130:133], v[242:245], v[18:21]
	v_mfma_f32_16x16x32_bf16 v[10:13], v[138:141], v[242:245], v[10:13]
	v_mfma_f32_16x16x32_bf16 v[62:65], v[134:137], v[206:209], v[62:65]
	v_mfma_f32_16x16x32_bf16 v[58:61], v[142:145], v[206:209], v[58:61]
	v_mfma_f32_16x16x32_bf16 v[50:53], v[134:137], v[214:217], v[50:53]
	v_mfma_f32_16x16x32_bf16 v[42:45], v[142:145], v[214:217], v[42:45]
	v_mfma_f32_16x16x32_bf16 v[34:37], v[134:137], v[222:225], v[34:37]
	v_mfma_f32_16x16x32_bf16 v[26:29], v[142:145], v[222:225], v[26:29]
	v_mfma_f32_16x16x32_bf16 v[18:21], v[134:137], v[246:249], v[18:21]
	v_mfma_f32_16x16x32_bf16 v[10:13], v[142:145], v[246:249], v[10:13]
	v_mfma_f32_16x16x32_bf16 v[54:57], v[146:149], v[180:183], v[54:57]
	v_mfma_f32_16x16x32_bf16 v[46:49], v[158:161], v[180:183], v[46:49]
	v_mfma_f32_16x16x32_bf16 v[38:41], v[146:149], v[210:213], v[38:41]
	v_mfma_f32_16x16x32_bf16 v[30:33], v[158:161], v[210:213], v[30:33]
	v_mfma_f32_16x16x32_bf16 v[22:25], v[146:149], v[218:221], v[22:25]
	v_mfma_f32_16x16x32_bf16 v[14:17], v[158:161], v[218:221], v[14:17]
	v_mfma_f32_16x16x32_bf16 v[6:9], v[146:149], v[242:245], v[6:9]
	v_mfma_f32_16x16x32_bf16 v[2:5], v[158:161], v[242:245], v[2:5]
	v_mfma_f32_16x16x32_bf16 v[54:57], v[154:157], v[206:209], v[54:57]
	v_mfma_f32_16x16x32_bf16 v[46:49], v[162:165], v[206:209], v[46:49]
	v_mfma_f32_16x16x32_bf16 v[38:41], v[154:157], v[214:217], v[38:41]
	v_mfma_f32_16x16x32_bf16 v[30:33], v[162:165], v[214:217], v[30:33]
	v_mfma_f32_16x16x32_bf16 v[22:25], v[154:157], v[222:225], v[22:25]
	v_mfma_f32_16x16x32_bf16 v[14:17], v[162:165], v[222:225], v[14:17]
	v_mfma_f32_16x16x32_bf16 v[6:9], v[154:157], v[246:249], v[6:9]
	v_mfma_f32_16x16x32_bf16 v[2:5], v[162:165], v[246:249], v[2:5]
	s_barrier
	s_add_i32 s72, 0, 0x18000
	s_add_i32 s73, 0, 0x1c000
	v_add_u32_e32 v142, s72, v177
	v_add_u32_e32 v162, s73, v177
	ds_read_b128 v[130:133], v142
	ds_read_b128 v[134:137], v142 offset:1024
	ds_read_b128 v[138:141], v142 offset:2048
	ds_read_b128 v[142:145], v142 offset:3072
	ds_read_b128 v[146:149], v162
	ds_read_b128 v[154:157], v162 offset:1024
	ds_read_b128 v[158:161], v162 offset:2048
	ds_read_b128 v[162:165], v162 offset:3072
	s_add_u32 s56, s56, 0x40000
	s_addc_u32 s57, s57, 0
	s_mov_b32 m0, s62
	ds_read_b128 v[180:183], v179 offset:32768
	ds_read_b128 v[206:209], v179 offset:33792
	ds_read_b128 v[210:213], v179 offset:34816
	ds_read_b128 v[214:217], v179 offset:35840
	ds_read_b128 v[218:221], v179 offset:36864
	ds_read_b128 v[222:225], v179 offset:37888
	ds_read_b128 v[242:245], v179 offset:38912
	ds_read_b128 v[246:249], v179 offset:39936
	global_load_lds_dwordx4 v200, s[56:57]
	s_mov_b32 m0, s63
	s_nop 0
	global_load_lds_dwordx4 v202, s[56:57]
	s_waitcnt vmcnt(8)
	s_waitcnt lgkmcnt(0)
	s_barrier
	s_waitcnt lgkmcnt(0)
	v_mfma_f32_16x16x32_bf16 v[126:129], v[130:133], v[180:183], v[126:129]
	v_mfma_f32_16x16x32_bf16 v[122:125], v[138:141], v[180:183], v[122:125]
	v_mfma_f32_16x16x32_bf16 v[118:121], v[130:133], v[210:213], v[118:121]
	v_mfma_f32_16x16x32_bf16 v[114:117], v[138:141], v[210:213], v[114:117]
	v_mfma_f32_16x16x32_bf16 v[98:101], v[130:133], v[218:221], v[98:101]
	v_mfma_f32_16x16x32_bf16 v[90:93], v[138:141], v[218:221], v[90:93]
	v_mfma_f32_16x16x32_bf16 v[82:85], v[130:133], v[242:245], v[82:85]
	v_mfma_f32_16x16x32_bf16 v[74:77], v[138:141], v[242:245], v[74:77]
	v_mfma_f32_16x16x32_bf16 v[126:129], v[134:137], v[206:209], v[126:129]
	v_mfma_f32_16x16x32_bf16 v[122:125], v[142:145], v[206:209], v[122:125]
	v_mfma_f32_16x16x32_bf16 v[118:121], v[134:137], v[214:217], v[118:121]
	v_mfma_f32_16x16x32_bf16 v[114:117], v[142:145], v[214:217], v[114:117]
	v_mfma_f32_16x16x32_bf16 v[98:101], v[134:137], v[222:225], v[98:101]
	v_mfma_f32_16x16x32_bf16 v[90:93], v[142:145], v[222:225], v[90:93]
	v_mfma_f32_16x16x32_bf16 v[82:85], v[134:137], v[246:249], v[82:85]
	v_mfma_f32_16x16x32_bf16 v[74:77], v[142:145], v[246:249], v[74:77]
	v_mfma_f32_16x16x32_bf16 v[110:113], v[146:149], v[180:183], v[110:113]
	v_mfma_f32_16x16x32_bf16 v[106:109], v[158:161], v[180:183], v[106:109]
	v_mfma_f32_16x16x32_bf16 v[102:105], v[146:149], v[210:213], v[102:105]
	v_mfma_f32_16x16x32_bf16 v[94:97], v[158:161], v[210:213], v[94:97]
	v_mfma_f32_16x16x32_bf16 v[86:89], v[146:149], v[218:221], v[86:89]
	v_mfma_f32_16x16x32_bf16 v[78:81], v[158:161], v[218:221], v[78:81]
	v_mfma_f32_16x16x32_bf16 v[70:73], v[146:149], v[242:245], v[70:73]
	v_mfma_f32_16x16x32_bf16 v[66:69], v[158:161], v[242:245], v[66:69]
	v_mfma_f32_16x16x32_bf16 v[110:113], v[154:157], v[206:209], v[110:113]
	v_mfma_f32_16x16x32_bf16 v[106:109], v[162:165], v[206:209], v[106:109]
	v_mfma_f32_16x16x32_bf16 v[102:105], v[154:157], v[214:217], v[102:105]
	v_mfma_f32_16x16x32_bf16 v[94:97], v[162:165], v[214:217], v[94:97]
	v_mfma_f32_16x16x32_bf16 v[86:89], v[154:157], v[222:225], v[86:89]
	v_mfma_f32_16x16x32_bf16 v[78:81], v[162:165], v[222:225], v[78:81]
	v_mfma_f32_16x16x32_bf16 v[70:73], v[154:157], v[246:249], v[70:73]
	v_mfma_f32_16x16x32_bf16 v[66:69], v[162:165], v[246:249], v[66:69]
	s_barrier
; #define PG8_STAGE(bufoff, gbase, voff) do { _Pragma("unroll") for (int _i = 0; _i < 2; ++_i) \
;         __builtin_amdgcn_global_load_lds((const unsigned*)((const char*)(gbase) + (voff)[_i]), (LAS unsigned*)(lds + (bufoff) + ldsw + _i * 8192), 16, 0, 0); } while (0)
; #define PG8_LDA(dst, b, h) do { _Pragma("unroll") for (int m = 0; m < 4; ++m) _Pragma("unroll") for (int k = 0; k < 2; ++k) dst[m][k] = *(const LAS bf16x8*)(lds + PG8_SA(b, h) + aoff + m * 2048 + k * 1024); } while (0)
; #define PG8_MMA(ai, bj, At, Bt) do { __builtin_amdgcn_s_setprio(1); _Pragma("unroll") for (int m = 0; m < 4; ++m) _Pragma("unroll") for (int n = 0; n < 2; ++n) _Pragma("unroll") for (int k = 0; k < 2; ++k) \
;         acc[ai][bj][m][n] = __builtin_amdgcn_mfma_f32_16x16x32_bf16(Bt[n][k], At[m][k], acc[ai][bj][m][n], 0, 0, 0); __builtin_amdgcn_s_setprio(0); } while (0)
; #define PG8_WAIT_V(n) asm volatile("s_waitcnt vmcnt(" #n ")" ::: "memory")
; #define PG8_WAIT_L(n) asm volatile("s_waitcnt lgkmcnt(" #n ")" ::: "memory")
; #define PG8_BAR __builtin_amdgcn_s_barrier()
; #define PG8_SCHED __builtin_amdgcn_sched_barrier(0)
; template <class Epi, class Sched, bool ALIGN_EPI = false, bool SP2 = false>
; __device__ __forceinline__ void gemm_phase(LAS unsigned char* lds, const Gemm g, const Sched& S, const Epi& E, const int tid_) {
;     ...
;             PG8_LDA(At, 1, 1); PG8_STAGE(PG8_SB(1, 0), b3, voffB); PG8_STAGE(PG8_SB(1, 1), b3 + hstep, voffB); PG8_STAGE(PG8_SA(1, 0), a3, voffA);
;             PG8_WAIT_V(8); PG8_WAIT_L(0); PG8_BAR; PG8_MMA(1, 0, At, B0); PG8_MMA(1, 1, At, B1); PG8_BAR; PG8_SCHED;
	s_add_i32 s56, s72, s60
	s_add_i32 m0, s56, 0xffffff80
	ds_read_b128 v[180:183], v179 offset:49152
	ds_read_b128 v[206:209], v179 offset:50176
	ds_read_b128 v[210:213], v179 offset:51200
	ds_read_b128 v[214:217], v179 offset:52224
	ds_read_b128 v[218:221], v179 offset:53248
	ds_read_b128 v[222:225], v179 offset:54272
	ds_read_b128 v[242:245], v179 offset:55296
	ds_read_b128 v[246:249], v179 offset:56320
	global_load_lds_dwordx4 v0, s[54:55] offset:128
	s_add_i32 m0, s56, 0x2000
	s_add_u32 s54, s54, 0x40080
	v_lshl_add_u64 v[184:185], v[236:237], 0, s[96:97]
	s_addc_u32 s55, s55, 0
	s_add_i32 s56, s73, s60
	global_load_lds_dwordx4 v[184:185], off
	s_mov_b32 m0, s56
	s_nop 0
	global_load_lds_dwordx4 v0, s[54:55]
	s_add_i32 m0, s56, 0x2000
	s_nop 0
	global_load_lds_dwordx4 v204, s[54:55]
	v_lshl_add_u64 v[184:185], v[250:251], 0, s[96:97]
	s_mov_b32 m0, s64
	s_nop 0
	global_load_lds_dwordx4 v[184:185], off
	v_lshl_add_u64 v[184:185], v[252:253], 0, s[96:97]
	s_mov_b32 m0, s65
	s_nop 0
	global_load_lds_dwordx4 v[184:185], off
	s_waitcnt vmcnt(8)
	s_waitcnt lgkmcnt(0)
	s_barrier
	s_waitcnt lgkmcnt(0)
	v_mfma_f32_16x16x32_bf16 v[62:65], v[130:133], v[180:183], v[62:65]
	v_mfma_f32_16x16x32_bf16 v[58:61], v[138:141], v[180:183], v[58:61]
	v_mfma_f32_16x16x32_bf16 v[50:53], v[130:133], v[210:213], v[50:53]
	v_mfma_f32_16x16x32_bf16 v[42:45], v[138:141], v[210:213], v[42:45]
	v_mfma_f32_16x16x32_bf16 v[34:37], v[130:133], v[218:221], v[34:37]
	v_mfma_f32_16x16x32_bf16 v[26:29], v[138:141], v[218:221], v[26:29]
	v_mfma_f32_16x16x32_bf16 v[18:21], v[130:133], v[242:245], v[18:21]
	v_mfma_f32_16x16x32_bf16 v[10:13], v[138:141], v[242:245], v[10:13]
	v_mfma_f32_16x16x32_bf16 v[62:65], v[134:137], v[206:209], v[62:65]
	v_mfma_f32_16x16x32_bf16 v[58:61], v[142:145], v[206:209], v[58:61]
	v_mfma_f32_16x16x32_bf16 v[50:53], v[134:137], v[214:217], v[50:53]
	v_mfma_f32_16x16x32_bf16 v[42:45], v[142:145], v[214:217], v[42:45]
	v_mfma_f32_16x16x32_bf16 v[34:37], v[134:137], v[222:225], v[34:37]
	v_mfma_f32_16x16x32_bf16 v[26:29], v[142:145], v[222:225], v[26:29]
	v_mfma_f32_16x16x32_bf16 v[18:21], v[134:137], v[246:249], v[18:21]
	v_mfma_f32_16x16x32_bf16 v[10:13], v[142:145], v[246:249], v[10:13]
	v_mfma_f32_16x16x32_bf16 v[54:57], v[146:149], v[180:183], v[54:57]
	v_mfma_f32_16x16x32_bf16 v[46:49], v[158:161], v[180:183], v[46:49]
	v_mfma_f32_16x16x32_bf16 v[38:41], v[146:149], v[210:213], v[38:41]
	v_mfma_f32_16x16x32_bf16 v[30:33], v[158:161], v[210:213], v[30:33]
	v_mfma_f32_16x16x32_bf16 v[22:25], v[146:149], v[218:221], v[22:25]
	v_mfma_f32_16x16x32_bf16 v[14:17], v[158:161], v[218:221], v[14:17]
	v_mfma_f32_16x16x32_bf16 v[6:9], v[146:149], v[242:245], v[6:9]
	v_mfma_f32_16x16x32_bf16 v[2:5], v[158:161], v[242:245], v[2:5]
	v_mfma_f32_16x16x32_bf16 v[54:57], v[154:157], v[206:209], v[54:57]
	v_mfma_f32_16x16x32_bf16 v[46:49], v[162:165], v[206:209], v[46:49]
	v_mfma_f32_16x16x32_bf16 v[38:41], v[154:157], v[214:217], v[38:41]
	v_mfma_f32_16x16x32_bf16 v[30:33], v[162:165], v[214:217], v[30:33]
	v_mfma_f32_16x16x32_bf16 v[22:25], v[154:157], v[222:225], v[22:25]
	v_mfma_f32_16x16x32_bf16 v[14:17], v[162:165], v[222:225], v[14:17]
	v_mfma_f32_16x16x32_bf16 v[6:9], v[154:157], v[246:249], v[6:9]
	v_mfma_f32_16x16x32_bf16 v[2:5], v[162:165], v[246:249], v[2:5]
	s_barrier
	s_add_i32 s71, s71, 2
	s_add_u32 s50, s50, 0x100
	s_addc_u32 s51, s51, 0
	s_add_u32 s69, s69, 0x100
	s_addc_u32 s70, s70, 0
	s_cmp_gt_u32 s71, 13
	s_cbranch_scc0 .LBB0_96
	s_andn2_b64 vcc, s[14:15], s[40:41]
	s_cbranch_vccz .LBB0_99
	s_barrier

; #define PG8_WAIT_V(n) asm volatile("s_waitcnt vmcnt(" #n ")" ::: "memory")
; #define PG8_BAR __builtin_amdgcn_s_barrier()
; template <class Epi, class Sched, bool ALIGN_EPI = false, bool SP2 = false>
; __device__ __forceinline__ void gemm_phase(LAS unsigned char* lds, const Gemm g, const Sched& S, const Epi& E, const int tid_) {
;     const int tid = tid_, wid = __builtin_amdgcn_readfirstlane(tid >> 6), lane = tid & 63, wr = wid >> 2, wc = wid & 3, fr = lane & 15, fq = lane >> 4;
;     const int K = g.K, nt = K / BK;
;     unsigned voffA[2], voffB[2];
; #pragma unroll
;     for (int i = 0; i < 2; ++i) { int R, C; stage_rc(tid * 16 + i * 8192, R, C); const int Rb = Epi::PERM ? ((R & ~31) + perm32(R & 31)) : R;
;         voffA[i] = (unsigned)(R * K + C) * 2u; voffB[i] = (unsigned)(Rb * K + C) * 2u; }
;     const size_t kstep = (size_t)(BK * 2);
;     const size_t hstep = (size_t)HALF * K * 2;
;     const size_t tstep = 2 * hstep;
;     const unsigned ldsw = (unsigned)wid * 1024u;
;     const int aoff = lds_byte(wr * 64 + fr, fq * 8), boff = lds_byte(wc * 32 + fr, fq * 8);
;     ...
;     Unit cur, nxt; int ui = 0;
;     if (!S.next(0, cur)) return;
;     f32x4 acc[2][2][4][2];
; #pragma unroll
;     for (int a = 0; a < 2; ++a)
; #pragma unroll
;         for (int b = 0; b < 2; ++b)
; #pragma unroll
;             for (int m = 0; m < 4; ++m)
; #pragma unroll
;                 for (int n = 0; n < 2; ++n) acc[a][b][m][n] = (f32x4){0.f, 0.f, 0.f, 0.f};
;     bf16x8 At[4][2], B0[2][2], B1[2][2];
;     const char* cA = (const char*)g.A + (size_t)cur.pm * tstep; const char* cB = (const char*)g.Bt + (size_t)cur.pn * tstep;
;     S.a_ready(cur);
;     if constexpr (SP2) {
;         PG8_STAGE(PG8_SB(0, 0), cB, voffB); PG8_STAGE(PG8_SB(0, 1), cB + hstep, voffB); PG8_STAGE(PG8_SA(0, 0), cA, voffA); PG8_STAGE(PG8_SA(0, 1), cA + hstep, voffA);
;         if (wr == 1) PG8_BAR;
;         PG8_WAIT_V(2); PG8_BAR;
;         PG8_STAGE(PG8_SB(1, 0), cB + kstep, voffB); PG8_STAGE(PG8_SA(1, 0), cA + kstep, voffA); PG8_STAGE(PG8_SB(1, 1), cB + hstep + kstep, voffB);
;         PG8_WAIT_V(6); PG8_BAR;
;     } else {
;         PG8_STAGE(PG8_SB(0, 0), cB, voffB); PG8_STAGE(PG8_SA(0, 0), cA, voffA); PG8_STAGE(PG8_SB(0, 1), cB + hstep, voffB); PG8_STAGE(PG8_SA(0, 1), cA + hstep, voffA);
;         if (wr == 1) PG8_BAR;
.LBB0_108:
	s_ashr_i32 s11, s11, 3
	s_add_u32 s30, s4, 0xf800000
	v_readlane_b32 s8, v255, 27
	s_addc_u32 s31, s5, 0
	v_readlane_b32 s9, v255, 28
	s_and_b64 s[8:9], s[8:9], exec
	s_mov_b32 s8, 0x1400000
	s_cselect_b32 s8, s8, 0x8c00000
	s_add_u32 s56, s4, s8
	s_addc_u32 s57, s5, 0
	s_add_i32 s8, s10, s11
	s_ashr_i32 s9, s8, 31
	s_lshr_b32 s9, s9, 26
	s_add_i32 s9, s8, s9
	s_ashr_i32 s10, s9, 6
	s_and_b32 s9, s9, 0xffc0
	s_sub_i32 s8, s8, s9
	s_bfe_i32 s9, s8, 0x80000
	s_bfe_u32 s9, s9, 0x3000c
	s_add_i32 s9, s8, s9
	s_bfe_i32 s11, s9, 0x80000
	s_and_b32 s9, s9, 0xf8
	s_sub_i32 s8, s8, s9
	s_lshl_b32 s10, s10, 3
	s_sext_i32_i16 s11, s11
	s_sext_i32_i8 s8, s8
	s_lshr_b32 s12, s11, 3
	s_add_i32 s46, s10, s8
	s_ashr_i32 s15, s13, 6
	s_ashr_i32 s47, s46, 31
	s_bfe_i64 s[10:11], s[12:13], 0x100000
	s_ashr_i32 s14, s13, 8
	s_lshl_b32 s58, s15, 10
	s_lshl_b64 s[8:9], s[46:47], 19
	s_lshl_b64 s[10:11], s[10:11], 19
	s_add_u32 s50, s56, s10
	s_addc_u32 s51, s57, s11
	s_add_i32 s47, s58, 0
	s_add_i32 m0, s47, 0x10000
	v_mov_b32_e32 v205, v1
	global_load_lds_dwordx4 v0, s[50:51]
	s_add_i32 m0, s47, 0x12000
	s_add_u32 s10, s50, 0x40000
	global_load_lds_dwordx4 v204, s[50:51]
	s_addc_u32 s11, s51, 0
	s_add_i32 m0, s47, 0x14000
	v_mov_b32_e32 v201, v1
	global_load_lds_dwordx4 v0, s[10:11]
	s_add_i32 m0, s47, 0x16000
	s_add_u32 s48, s30, s8
	s_addc_u32 s49, s31, s9
	s_add_i32 s59, s47, 0x2000
	global_load_lds_dwordx4 v204, s[10:11]
	s_mov_b32 m0, s47
	s_add_u32 s8, s48, 0x40000
	global_load_lds_dwordx4 v200, s[48:49]
	s_mov_b32 m0, s59
	s_addc_u32 s9, s49, 0
	s_add_i32 s60, s47, 0x4000
	global_load_lds_dwordx4 v202, s[48:49]
	s_mov_b32 m0, s60
	s_add_i32 s61, s47, 0x6000
	global_load_lds_dwordx4 v200, s[8:9]
	s_mov_b32 m0, s61
	v_mov_b32_e32 v203, v1
	global_load_lds_dwordx4 v202, s[8:9]
	s_cmp_eq_u32 s14, 1
	v_lshl_add_u64 v[8:9], s[50:51], 0, v[0:1]
	v_lshl_add_u64 v[6:7], s[50:51], 0, v[204:205]
	v_lshl_add_u64 v[2:3], s[48:49], 0, v[200:201]
	s_cselect_b64 s[8:9], -1, 0
	s_cmp_lg_u32 s14, 1
	v_lshl_add_u64 v[4:5], s[48:49], 0, v[202:203]
	s_cbranch_scc1 .LBB0_110
	s_setprio 1
	s_barrier

; #define PG8_STAGE(bufoff, gbase, voff) do { _Pragma("unroll") for (int _i = 0; _i < 2; ++_i) \
;         __builtin_amdgcn_global_load_lds((const unsigned*)((const char*)(gbase) + (voff)[_i]), (LAS unsigned*)(lds + (bufoff) + ldsw + _i * 8192), 16, 0, 0); } while (0)
; #define PG8_LDA(dst, b, h) do { _Pragma("unroll") for (int m = 0; m < 4; ++m) _Pragma("unroll") for (int k = 0; k < 2; ++k) dst[m][k] = *(const LAS bf16x8*)(lds + PG8_SA(b, h) + aoff + m * 2048 + k * 1024); } while (0)
; #define PG8_LDB(dst, b, h) do { _Pragma("unroll") for (int n = 0; n < 2; ++n) _Pragma("unroll") for (int k = 0; k < 2; ++k) dst[n][k] = *(const LAS bf16x8*)(lds + PG8_SB(b, h) + boff + n * 2048 + k * 1024); } while (0)
; #define PG8_MMA(ai, bj, At, Bt) do { __builtin_amdgcn_s_setprio(1); _Pragma("unroll") for (int m = 0; m < 4; ++m) _Pragma("unroll") for (int n = 0; n < 2; ++n) _Pragma("unroll") for (int k = 0; k < 2; ++k) \
;         acc[ai][bj][m][n] = __builtin_amdgcn_mfma_f32_16x16x32_bf16(Bt[n][k], At[m][k], acc[ai][bj][m][n], 0, 0, 0); __builtin_amdgcn_s_setprio(0); } while (0)
; #define PG8_WAIT_V(n) asm volatile("s_waitcnt vmcnt(" #n ")" ::: "memory")
; #define PG8_WAIT_L(n) asm volatile("s_waitcnt lgkmcnt(" #n ")" ::: "memory")
; #define PG8_BAR __builtin_amdgcn_s_barrier()
; #define PG8_SCHED __builtin_amdgcn_sched_barrier(0)
; template <class Epi, class Sched, bool ALIGN_EPI = false, bool SP2 = false>
; __device__ __forceinline__ void gemm_phase(LAS unsigned char* lds, const Gemm g, const Sched& S, const Epi& E, const int tid_) {
;     ...
;             PG8_LDB(B0, 0, 0); PG8_LDB(B1, 0, 1); PG8_SCHED; PG8_LDA(At, 0, 0); PG8_STAGE(PG8_SA(1, 1), a1 + hstep, voffA);
;             PG8_WAIT_V(8); PG8_WAIT_L(0); PG8_BAR; PG8_MMA(0, 0, At, B0); PG8_MMA(0, 1, At, B1); PG8_BAR; PG8_SCHED;
;             PG8_LDA(At, 0, 1); PG8_STAGE(PG8_SB(0, 0), b2, voffB); PG8_STAGE(PG8_SB(0, 1), b2 + hstep, voffB); PG8_STAGE(PG8_SA(0, 0), a2, voffA);
.LBB0_120:
	s_add_u32 s50, s48, 0xfffc0080
	s_addc_u32 s51, s49, -1
	s_add_i32 s70, 0, 0x10000
	s_cmp_eq_u32 s69, 12
	s_cselect_b32 s55, s17, s51
	s_cselect_b32 s54, s21, s50
	s_cselect_b32 s51, s15, s68
	s_cselect_b32 s50, s66, s67
	s_add_i32 s72, 0, 0x14000
	v_add_u32_e32 v142, s70, v199
	v_add_u32_e32 v158, s72, v199
	ds_read_b128 v[130:133], v142
	ds_read_b128 v[134:137], v142 offset:1024
	ds_read_b128 v[138:141], v142 offset:2048
	ds_read_b128 v[142:145], v142 offset:3072
	ds_read_b128 v[146:149], v158
	ds_read_b128 v[150:153], v158 offset:1024
	ds_read_b128 v[154:157], v158 offset:2048
	ds_read_b128 v[158:161], v158 offset:3072
	s_add_i32 m0, s47, 0xc000
	ds_read_b128 v[162:165], v237
	ds_read_b128 v[166:169], v237 offset:1024
	ds_read_b128 v[170:173], v237 offset:2048
	ds_read_b128 v[174:177], v237 offset:3072
	ds_read_b128 v[178:181], v237 offset:4096
	ds_read_b128 v[182:185], v237 offset:5120
	ds_read_b128 v[210:213], v237 offset:6144
	ds_read_b128 v[214:217], v237 offset:7168
	global_load_lds_dwordx4 v206, s[48:49]
	s_add_i32 m0, s47, 0xe000
	s_nop 0
	global_load_lds_dwordx4 v208, s[48:49]
	s_waitcnt vmcnt(8)
	s_waitcnt lgkmcnt(0)
	s_barrier
	s_waitcnt lgkmcnt(0)
	v_mfma_f32_16x16x32_bf16 v[126:129], v[130:133], v[162:165], v[126:129]
	v_mfma_f32_16x16x32_bf16 v[122:125], v[138:141], v[162:165], v[122:125]
	v_mfma_f32_16x16x32_bf16 v[110:113], v[130:133], v[170:173], v[110:113]
	v_mfma_f32_16x16x32_bf16 v[106:109], v[138:141], v[170:173], v[106:109]
	v_mfma_f32_16x16x32_bf16 v[94:97], v[130:133], v[178:181], v[94:97]
	v_mfma_f32_16x16x32_bf16 v[90:93], v[138:141], v[178:181], v[90:93]
	v_mfma_f32_16x16x32_bf16 v[78:81], v[130:133], v[210:213], v[78:81]
	v_mfma_f32_16x16x32_bf16 v[74:77], v[138:141], v[210:213], v[74:77]
	v_mfma_f32_16x16x32_bf16 v[126:129], v[134:137], v[166:169], v[126:129]
	v_mfma_f32_16x16x32_bf16 v[122:125], v[142:145], v[166:169], v[122:125]
	v_mfma_f32_16x16x32_bf16 v[110:113], v[134:137], v[174:177], v[110:113]
	v_mfma_f32_16x16x32_bf16 v[106:109], v[142:145], v[174:177], v[106:109]
	v_mfma_f32_16x16x32_bf16 v[94:97], v[134:137], v[182:185], v[94:97]
	v_mfma_f32_16x16x32_bf16 v[90:93], v[142:145], v[182:185], v[90:93]
	v_mfma_f32_16x16x32_bf16 v[78:81], v[134:137], v[214:217], v[78:81]
	v_mfma_f32_16x16x32_bf16 v[74:77], v[142:145], v[214:217], v[74:77]
	v_mfma_f32_16x16x32_bf16 v[118:121], v[146:149], v[162:165], v[118:121]
	v_mfma_f32_16x16x32_bf16 v[114:117], v[154:157], v[162:165], v[114:117]
	v_mfma_f32_16x16x32_bf16 v[102:105], v[146:149], v[170:173], v[102:105]
	v_mfma_f32_16x16x32_bf16 v[98:101], v[154:157], v[170:173], v[98:101]
	v_mfma_f32_16x16x32_bf16 v[86:89], v[146:149], v[178:181], v[86:89]
	v_mfma_f32_16x16x32_bf16 v[82:85], v[154:157], v[178:181], v[82:85]
	v_mfma_f32_16x16x32_bf16 v[70:73], v[146:149], v[210:213], v[70:73]
	v_mfma_f32_16x16x32_bf16 v[66:69], v[154:157], v[210:213], v[66:69]
	v_mfma_f32_16x16x32_bf16 v[118:121], v[150:153], v[166:169], v[118:121]
	v_mfma_f32_16x16x32_bf16 v[114:117], v[158:161], v[166:169], v[114:117]
	v_mfma_f32_16x16x32_bf16 v[102:105], v[150:153], v[174:177], v[102:105]
	v_mfma_f32_16x16x32_bf16 v[98:101], v[158:161], v[174:177], v[98:101]
	v_mfma_f32_16x16x32_bf16 v[86:89], v[150:153], v[182:185], v[86:89]
	v_mfma_f32_16x16x32_bf16 v[82:85], v[158:161], v[182:185], v[82:85]
	v_mfma_f32_16x16x32_bf16 v[70:73], v[150:153], v[214:217], v[70:73]
	v_mfma_f32_16x16x32_bf16 v[66:69], v[158:161], v[214:217], v[66:69]
	s_barrier
	s_add_i32 s70, s70, s58
	s_mov_b32 m0, s70
	ds_read_b128 v[162:165], v237 offset:16384
	ds_read_b128 v[166:169], v237 offset:17408
	ds_read_b128 v[170:173], v237 offset:18432
	ds_read_b128 v[174:177], v237 offset:19456
	ds_read_b128 v[178:181], v237 offset:20480
	ds_read_b128 v[182:185], v237 offset:21504
	ds_read_b128 v[210:213], v237 offset:22528
	ds_read_b128 v[214:217], v237 offset:23552
	global_load_lds_dwordx4 v0, s[50:51]
	s_add_i32 m0, s70, 0x2000
	s_add_u32 s70, s50, 0x40000
	v_lshl_add_u64 v[218:219], s[50:51], 0, v[204:205]
	s_addc_u32 s71, s51, 0
	s_add_i32 s72, s72, s58
	global_load_lds_dwordx4 v204, s[50:51]
	s_mov_b32 m0, s72
	v_lshl_add_u64 v[222:223], s[54:55], 0, v[202:203]
	global_load_lds_dwordx4 v0, s[70:71]
	s_add_i32 m0, s72, 0x2000
	s_nop 0
	global_load_lds_dwordx4 v204, s[70:71]
	v_lshl_add_u64 v[220:221], s[54:55], 0, v[200:201]
	s_mov_b32 m0, s47
	s_nop 0
	global_load_lds_dwordx4 v200, s[54:55]
	s_mov_b32 m0, s59
	s_nop 0
	global_load_lds_dwordx4 v202, s[54:55]
	s_waitcnt vmcnt(8)
	s_waitcnt lgkmcnt(0)
	s_barrier
; #define PG8_STAGE(bufoff, gbase, voff) do { _Pragma("unroll") for (int _i = 0; _i < 2; ++_i) \
;         __builtin_amdgcn_global_load_lds((const unsigned*)((const char*)(gbase) + (voff)[_i]), (LAS unsigned*)(lds + (bufoff) + ldsw + _i * 8192), 16, 0, 0); } while (0)
; #define PG8_LDA(dst, b, h) do { _Pragma("unroll") for (int m = 0; m < 4; ++m) _Pragma("unroll") for (int k = 0; k < 2; ++k) dst[m][k] = *(const LAS bf16x8*)(lds + PG8_SA(b, h) + aoff + m * 2048 + k * 1024); } while (0)
; #define PG8_LDB(dst, b, h) do { _Pragma("unroll") for (int n = 0; n < 2; ++n) _Pragma("unroll") for (int k = 0; k < 2; ++k) dst[n][k] = *(const LAS bf16x8*)(lds + PG8_SB(b, h) + boff + n * 2048 + k * 1024); } while (0)
; #define PG8_MMA(ai, bj, At, Bt) do { __builtin_amdgcn_s_setprio(1); _Pragma("unroll") for (int m = 0; m < 4; ++m) _Pragma("unroll") for (int n = 0; n < 2; ++n) _Pragma("unroll") for (int k = 0; k < 2; ++k) \
;         acc[ai][bj][m][n] = __builtin_amdgcn_mfma_f32_16x16x32_bf16(Bt[n][k], At[m][k], acc[ai][bj][m][n], 0, 0, 0); __builtin_amdgcn_s_setprio(0); } while (0)
; #define PG8_WAIT_V(n) asm volatile("s_waitcnt vmcnt(" #n ")" ::: "memory")
; #define PG8_WAIT_L(n) asm volatile("s_waitcnt lgkmcnt(" #n ")" ::: "memory")
; #define PG8_BAR __builtin_amdgcn_s_barrier()
; #define PG8_SCHED __builtin_amdgcn_sched_barrier(0)
; template <class Epi, class Sched, bool ALIGN_EPI = false, bool SP2 = false>
; __device__ __forceinline__ void gemm_phase(LAS unsigned char* lds, const Gemm g, const Sched& S, const Epi& E, const int tid_) {
;     ...
;             PG8_WAIT_V(8); PG8_WAIT_L(0); PG8_BAR; PG8_MMA(1, 0, At, B0); PG8_MMA(1, 1, At, B1); PG8_BAR; PG8_SCHED;
;             PG8_LDB(B0, 1, 0); PG8_LDB(B1, 1, 1); PG8_SCHED; PG8_LDA(At, 1, 0); PG8_STAGE(PG8_SA(0, 1), a2 + hstep, voffA);
;             PG8_WAIT_V(8); PG8_WAIT_L(0); PG8_BAR; PG8_MMA(0, 0, At, B0); PG8_MMA(0, 1, At, B1); PG8_BAR; PG8_SCHED;
	s_waitcnt lgkmcnt(0)
	v_mfma_f32_16x16x32_bf16 v[62:65], v[130:133], v[162:165], v[62:65]
	v_mfma_f32_16x16x32_bf16 v[58:61], v[138:141], v[162:165], v[58:61]
	v_mfma_f32_16x16x32_bf16 v[46:49], v[130:133], v[170:173], v[46:49]
	v_mfma_f32_16x16x32_bf16 v[42:45], v[138:141], v[170:173], v[42:45]
	v_mfma_f32_16x16x32_bf16 v[30:33], v[130:133], v[178:181], v[30:33]
	v_mfma_f32_16x16x32_bf16 v[26:29], v[138:141], v[178:181], v[26:29]
	v_mfma_f32_16x16x32_bf16 v[14:17], v[130:133], v[210:213], v[14:17]
	v_mfma_f32_16x16x32_bf16 v[10:13], v[138:141], v[210:213], v[10:13]
	v_mfma_f32_16x16x32_bf16 v[62:65], v[134:137], v[166:169], v[62:65]
	v_mfma_f32_16x16x32_bf16 v[58:61], v[142:145], v[166:169], v[58:61]
	v_mfma_f32_16x16x32_bf16 v[46:49], v[134:137], v[174:177], v[46:49]
	v_mfma_f32_16x16x32_bf16 v[42:45], v[142:145], v[174:177], v[42:45]
	v_mfma_f32_16x16x32_bf16 v[30:33], v[134:137], v[182:185], v[30:33]
	v_mfma_f32_16x16x32_bf16 v[26:29], v[142:145], v[182:185], v[26:29]
	v_mfma_f32_16x16x32_bf16 v[14:17], v[134:137], v[214:217], v[14:17]
	v_mfma_f32_16x16x32_bf16 v[10:13], v[142:145], v[214:217], v[10:13]
	v_mfma_f32_16x16x32_bf16 v[54:57], v[146:149], v[162:165], v[54:57]
	v_mfma_f32_16x16x32_bf16 v[50:53], v[154:157], v[162:165], v[50:53]
	v_mfma_f32_16x16x32_bf16 v[38:41], v[146:149], v[170:173], v[38:41]
	v_mfma_f32_16x16x32_bf16 v[34:37], v[154:157], v[170:173], v[34:37]
	v_mfma_f32_16x16x32_bf16 v[22:25], v[146:149], v[178:181], v[22:25]
	v_mfma_f32_16x16x32_bf16 v[18:21], v[154:157], v[178:181], v[18:21]
	v_mfma_f32_16x16x32_bf16 v[6:9], v[146:149], v[210:213], v[6:9]
	v_mfma_f32_16x16x32_bf16 v[2:5], v[154:157], v[210:213], v[2:5]
	v_mfma_f32_16x16x32_bf16 v[54:57], v[150:153], v[166:169], v[54:57]
	v_mfma_f32_16x16x32_bf16 v[50:53], v[158:161], v[166:169], v[50:53]
	v_mfma_f32_16x16x32_bf16 v[38:41], v[150:153], v[174:177], v[38:41]
	v_mfma_f32_16x16x32_bf16 v[34:37], v[158:161], v[174:177], v[34:37]
	v_mfma_f32_16x16x32_bf16 v[22:25], v[150:153], v[182:185], v[22:25]
	v_mfma_f32_16x16x32_bf16 v[18:21], v[158:161], v[182:185], v[18:21]
	v_mfma_f32_16x16x32_bf16 v[6:9], v[150:153], v[214:217], v[6:9]
	v_mfma_f32_16x16x32_bf16 v[2:5], v[158:161], v[214:217], v[2:5]
	s_barrier
	s_add_i32 s70, 0, 0x18000
	s_add_i32 s71, 0, 0x1c000
	v_add_u32_e32 v142, s70, v199
	v_add_u32_e32 v158, s71, v199
	ds_read_b128 v[130:133], v142
	ds_read_b128 v[134:137], v142 offset:1024
	ds_read_b128 v[138:141], v142 offset:2048
	ds_read_b128 v[142:145], v142 offset:3072
	ds_read_b128 v[146:149], v158
	ds_read_b128 v[150:153], v158 offset:1024
	ds_read_b128 v[154:157], v158 offset:2048
	ds_read_b128 v[158:161], v158 offset:3072
	s_add_u32 s54, s54, 0x40000
	s_addc_u32 s55, s55, 0
	s_mov_b32 m0, s60
	ds_read_b128 v[162:165], v237 offset:32768
	ds_read_b128 v[166:169], v237 offset:33792
	ds_read_b128 v[170:173], v237 offset:34816
	ds_read_b128 v[174:177], v237 offset:35840
	ds_read_b128 v[178:181], v237 offset:36864
	ds_read_b128 v[182:185], v237 offset:37888
	ds_read_b128 v[210:213], v237 offset:38912
	ds_read_b128 v[214:217], v237 offset:39936
	global_load_lds_dwordx4 v200, s[54:55]
	s_mov_b32 m0, s61
	s_nop 0
	global_load_lds_dwordx4 v202, s[54:55]
	s_waitcnt vmcnt(8)
	s_waitcnt lgkmcnt(0)
	s_barrier
	s_waitcnt lgkmcnt(0)
	v_mfma_f32_16x16x32_bf16 v[126:129], v[130:133], v[162:165], v[126:129]
	v_mfma_f32_16x16x32_bf16 v[122:125], v[138:141], v[162:165], v[122:125]
	v_mfma_f32_16x16x32_bf16 v[110:113], v[130:133], v[170:173], v[110:113]
	v_mfma_f32_16x16x32_bf16 v[106:109], v[138:141], v[170:173], v[106:109]
	v_mfma_f32_16x16x32_bf16 v[94:97], v[130:133], v[178:181], v[94:97]
	v_mfma_f32_16x16x32_bf16 v[90:93], v[138:141], v[178:181], v[90:93]
	v_mfma_f32_16x16x32_bf16 v[78:81], v[130:133], v[210:213], v[78:81]
	v_mfma_f32_16x16x32_bf16 v[74:77], v[138:141], v[210:213], v[74:77]
	v_mfma_f32_16x16x32_bf16 v[126:129], v[134:137], v[166:169], v[126:129]
	v_mfma_f32_16x16x32_bf16 v[122:125], v[142:145], v[166:169], v[122:125]
	v_mfma_f32_16x16x32_bf16 v[110:113], v[134:137], v[174:177], v[110:113]
	v_mfma_f32_16x16x32_bf16 v[106:109], v[142:145], v[174:177], v[106:109]
	v_mfma_f32_16x16x32_bf16 v[94:97], v[134:137], v[182:185], v[94:97]
	v_mfma_f32_16x16x32_bf16 v[90:93], v[142:145], v[182:185], v[90:93]
	v_mfma_f32_16x16x32_bf16 v[78:81], v[134:137], v[214:217], v[78:81]
	v_mfma_f32_16x16x32_bf16 v[74:77], v[142:145], v[214:217], v[74:77]
	v_mfma_f32_16x16x32_bf16 v[118:121], v[146:149], v[162:165], v[118:121]
	v_mfma_f32_16x16x32_bf16 v[114:117], v[154:157], v[162:165], v[114:117]
	v_mfma_f32_16x16x32_bf16 v[102:105], v[146:149], v[170:173], v[102:105]
	v_mfma_f32_16x16x32_bf16 v[98:101], v[154:157], v[170:173], v[98:101]
	v_mfma_f32_16x16x32_bf16 v[86:89], v[146:149], v[178:181], v[86:89]
	v_mfma_f32_16x16x32_bf16 v[82:85], v[154:157], v[178:181], v[82:85]
	v_mfma_f32_16x16x32_bf16 v[70:73], v[146:149], v[210:213], v[70:73]
	v_mfma_f32_16x16x32_bf16 v[66:69], v[154:157], v[210:213], v[66:69]
	v_mfma_f32_16x16x32_bf16 v[118:121], v[150:153], v[166:169], v[118:121]
	v_mfma_f32_16x16x32_bf16 v[114:117], v[158:161], v[166:169], v[114:117]
	v_mfma_f32_16x16x32_bf16 v[102:105], v[150:153], v[174:177], v[102:105]
	v_mfma_f32_16x16x32_bf16 v[98:101], v[158:161], v[174:177], v[98:101]
	v_mfma_f32_16x16x32_bf16 v[86:89], v[150:153], v[182:185], v[86:89]
	v_mfma_f32_16x16x32_bf16 v[82:85], v[158:161], v[182:185], v[82:85]
	v_mfma_f32_16x16x32_bf16 v[70:73], v[150:153], v[214:217], v[70:73]
	v_mfma_f32_16x16x32_bf16 v[66:69], v[158:161], v[214:217], v[66:69]
	s_barrier
; #define PG8_STAGE(bufoff, gbase, voff) do { _Pragma("unroll") for (int _i = 0; _i < 2; ++_i) \
;         __builtin_amdgcn_global_load_lds((const unsigned*)((const char*)(gbase) + (voff)[_i]), (LAS unsigned*)(lds + (bufoff) + ldsw + _i * 8192), 16, 0, 0); } while (0)
; #define PG8_LDA(dst, b, h) do { _Pragma("unroll") for (int m = 0; m < 4; ++m) _Pragma("unroll") for (int k = 0; k < 2; ++k) dst[m][k] = *(const LAS bf16x8*)(lds + PG8_SA(b, h) + aoff + m * 2048 + k * 1024); } while (0)
; #define PG8_MMA(ai, bj, At, Bt) do { __builtin_amdgcn_s_setprio(1); _Pragma("unroll") for (int m = 0; m < 4; ++m) _Pragma("unroll") for (int n = 0; n < 2; ++n) _Pragma("unroll") for (int k = 0; k < 2; ++k) \
;         acc[ai][bj][m][n] = __builtin_amdgcn_mfma_f32_16x16x32_bf16(Bt[n][k], At[m][k], acc[ai][bj][m][n], 0, 0, 0); __builtin_amdgcn_s_setprio(0); } while (0)
; #define PG8_WAIT_V(n) asm volatile("s_waitcnt vmcnt(" #n ")" ::: "memory")
; #define PG8_WAIT_L(n) asm volatile("s_waitcnt lgkmcnt(" #n ")" ::: "memory")
; #define PG8_BAR __builtin_amdgcn_s_barrier()
; #define PG8_SCHED __builtin_amdgcn_sched_barrier(0)
; template <class Epi, class Sched, bool ALIGN_EPI = false, bool SP2 = false>
; __device__ __forceinline__ void gemm_phase(LAS unsigned char* lds, const Gemm g, const Sched& S, const Epi& E, const int tid_) {
;     ...
;             PG8_LDA(At, 1, 1); PG8_STAGE(PG8_SB(1, 0), b3, voffB); PG8_STAGE(PG8_SB(1, 1), b3 + hstep, voffB); PG8_STAGE(PG8_SA(1, 0), a3, voffA);
;             PG8_WAIT_V(8); PG8_WAIT_L(0); PG8_BAR; PG8_MMA(1, 0, At, B0); PG8_MMA(1, 1, At, B1); PG8_BAR; PG8_SCHED;
	s_add_i32 s54, s70, s58
	s_add_i32 m0, s54, 0xffffff80
	ds_read_b128 v[162:165], v237 offset:49152
	ds_read_b128 v[166:169], v237 offset:50176
	ds_read_b128 v[170:173], v237 offset:51200
	ds_read_b128 v[174:177], v237 offset:52224
	ds_read_b128 v[178:181], v237 offset:53248
	ds_read_b128 v[182:185], v237 offset:54272
	ds_read_b128 v[210:213], v237 offset:55296
	ds_read_b128 v[214:217], v237 offset:56320
	global_load_lds_dwordx4 v0, s[50:51] offset:128
	s_add_i32 m0, s54, 0x2000
	s_add_u32 s50, s50, 0x40080
	v_lshl_add_u64 v[192:193], v[218:219], 0, s[96:97]
	s_addc_u32 s51, s51, 0
	s_add_i32 s54, s71, s58
	global_load_lds_dwordx4 v[192:193], off
	s_mov_b32 m0, s54
	s_nop 0
	global_load_lds_dwordx4 v0, s[50:51]
	s_add_i32 m0, s54, 0x2000
	s_nop 0
	global_load_lds_dwordx4 v204, s[50:51]
	v_lshl_add_u64 v[192:193], v[220:221], 0, s[96:97]
	s_mov_b32 m0, s62
	s_nop 0
	global_load_lds_dwordx4 v[192:193], off
	v_lshl_add_u64 v[192:193], v[222:223], 0, s[96:97]
	s_mov_b32 m0, s63
	s_nop 0
	global_load_lds_dwordx4 v[192:193], off
	s_waitcnt vmcnt(8)
	s_waitcnt lgkmcnt(0)
	s_barrier
	s_waitcnt lgkmcnt(0)
	v_mfma_f32_16x16x32_bf16 v[62:65], v[130:133], v[162:165], v[62:65]
	v_mfma_f32_16x16x32_bf16 v[58:61], v[138:141], v[162:165], v[58:61]
	v_mfma_f32_16x16x32_bf16 v[46:49], v[130:133], v[170:173], v[46:49]
	v_mfma_f32_16x16x32_bf16 v[42:45], v[138:141], v[170:173], v[42:45]
	v_mfma_f32_16x16x32_bf16 v[30:33], v[130:133], v[178:181], v[30:33]
	v_mfma_f32_16x16x32_bf16 v[26:29], v[138:141], v[178:181], v[26:29]
	v_mfma_f32_16x16x32_bf16 v[14:17], v[130:133], v[210:213], v[14:17]
	v_mfma_f32_16x16x32_bf16 v[10:13], v[138:141], v[210:213], v[10:13]
	v_mfma_f32_16x16x32_bf16 v[62:65], v[134:137], v[166:169], v[62:65]
	v_mfma_f32_16x16x32_bf16 v[58:61], v[142:145], v[166:169], v[58:61]
	v_mfma_f32_16x16x32_bf16 v[46:49], v[134:137], v[174:177], v[46:49]
	v_mfma_f32_16x16x32_bf16 v[42:45], v[142:145], v[174:177], v[42:45]
	v_mfma_f32_16x16x32_bf16 v[30:33], v[134:137], v[182:185], v[30:33]
	v_mfma_f32_16x16x32_bf16 v[26:29], v[142:145], v[182:185], v[26:29]
	v_mfma_f32_16x16x32_bf16 v[14:17], v[134:137], v[214:217], v[14:17]
	v_mfma_f32_16x16x32_bf16 v[10:13], v[142:145], v[214:217], v[10:13]
	v_mfma_f32_16x16x32_bf16 v[54:57], v[146:149], v[162:165], v[54:57]
	v_mfma_f32_16x16x32_bf16 v[50:53], v[154:157], v[162:165], v[50:53]
	v_mfma_f32_16x16x32_bf16 v[38:41], v[146:149], v[170:173], v[38:41]
	v_mfma_f32_16x16x32_bf16 v[34:37], v[154:157], v[170:173], v[34:37]
	v_mfma_f32_16x16x32_bf16 v[22:25], v[146:149], v[178:181], v[22:25]
	v_mfma_f32_16x16x32_bf16 v[18:21], v[154:157], v[178:181], v[18:21]
	v_mfma_f32_16x16x32_bf16 v[6:9], v[146:149], v[210:213], v[6:9]
	v_mfma_f32_16x16x32_bf16 v[2:5], v[154:157], v[210:213], v[2:5]
	v_mfma_f32_16x16x32_bf16 v[54:57], v[150:153], v[166:169], v[54:57]
	v_mfma_f32_16x16x32_bf16 v[50:53], v[158:161], v[166:169], v[50:53]
	v_mfma_f32_16x16x32_bf16 v[38:41], v[150:153], v[174:177], v[38:41]
	v_mfma_f32_16x16x32_bf16 v[34:37], v[158:161], v[174:177], v[34:37]
	v_mfma_f32_16x16x32_bf16 v[22:25], v[150:153], v[182:185], v[22:25]
	v_mfma_f32_16x16x32_bf16 v[18:21], v[158:161], v[182:185], v[18:21]
	v_mfma_f32_16x16x32_bf16 v[6:9], v[150:153], v[214:217], v[6:9]
	v_mfma_f32_16x16x32_bf16 v[2:5], v[158:161], v[214:217], v[2:5]
	s_barrier
	s_add_i32 s69, s69, 2
	s_add_u32 s48, s48, 0x100
	s_addc_u32 s49, s49, 0
	s_add_u32 s67, s67, 0x100
	s_addc_u32 s68, s68, 0
	s_cmp_gt_u32 s69, 13
	s_cbranch_scc0 .LBB0_120
	s_andn2_b64 vcc, s[12:13], s[40:41]
	s_cbranch_vccz .LBB0_123
	s_barrier

; #define PG8_STAGE(bufoff, gbase, voff) do { _Pragma("unroll") for (int _i = 0; _i < 2; ++_i) \
;         __builtin_amdgcn_global_load_lds((const unsigned*)((const char*)(gbase) + (voff)[_i]), (LAS unsigned*)(lds + (bufoff) + ldsw + _i * 8192), 16, 0, 0); } while (0)
; #define PG8_WAIT_V(n) asm volatile("s_waitcnt vmcnt(" #n ")" ::: "memory")
; #define PG8_BAR __builtin_amdgcn_s_barrier()
; template <class Epi, class Sched, bool ALIGN_EPI = false, bool SP2 = false>
; __device__ __forceinline__ void gemm_phase(LAS unsigned char* lds, const Gemm g, const Sched& S, const Epi& E, const int tid_) {
;     const int tid = tid_, wid = __builtin_amdgcn_readfirstlane(tid >> 6), lane = tid & 63, wr = wid >> 2, wc = wid & 3, fr = lane & 15, fq = lane >> 4;
;     const int K = g.K, nt = K / BK;
;     unsigned voffA[2], voffB[2];
; #pragma unroll
;     for (int i = 0; i < 2; ++i) { int R, C; stage_rc(tid * 16 + i * 8192, R, C); const int Rb = Epi::PERM ? ((R & ~31) + perm32(R & 31)) : R;
;         voffA[i] = (unsigned)(R * K + C) * 2u; voffB[i] = (unsigned)(Rb * K + C) * 2u; }
;     const size_t kstep = (size_t)(BK * 2);
;     const size_t hstep = (size_t)HALF * K * 2;
;     const size_t tstep = 2 * hstep;
;     const unsigned ldsw = (unsigned)wid * 1024u;
;     const int aoff = lds_byte(wr * 64 + fr, fq * 8), boff = lds_byte(wc * 32 + fr, fq * 8);
;     ...
;     Unit cur, nxt; int ui = 0;
;     if (!S.next(0, cur)) return;
;     f32x4 acc[2][2][4][2];
; #pragma unroll
;     for (int a = 0; a < 2; ++a)
; #pragma unroll
;         for (int b = 0; b < 2; ++b)
; #pragma unroll
;             for (int m = 0; m < 4; ++m)
; #pragma unroll
;                 for (int n = 0; n < 2; ++n) acc[a][b][m][n] = (f32x4){0.f, 0.f, 0.f, 0.f};
;     bf16x8 At[4][2], B0[2][2], B1[2][2];
;     const char* cA = (const char*)g.A + (size_t)cur.pm * tstep; const char* cB = (const char*)g.Bt + (size_t)cur.pn * tstep;
;     S.a_ready(cur);
;     if constexpr (SP2) {
;         PG8_STAGE(PG8_SB(0, 0), cB, voffB); PG8_STAGE(PG8_SB(0, 1), cB + hstep, voffB); PG8_STAGE(PG8_SA(0, 0), cA, voffA); PG8_STAGE(PG8_SA(0, 1), cA + hstep, voffA);
;         if (wr == 1) PG8_BAR;
;         PG8_WAIT_V(2); PG8_BAR;
.LBB0_244:
	s_andn2_b64 vcc, exec, s[8:9]
	s_cbranch_vccnz .LBB0_338
	v_ashrrev_i32_e32 v0, 31, v198
	v_lshrrev_b32_e32 v0, 26, v0
	v_add_u32_e32 v0, v198, v0
	v_ashrrev_i32_e32 v10, 6, v0
	v_bfe_i32 v0, v198, 27, 1
	v_lshlrev_b32_e32 v2, 4, v198
	v_lshrrev_b32_e32 v0, 22, v0
	v_add_u32_e32 v0, v2, v0
	v_and_b32_e32 v0, 0xfffffc00, v0
	v_sub_u32_e32 v0, v2, v0
	v_lshrrev_b32_e32 v3, 4, v0
	v_bitop3_b32 v0, v3, v0, 32 bitop3:0x6c
	v_ashrrev_i32_e32 v4, 31, v0
	s_add_u32 s7, s4, 0x9800000
	v_readlane_b32 s8, v255, 27
	v_lshrrev_b32_e32 v4, 26, v4
	s_addc_u32 s29, s5, 0
	v_readlane_b32 s9, v255, 28
	v_add_u32_e32 v4, v0, v4
	s_and_b64 s[8:9], s[8:9], exec
	v_lshlrev_b32_e32 v3, 3, v10
	v_ashrrev_i32_e32 v11, 6, v4
	v_and_b32_e32 v4, 0xc0, v4
	s_mov_b32 s8, 0x5800000
	v_and_b32_e32 v3, -16, v3
	v_sub_u32_e32 v0, v0, v4
	s_cselect_b32 s8, 0x21800000, s8
	v_add_u32_e32 v3, v11, v3
	v_ashrrev_i16_sdwa v0, v230, sext(v0) dst_sel:DWORD dst_unused:UNUSED_PAD src0_sel:DWORD src1_sel:BYTE_0
	s_add_u32 s30, s4, s8
	v_lshlrev_b32_e32 v5, 5, v10
	v_bfe_i32 v12, v0, 0, 16
	v_lshlrev_b32_e32 v0, 1, v3
	v_lshrrev_b32_e32 v4, 2, v3
	v_and_b32_e32 v6, 3, v11
	s_mov_b32 s8, 0xfffe0
	v_and_b32_e32 v5, 32, v5
	v_and_b32_e32 v0, 24, v0
	v_and_b32_e32 v4, 4, v4
	v_and_or_b32 v6, v3, s8, v6
	v_or3_b32 v0, v6, v4, v0
	v_add_lshl_u32 v4, v5, v12, 1
	v_add_u32_e32 v2, 0x2000, v2
	v_lshl_add_u32 v130, v3, 12, v4
	v_ashrrev_i32_e32 v3, 31, v2
	v_lshrrev_b32_e32 v3, 22, v3
	v_add_u32_e32 v3, v2, v3
	v_ashrrev_i32_e32 v13, 10, v3
	v_mul_i32_i24_e32 v3, 0x400, v13
	v_sub_u32_e32 v2, v2, v3
	v_lshrrev_b32_e32 v3, 4, v2
	v_bitop3_b32 v2, v3, v2, 32 bitop3:0x6c
	v_lshl_add_u32 v0, v0, 12, v4
	v_ashrrev_i32_e32 v4, 31, v2
	v_lshrrev_b32_e32 v4, 26, v4
	v_lshlrev_b32_e32 v3, 3, v13
	v_add_u32_e32 v4, v2, v4
	v_and_b32_e32 v3, -16, v3
	v_ashrrev_i32_e32 v14, 6, v4
	s_addc_u32 s31, s5, 0
	v_add_u32_e32 v3, v14, v3
	v_and_b32_e32 v4, 0xc0, v4
	v_and_b32_e32 v6, 3, v14
	s_ashr_i32 s12, s10, 6
	s_ashr_i32 s43, s42, 31
	s_ashr_i32 s57, s56, 31
	s_ashr_i32 s11, s10, 8
	v_sub_u32_e32 v2, v2, v4
	v_and_or_b32 v6, v3, s8, v6
	s_lshl_b32 s62, s12, 10
	s_lshl_b64 s[8:9], s[42:43], 20
	s_lshl_b64 s[14:15], s[56:57], 20
	v_ashrrev_i16_sdwa v2, v230, sext(v2) dst_sel:DWORD dst_unused:UNUSED_PAD src0_sel:DWORD src1_sel:BYTE_0
	s_add_u32 s58, s30, s14
	v_lshlrev_b32_e32 v5, 5, v13
	v_bfe_i32 v15, v2, 0, 16
	v_lshlrev_b32_e32 v2, 1, v3
	v_lshrrev_b32_e32 v4, 2, v3
	s_addc_u32 s59, s31, s15
	s_add_i32 s57, s62, 0
	v_and_b32_e32 v5, 32, v5
	v_and_b32_e32 v2, 24, v2
	v_and_b32_e32 v4, 4, v4
	s_add_i32 m0, s57, 0x10000
	v_or3_b32 v2, v6, v4, v2
	v_add_lshl_u32 v4, v5, v15, 1
	global_load_lds_dwordx4 v0, s[58:59]
	s_add_i32 m0, s57, 0x12000
	v_lshl_add_u32 v134, v2, 12, v4
	s_add_u32 s14, s58, 0x80000
	global_load_lds_dwordx4 v134, s[58:59]
	s_addc_u32 s15, s59, 0
	s_add_i32 m0, s57, 0x14000
	v_lshl_add_u32 v132, v3, 12, v4
	global_load_lds_dwordx4 v0, s[14:15]
	s_add_i32 m0, s57, 0x16000
	s_add_u32 s54, s7, s8
	s_addc_u32 s55, s29, s9
	s_add_i32 s63, s57, 0x2000
	global_load_lds_dwordx4 v134, s[14:15]
	s_mov_b32 m0, s57
	s_add_u32 s8, s54, 0x80000
	global_load_lds_dwordx4 v130, s[54:55]
	s_mov_b32 m0, s63
	s_addc_u32 s9, s55, 0
	s_add_i32 s64, s57, 0x4000
	global_load_lds_dwordx4 v132, s[54:55]
	s_mov_b32 m0, s64
	s_add_i32 s65, s57, 0x6000
	global_load_lds_dwordx4 v130, s[8:9]
	s_mov_b32 m0, s65
	s_load_dword s66, s[94:95], 0x0
	global_load_lds_dwordx4 v132, s[8:9]
	v_mov_b32_e32 v135, v1
	v_mov_b32_e32 v131, v1
	v_mov_b32_e32 v133, v1
	s_cmp_eq_u32 s11, 1
	v_lshl_add_u64 v[8:9], s[58:59], 0, v[0:1]
	v_lshl_add_u64 v[6:7], s[58:59], 0, v[134:135]
	v_lshl_add_u64 v[2:3], s[54:55], 0, v[130:131]
	s_cselect_b64 s[8:9], -1, 0
	s_cmp_lg_u32 s11, 1
	v_lshl_add_u64 v[4:5], s[54:55], 0, v[132:133]
	s_cbranch_scc1 .LBB0_247
	s_setprio 1
	s_barrier

; #define PG8_STAGE(bufoff, gbase, voff) do { _Pragma("unroll") for (int _i = 0; _i < 2; ++_i) \
;         __builtin_amdgcn_global_load_lds((const unsigned*)((const char*)(gbase) + (voff)[_i]), (LAS unsigned*)(lds + (bufoff) + ldsw + _i * 8192), 16, 0, 0); } while (0)
; #define PG8_LDA(dst, b, h) do { _Pragma("unroll") for (int m = 0; m < 4; ++m) _Pragma("unroll") for (int k = 0; k < 2; ++k) dst[m][k] = *(const LAS bf16x8*)(lds + PG8_SA(b, h) + aoff + m * 2048 + k * 1024); } while (0)
; #define PG8_LDB(dst, b, h) do { _Pragma("unroll") for (int n = 0; n < 2; ++n) _Pragma("unroll") for (int k = 0; k < 2; ++k) dst[n][k] = *(const LAS bf16x8*)(lds + PG8_SB(b, h) + boff + n * 2048 + k * 1024); } while (0)
; #define PG8_MMA(ai, bj, At, Bt) do { __builtin_amdgcn_s_setprio(1); _Pragma("unroll") for (int m = 0; m < 4; ++m) _Pragma("unroll") for (int n = 0; n < 2; ++n) _Pragma("unroll") for (int k = 0; k < 2; ++k) \
;         acc[ai][bj][m][n] = __builtin_amdgcn_mfma_f32_16x16x32_bf16(Bt[n][k], At[m][k], acc[ai][bj][m][n], 0, 0, 0); __builtin_amdgcn_s_setprio(0); } while (0)
; #define PG8_WAIT_V(n) asm volatile("s_waitcnt vmcnt(" #n ")" ::: "memory")
; #define PG8_WAIT_L(n) asm volatile("s_waitcnt lgkmcnt(" #n ")" ::: "memory")
; #define PG8_BAR __builtin_amdgcn_s_barrier()
; #define PG8_SCHED __builtin_amdgcn_sched_barrier(0)
; template <class Epi, class Sched, bool ALIGN_EPI = false, bool SP2 = false>
; __device__ __forceinline__ void gemm_phase(LAS unsigned char* lds, const Gemm g, const Sched& S, const Epi& E, const int tid_) {
;     ...
;             PG8_LDB(B0, 0, 0); PG8_LDB(B1, 0, 1); PG8_SCHED; PG8_LDA(At, 0, 0); PG8_STAGE(PG8_SA(1, 1), a1 + hstep, voffA);
;             PG8_WAIT_V(8); PG8_WAIT_L(0); PG8_BAR; PG8_MMA(0, 0, At, B0); PG8_MMA(0, 1, At, B1); PG8_BAR; PG8_SCHED;
;             PG8_LDA(At, 0, 1); PG8_STAGE(PG8_SB(0, 0), b2, voffB); PG8_STAGE(PG8_SB(0, 1), b2 + hstep, voffB); PG8_STAGE(PG8_SA(0, 0), a2, voffA);
;             PG8_WAIT_V(8); PG8_WAIT_L(0); PG8_BAR; PG8_MMA(1, 0, At, B0); PG8_MMA(1, 1, At, B1); PG8_BAR; PG8_SCHED;
.LBB0_253:
	s_add_u32 s58, s54, 0xfff80080
	s_addc_u32 s59, s55, -1
	s_add_i32 s74, 0, 0x10000
	s_cmp_eq_u32 s73, 28
	s_cselect_b32 s61, s20, s59
	s_cselect_b32 s60, s21, s58
	s_cselect_b32 s59, s43, s72
	s_cselect_b32 s58, s47, s49
	s_add_i32 s76, 0, 0x14000
	v_add_u32_e32 v156, s74, v145
	v_add_u32_e32 v172, s76, v145
	ds_read_b128 v[140:143], v156
	ds_read_b128 v[148:151], v156 offset:1024
	ds_read_b128 v[152:155], v156 offset:2048
	ds_read_b128 v[156:159], v156 offset:3072
	ds_read_b128 v[160:163], v172
	ds_read_b128 v[164:167], v172 offset:1024
	ds_read_b128 v[168:171], v172 offset:2048
	ds_read_b128 v[172:175], v172 offset:3072
	s_add_i32 m0, s57, 0xc000
	ds_read_b128 v[176:179], v147
	ds_read_b128 v[180:183], v147 offset:1024
	ds_read_b128 v[200:203], v147 offset:2048
	ds_read_b128 v[204:207], v147 offset:3072
	ds_read_b128 v[208:211], v147 offset:4096
	ds_read_b128 v[212:215], v147 offset:5120
	ds_read_b128 v[216:219], v147 offset:6144
	ds_read_b128 v[220:223], v147 offset:7168
	global_load_lds_dwordx4 v136, s[54:55]
	s_add_i32 m0, s57, 0xe000
	s_nop 0
	global_load_lds_dwordx4 v138, s[54:55]
	s_waitcnt vmcnt(8)
	s_waitcnt lgkmcnt(0)
	s_barrier
	s_waitcnt lgkmcnt(0)
	v_mfma_f32_16x16x32_bf16 v[126:129], v[140:143], v[176:179], v[126:129]
	v_mfma_f32_16x16x32_bf16 v[122:125], v[152:155], v[176:179], v[122:125]
	v_mfma_f32_16x16x32_bf16 v[110:113], v[140:143], v[200:203], v[110:113]
	v_mfma_f32_16x16x32_bf16 v[106:109], v[152:155], v[200:203], v[106:109]
	v_mfma_f32_16x16x32_bf16 v[94:97], v[140:143], v[208:211], v[94:97]
	v_mfma_f32_16x16x32_bf16 v[90:93], v[152:155], v[208:211], v[90:93]
	v_mfma_f32_16x16x32_bf16 v[78:81], v[140:143], v[216:219], v[78:81]
	v_mfma_f32_16x16x32_bf16 v[74:77], v[152:155], v[216:219], v[74:77]
	v_mfma_f32_16x16x32_bf16 v[126:129], v[148:151], v[180:183], v[126:129]
	v_mfma_f32_16x16x32_bf16 v[122:125], v[156:159], v[180:183], v[122:125]
	v_mfma_f32_16x16x32_bf16 v[110:113], v[148:151], v[204:207], v[110:113]
	v_mfma_f32_16x16x32_bf16 v[106:109], v[156:159], v[204:207], v[106:109]
	v_mfma_f32_16x16x32_bf16 v[94:97], v[148:151], v[212:215], v[94:97]
	v_mfma_f32_16x16x32_bf16 v[90:93], v[156:159], v[212:215], v[90:93]
	v_mfma_f32_16x16x32_bf16 v[78:81], v[148:151], v[220:223], v[78:81]
	v_mfma_f32_16x16x32_bf16 v[74:77], v[156:159], v[220:223], v[74:77]
	v_mfma_f32_16x16x32_bf16 v[118:121], v[160:163], v[176:179], v[118:121]
	v_mfma_f32_16x16x32_bf16 v[114:117], v[168:171], v[176:179], v[114:117]
	v_mfma_f32_16x16x32_bf16 v[102:105], v[160:163], v[200:203], v[102:105]
	v_mfma_f32_16x16x32_bf16 v[98:101], v[168:171], v[200:203], v[98:101]
	v_mfma_f32_16x16x32_bf16 v[86:89], v[160:163], v[208:211], v[86:89]
	v_mfma_f32_16x16x32_bf16 v[82:85], v[168:171], v[208:211], v[82:85]
	v_mfma_f32_16x16x32_bf16 v[70:73], v[160:163], v[216:219], v[70:73]
	v_mfma_f32_16x16x32_bf16 v[66:69], v[168:171], v[216:219], v[66:69]
	v_mfma_f32_16x16x32_bf16 v[118:121], v[164:167], v[180:183], v[118:121]
	v_mfma_f32_16x16x32_bf16 v[114:117], v[172:175], v[180:183], v[114:117]
	v_mfma_f32_16x16x32_bf16 v[102:105], v[164:167], v[204:207], v[102:105]
	v_mfma_f32_16x16x32_bf16 v[98:101], v[172:175], v[204:207], v[98:101]
	v_mfma_f32_16x16x32_bf16 v[86:89], v[164:167], v[212:215], v[86:89]
	v_mfma_f32_16x16x32_bf16 v[82:85], v[172:175], v[212:215], v[82:85]
	v_mfma_f32_16x16x32_bf16 v[70:73], v[164:167], v[220:223], v[70:73]
	v_mfma_f32_16x16x32_bf16 v[66:69], v[172:175], v[220:223], v[66:69]
	s_barrier
	s_add_i32 s74, s74, s62
	s_mov_b32 m0, s74
	ds_read_b128 v[176:179], v147 offset:16384
	ds_read_b128 v[180:183], v147 offset:17408
	ds_read_b128 v[200:203], v147 offset:18432
	ds_read_b128 v[204:207], v147 offset:19456
	ds_read_b128 v[208:211], v147 offset:20480
	ds_read_b128 v[212:215], v147 offset:21504
	ds_read_b128 v[216:219], v147 offset:22528
	ds_read_b128 v[220:223], v147 offset:23552
	global_load_lds_dwordx4 v0, s[58:59]
	s_add_i32 m0, s74, 0x2000
	s_add_u32 s74, s58, 0x80000
	v_lshl_add_u64 v[224:225], s[58:59], 0, v[134:135]
	s_addc_u32 s75, s59, 0
	s_add_i32 s76, s76, s62
	global_load_lds_dwordx4 v134, s[58:59]
	s_mov_b32 m0, s76
	v_lshl_add_u64 v[242:243], s[60:61], 0, v[132:133]
	global_load_lds_dwordx4 v0, s[74:75]
	s_add_i32 m0, s76, 0x2000
	s_nop 0
	global_load_lds_dwordx4 v134, s[74:75]
	v_lshl_add_u64 v[236:237], s[60:61], 0, v[130:131]
	s_mov_b32 m0, s57
	s_nop 0
	global_load_lds_dwordx4 v130, s[60:61]
	s_mov_b32 m0, s63
	s_nop 0
	global_load_lds_dwordx4 v132, s[60:61]
	s_waitcnt vmcnt(8)
	s_waitcnt lgkmcnt(0)
	s_barrier
; #define PG8_STAGE(bufoff, gbase, voff) do { _Pragma("unroll") for (int _i = 0; _i < 2; ++_i) \
;         __builtin_amdgcn_global_load_lds((const unsigned*)((const char*)(gbase) + (voff)[_i]), (LAS unsigned*)(lds + (bufoff) + ldsw + _i * 8192), 16, 0, 0); } while (0)
; #define PG8_LDA(dst, b, h) do { _Pragma("unroll") for (int m = 0; m < 4; ++m) _Pragma("unroll") for (int k = 0; k < 2; ++k) dst[m][k] = *(const LAS bf16x8*)(lds + PG8_SA(b, h) + aoff + m * 2048 + k * 1024); } while (0)
; #define PG8_LDB(dst, b, h) do { _Pragma("unroll") for (int n = 0; n < 2; ++n) _Pragma("unroll") for (int k = 0; k < 2; ++k) dst[n][k] = *(const LAS bf16x8*)(lds + PG8_SB(b, h) + boff + n * 2048 + k * 1024); } while (0)
; #define PG8_MMA(ai, bj, At, Bt) do { __builtin_amdgcn_s_setprio(1); _Pragma("unroll") for (int m = 0; m < 4; ++m) _Pragma("unroll") for (int n = 0; n < 2; ++n) _Pragma("unroll") for (int k = 0; k < 2; ++k) \
;         acc[ai][bj][m][n] = __builtin_amdgcn_mfma_f32_16x16x32_bf16(Bt[n][k], At[m][k], acc[ai][bj][m][n], 0, 0, 0); __builtin_amdgcn_s_setprio(0); } while (0)
; #define PG8_WAIT_V(n) asm volatile("s_waitcnt vmcnt(" #n ")" ::: "memory")
; #define PG8_WAIT_L(n) asm volatile("s_waitcnt lgkmcnt(" #n ")" ::: "memory")
; #define PG8_BAR __builtin_amdgcn_s_barrier()
; #define PG8_SCHED __builtin_amdgcn_sched_barrier(0)
; template <class Epi, class Sched, bool ALIGN_EPI = false, bool SP2 = false>
; __device__ __forceinline__ void gemm_phase(LAS unsigned char* lds, const Gemm g, const Sched& S, const Epi& E, const int tid_) {
;     ...
;             PG8_WAIT_V(8); PG8_WAIT_L(0); PG8_BAR; PG8_MMA(1, 0, At, B0); PG8_MMA(1, 1, At, B1); PG8_BAR; PG8_SCHED;
;             PG8_LDB(B0, 1, 0); PG8_LDB(B1, 1, 1); PG8_SCHED; PG8_LDA(At, 1, 0); PG8_STAGE(PG8_SA(0, 1), a2 + hstep, voffA);
;             PG8_WAIT_V(8); PG8_WAIT_L(0); PG8_BAR; PG8_MMA(0, 0, At, B0); PG8_MMA(0, 1, At, B1); PG8_BAR; PG8_SCHED;
	s_waitcnt lgkmcnt(0)
	v_mfma_f32_16x16x32_bf16 v[62:65], v[140:143], v[176:179], v[62:65]
	v_mfma_f32_16x16x32_bf16 v[58:61], v[152:155], v[176:179], v[58:61]
	v_mfma_f32_16x16x32_bf16 v[46:49], v[140:143], v[200:203], v[46:49]
	v_mfma_f32_16x16x32_bf16 v[42:45], v[152:155], v[200:203], v[42:45]
	v_mfma_f32_16x16x32_bf16 v[30:33], v[140:143], v[208:211], v[30:33]
	v_mfma_f32_16x16x32_bf16 v[26:29], v[152:155], v[208:211], v[26:29]
	v_mfma_f32_16x16x32_bf16 v[14:17], v[140:143], v[216:219], v[14:17]
	v_mfma_f32_16x16x32_bf16 v[10:13], v[152:155], v[216:219], v[10:13]
	v_mfma_f32_16x16x32_bf16 v[62:65], v[148:151], v[180:183], v[62:65]
	v_mfma_f32_16x16x32_bf16 v[58:61], v[156:159], v[180:183], v[58:61]
	v_mfma_f32_16x16x32_bf16 v[46:49], v[148:151], v[204:207], v[46:49]
	v_mfma_f32_16x16x32_bf16 v[42:45], v[156:159], v[204:207], v[42:45]
	v_mfma_f32_16x16x32_bf16 v[30:33], v[148:151], v[212:215], v[30:33]
	v_mfma_f32_16x16x32_bf16 v[26:29], v[156:159], v[212:215], v[26:29]
	v_mfma_f32_16x16x32_bf16 v[14:17], v[148:151], v[220:223], v[14:17]
	v_mfma_f32_16x16x32_bf16 v[10:13], v[156:159], v[220:223], v[10:13]
	v_mfma_f32_16x16x32_bf16 v[54:57], v[160:163], v[176:179], v[54:57]
	v_mfma_f32_16x16x32_bf16 v[50:53], v[168:171], v[176:179], v[50:53]
	v_mfma_f32_16x16x32_bf16 v[38:41], v[160:163], v[200:203], v[38:41]
	v_mfma_f32_16x16x32_bf16 v[34:37], v[168:171], v[200:203], v[34:37]
	v_mfma_f32_16x16x32_bf16 v[22:25], v[160:163], v[208:211], v[22:25]
	v_mfma_f32_16x16x32_bf16 v[18:21], v[168:171], v[208:211], v[18:21]
	v_mfma_f32_16x16x32_bf16 v[6:9], v[160:163], v[216:219], v[6:9]
	v_mfma_f32_16x16x32_bf16 v[2:5], v[168:171], v[216:219], v[2:5]
	v_mfma_f32_16x16x32_bf16 v[54:57], v[164:167], v[180:183], v[54:57]
	v_mfma_f32_16x16x32_bf16 v[50:53], v[172:175], v[180:183], v[50:53]
	v_mfma_f32_16x16x32_bf16 v[38:41], v[164:167], v[204:207], v[38:41]
	v_mfma_f32_16x16x32_bf16 v[34:37], v[172:175], v[204:207], v[34:37]
	v_mfma_f32_16x16x32_bf16 v[22:25], v[164:167], v[212:215], v[22:25]
	v_mfma_f32_16x16x32_bf16 v[18:21], v[172:175], v[212:215], v[18:21]
	v_mfma_f32_16x16x32_bf16 v[6:9], v[164:167], v[220:223], v[6:9]
	v_mfma_f32_16x16x32_bf16 v[2:5], v[172:175], v[220:223], v[2:5]
	s_barrier
	s_add_i32 s74, 0, 0x18000
	s_add_i32 s75, 0, 0x1c000
	v_add_u32_e32 v156, s74, v145
	v_add_u32_e32 v172, s75, v145
	ds_read_b128 v[140:143], v156
	ds_read_b128 v[148:151], v156 offset:1024
	ds_read_b128 v[152:155], v156 offset:2048
	ds_read_b128 v[156:159], v156 offset:3072
	ds_read_b128 v[160:163], v172
	ds_read_b128 v[164:167], v172 offset:1024
	ds_read_b128 v[168:171], v172 offset:2048
	ds_read_b128 v[172:175], v172 offset:3072
	s_add_u32 s60, s60, 0x80000
	s_addc_u32 s61, s61, 0
	s_mov_b32 m0, s64
	ds_read_b128 v[176:179], v147 offset:32768
	ds_read_b128 v[180:183], v147 offset:33792
	ds_read_b128 v[200:203], v147 offset:34816
	ds_read_b128 v[204:207], v147 offset:35840
	ds_read_b128 v[208:211], v147 offset:36864
	ds_read_b128 v[212:215], v147 offset:37888
	ds_read_b128 v[216:219], v147 offset:38912
	ds_read_b128 v[220:223], v147 offset:39936
	global_load_lds_dwordx4 v130, s[60:61]
	s_mov_b32 m0, s65
	s_nop 0
	global_load_lds_dwordx4 v132, s[60:61]
	s_waitcnt vmcnt(8)
	s_waitcnt lgkmcnt(0)
	s_barrier
	s_waitcnt lgkmcnt(0)
	v_mfma_f32_16x16x32_bf16 v[126:129], v[140:143], v[176:179], v[126:129]
	v_mfma_f32_16x16x32_bf16 v[122:125], v[152:155], v[176:179], v[122:125]
	v_mfma_f32_16x16x32_bf16 v[110:113], v[140:143], v[200:203], v[110:113]
	v_mfma_f32_16x16x32_bf16 v[106:109], v[152:155], v[200:203], v[106:109]
	v_mfma_f32_16x16x32_bf16 v[94:97], v[140:143], v[208:211], v[94:97]
	v_mfma_f32_16x16x32_bf16 v[90:93], v[152:155], v[208:211], v[90:93]
	v_mfma_f32_16x16x32_bf16 v[78:81], v[140:143], v[216:219], v[78:81]
	v_mfma_f32_16x16x32_bf16 v[74:77], v[152:155], v[216:219], v[74:77]
	v_mfma_f32_16x16x32_bf16 v[126:129], v[148:151], v[180:183], v[126:129]
	v_mfma_f32_16x16x32_bf16 v[122:125], v[156:159], v[180:183], v[122:125]
	v_mfma_f32_16x16x32_bf16 v[110:113], v[148:151], v[204:207], v[110:113]
	v_mfma_f32_16x16x32_bf16 v[106:109], v[156:159], v[204:207], v[106:109]
	v_mfma_f32_16x16x32_bf16 v[94:97], v[148:151], v[212:215], v[94:97]
	v_mfma_f32_16x16x32_bf16 v[90:93], v[156:159], v[212:215], v[90:93]
	v_mfma_f32_16x16x32_bf16 v[78:81], v[148:151], v[220:223], v[78:81]
	v_mfma_f32_16x16x32_bf16 v[74:77], v[156:159], v[220:223], v[74:77]
	v_mfma_f32_16x16x32_bf16 v[118:121], v[160:163], v[176:179], v[118:121]
	v_mfma_f32_16x16x32_bf16 v[114:117], v[168:171], v[176:179], v[114:117]
	v_mfma_f32_16x16x32_bf16 v[102:105], v[160:163], v[200:203], v[102:105]
	v_mfma_f32_16x16x32_bf16 v[98:101], v[168:171], v[200:203], v[98:101]
	v_mfma_f32_16x16x32_bf16 v[86:89], v[160:163], v[208:211], v[86:89]
	v_mfma_f32_16x16x32_bf16 v[82:85], v[168:171], v[208:211], v[82:85]
	v_mfma_f32_16x16x32_bf16 v[70:73], v[160:163], v[216:219], v[70:73]
	v_mfma_f32_16x16x32_bf16 v[66:69], v[168:171], v[216:219], v[66:69]
	v_mfma_f32_16x16x32_bf16 v[118:121], v[164:167], v[180:183], v[118:121]
	v_mfma_f32_16x16x32_bf16 v[114:117], v[172:175], v[180:183], v[114:117]
	v_mfma_f32_16x16x32_bf16 v[102:105], v[164:167], v[204:207], v[102:105]
	v_mfma_f32_16x16x32_bf16 v[98:101], v[172:175], v[204:207], v[98:101]
	v_mfma_f32_16x16x32_bf16 v[86:89], v[164:167], v[212:215], v[86:89]
	v_mfma_f32_16x16x32_bf16 v[82:85], v[172:175], v[212:215], v[82:85]
	v_mfma_f32_16x16x32_bf16 v[70:73], v[164:167], v[220:223], v[70:73]
	v_mfma_f32_16x16x32_bf16 v[66:69], v[172:175], v[220:223], v[66:69]
	s_barrier
; #define PG8_STAGE(bufoff, gbase, voff) do { _Pragma("unroll") for (int _i = 0; _i < 2; ++_i) \
;         __builtin_amdgcn_global_load_lds((const unsigned*)((const char*)(gbase) + (voff)[_i]), (LAS unsigned*)(lds + (bufoff) + ldsw + _i * 8192), 16, 0, 0); } while (0)
; #define PG8_LDA(dst, b, h) do { _Pragma("unroll") for (int m = 0; m < 4; ++m) _Pragma("unroll") for (int k = 0; k < 2; ++k) dst[m][k] = *(const LAS bf16x8*)(lds + PG8_SA(b, h) + aoff + m * 2048 + k * 1024); } while (0)
; #define PG8_MMA(ai, bj, At, Bt) do { __builtin_amdgcn_s_setprio(1); _Pragma("unroll") for (int m = 0; m < 4; ++m) _Pragma("unroll") for (int n = 0; n < 2; ++n) _Pragma("unroll") for (int k = 0; k < 2; ++k) \
;         acc[ai][bj][m][n] = __builtin_amdgcn_mfma_f32_16x16x32_bf16(Bt[n][k], At[m][k], acc[ai][bj][m][n], 0, 0, 0); __builtin_amdgcn_s_setprio(0); } while (0)
; #define PG8_WAIT_V(n) asm volatile("s_waitcnt vmcnt(" #n ")" ::: "memory")
; #define PG8_WAIT_L(n) asm volatile("s_waitcnt lgkmcnt(" #n ")" ::: "memory")
; #define PG8_BAR __builtin_amdgcn_s_barrier()
; #define PG8_SCHED __builtin_amdgcn_sched_barrier(0)
; template <class Epi, class Sched, bool ALIGN_EPI = false, bool SP2 = false>
; __device__ __forceinline__ void gemm_phase(LAS unsigned char* lds, const Gemm g, const Sched& S, const Epi& E, const int tid_) {
;     ...
;         for (int t = 0; t < nt; t += 2) {
;     ...
;             PG8_LDA(At, 1, 1); PG8_STAGE(PG8_SB(1, 0), b3, voffB); PG8_STAGE(PG8_SB(1, 1), b3 + hstep, voffB); PG8_STAGE(PG8_SA(1, 0), a3, voffA);
;             PG8_WAIT_V(8); PG8_WAIT_L(0); PG8_BAR; PG8_MMA(1, 0, At, B0); PG8_MMA(1, 1, At, B1); PG8_BAR; PG8_SCHED;
	s_add_i32 s60, s74, s62
	s_add_i32 m0, s60, 0xffffff80
	ds_read_b128 v[176:179], v147 offset:49152
	ds_read_b128 v[180:183], v147 offset:50176
	ds_read_b128 v[200:203], v147 offset:51200
	ds_read_b128 v[204:207], v147 offset:52224
	ds_read_b128 v[208:211], v147 offset:53248
	ds_read_b128 v[212:215], v147 offset:54272
	ds_read_b128 v[216:219], v147 offset:55296
	ds_read_b128 v[220:223], v147 offset:56320
	global_load_lds_dwordx4 v0, s[58:59] offset:128
	s_add_i32 m0, s60, 0x2000
	s_add_u32 s58, s58, 0x80080
	v_lshl_add_u64 v[184:185], v[224:225], 0, s[96:97]
	s_addc_u32 s59, s59, 0
	s_add_i32 s60, s75, s62
	global_load_lds_dwordx4 v[184:185], off
	s_mov_b32 m0, s60
	s_nop 0
	global_load_lds_dwordx4 v0, s[58:59]
	s_add_i32 m0, s60, 0x2000
	s_nop 0
	global_load_lds_dwordx4 v134, s[58:59]
	v_lshl_add_u64 v[184:185], v[236:237], 0, s[96:97]
	s_mov_b32 m0, s67
	s_nop 0
	global_load_lds_dwordx4 v[184:185], off
	v_lshl_add_u64 v[184:185], v[242:243], 0, s[96:97]
	s_mov_b32 m0, s68
	s_nop 0
	global_load_lds_dwordx4 v[184:185], off
	s_waitcnt vmcnt(8)
	s_waitcnt lgkmcnt(0)
	s_barrier
	s_waitcnt lgkmcnt(0)
	v_mfma_f32_16x16x32_bf16 v[62:65], v[140:143], v[176:179], v[62:65]
	v_mfma_f32_16x16x32_bf16 v[58:61], v[152:155], v[176:179], v[58:61]
	v_mfma_f32_16x16x32_bf16 v[46:49], v[140:143], v[200:203], v[46:49]
	v_mfma_f32_16x16x32_bf16 v[42:45], v[152:155], v[200:203], v[42:45]
	v_mfma_f32_16x16x32_bf16 v[30:33], v[140:143], v[208:211], v[30:33]
	v_mfma_f32_16x16x32_bf16 v[26:29], v[152:155], v[208:211], v[26:29]
	v_mfma_f32_16x16x32_bf16 v[14:17], v[140:143], v[216:219], v[14:17]
	v_mfma_f32_16x16x32_bf16 v[10:13], v[152:155], v[216:219], v[10:13]
	v_mfma_f32_16x16x32_bf16 v[62:65], v[148:151], v[180:183], v[62:65]
	v_mfma_f32_16x16x32_bf16 v[58:61], v[156:159], v[180:183], v[58:61]
	v_mfma_f32_16x16x32_bf16 v[46:49], v[148:151], v[204:207], v[46:49]
	v_mfma_f32_16x16x32_bf16 v[42:45], v[156:159], v[204:207], v[42:45]
	v_mfma_f32_16x16x32_bf16 v[30:33], v[148:151], v[212:215], v[30:33]
	v_mfma_f32_16x16x32_bf16 v[26:29], v[156:159], v[212:215], v[26:29]
	v_mfma_f32_16x16x32_bf16 v[14:17], v[148:151], v[220:223], v[14:17]
	v_mfma_f32_16x16x32_bf16 v[10:13], v[156:159], v[220:223], v[10:13]
	v_mfma_f32_16x16x32_bf16 v[54:57], v[160:163], v[176:179], v[54:57]
	v_mfma_f32_16x16x32_bf16 v[50:53], v[168:171], v[176:179], v[50:53]
	v_mfma_f32_16x16x32_bf16 v[38:41], v[160:163], v[200:203], v[38:41]
	v_mfma_f32_16x16x32_bf16 v[34:37], v[168:171], v[200:203], v[34:37]
	v_mfma_f32_16x16x32_bf16 v[22:25], v[160:163], v[208:211], v[22:25]
	v_mfma_f32_16x16x32_bf16 v[18:21], v[168:171], v[208:211], v[18:21]
	v_mfma_f32_16x16x32_bf16 v[6:9], v[160:163], v[216:219], v[6:9]
	v_mfma_f32_16x16x32_bf16 v[2:5], v[168:171], v[216:219], v[2:5]
	v_mfma_f32_16x16x32_bf16 v[54:57], v[164:167], v[180:183], v[54:57]
	v_mfma_f32_16x16x32_bf16 v[50:53], v[172:175], v[180:183], v[50:53]
	v_mfma_f32_16x16x32_bf16 v[38:41], v[164:167], v[204:207], v[38:41]
	v_mfma_f32_16x16x32_bf16 v[34:37], v[172:175], v[204:207], v[34:37]
	v_mfma_f32_16x16x32_bf16 v[22:25], v[164:167], v[212:215], v[22:25]
	v_mfma_f32_16x16x32_bf16 v[18:21], v[172:175], v[212:215], v[18:21]
	v_mfma_f32_16x16x32_bf16 v[6:9], v[164:167], v[220:223], v[6:9]
	v_mfma_f32_16x16x32_bf16 v[2:5], v[172:175], v[220:223], v[2:5]
	s_barrier
	s_add_i32 s73, s73, 2
	s_add_u32 s54, s54, 0x100
	s_addc_u32 s55, s55, 0
	s_add_u32 s49, s49, 0x100
	s_addc_u32 s72, s72, 0
	s_cmp_gt_u32 s73, 29
	s_cbranch_scc0 .LBB0_253
	s_andn2_b64 vcc, s[10:11], s[40:41]
	s_cbranch_vccz .LBB0_256
	s_barrier

; #define LAS __attribute__((address_space(3)))
;     __host__ __device__ bool next(int i, Unit& u) const {
;         const long L = (long)i * G + c; if (L >= nwg) return false;
;         int wgid = (int)L; { const int q = nwg / NXCD, r = nwg % NXCD, xcd = wgid % NXCD, off = wgid / NXCD; wgid = (xcd < r ? xcd * (q + 1) : r * (q + 1) + (xcd - r) * q) + off; }
;         const int nig = WGM * nN, gid = wgid / nig, fm = gid * WGM, gsz = (nM - fm) < WGM ? (nM - fm) : WGM;
;         u.pm = fm + ((wgid % nig) % gsz); u.pn = (wgid % nig) / gsz; return true;
;     }
; template <class Epi, class Sched, bool ALIGN_EPI = false, bool SP2 = false>
; __device__ __forceinline__ void gemm_phase(LAS unsigned char* lds, const Gemm g, const Sched& S, const Epi& E, const int tid_) {
;     const int tid = tid_, wid = __builtin_amdgcn_readfirstlane(tid >> 6), lane = tid & 63, wr = wid >> 2, wc = wid & 3, fr = lane & 15, fq = lane >> 4;
;     const int K = g.K, nt = K / BK;
;     unsigned voffA[2], voffB[2];
; #pragma unroll
;     for (int i = 0; i < 2; ++i) { int R, C; stage_rc(tid * 16 + i * 8192, R, C); const int Rb = Epi::PERM ? ((R & ~31) + perm32(R & 31)) : R;
;         voffA[i] = (unsigned)(R * K + C) * 2u; voffB[i] = (unsigned)(Rb * K + C) * 2u; }
;     const size_t kstep = (size_t)(BK * 2);
;     const size_t hstep = (size_t)HALF * K * 2;
;     const size_t tstep = 2 * hstep;
;     const unsigned ldsw = (unsigned)wid * 1024u;
;     const int aoff = lds_byte(wr * 64 + fr, fq * 8), boff = lds_byte(wc * 32 + fr, fq * 8);
;     ...
;     Unit cur, nxt; int ui = 0;
;     if (!S.next(0, cur)) return;
;     f32x4 acc[2][2][4][2];
; #pragma unroll
;     for (int a = 0; a < 2; ++a)
; #pragma unroll
;         for (int b = 0; b < 2; ++b)
; #pragma unroll
;             for (int m = 0; m < 4; ++m)
; #pragma unroll
;                 for (int n = 0; n < 2; ++n) acc[a][b][m][n] = (f32x4){0.f, 0.f, 0.f, 0.f};
;     bf16x8 At[4][2], B0[2][2], B1[2][2];
;     const char* cA = (const char*)g.A + (size_t)cur.pm * tstep; const char* cB = (const char*)g.Bt + (size_t)cur.pn * tstep;
;     S.a_ready(cur);
;     if constexpr (SP2) {
;         PG8_STAGE(PG8_SB(0, 0), cB, voffB); PG8_STAGE(PG8_SB(0, 1), cB + hstep, voffB); PG8_STAGE(PG8_SA(0, 0), cA, voffA); PG8_STAGE(PG8_SA(0, 1), cA + hstep, voffA);
;         if (wr == 1) PG8_BAR;
;         PG8_WAIT_V(2); PG8_BAR;
.LBB0_347:
	v_ashrrev_i32_e32 v0, 31, v198
	v_lshrrev_b32_e32 v0, 26, v0
	v_add_u32_e32 v0, v198, v0
	v_ashrrev_i32_e32 v10, 6, v0
	v_bfe_i32 v0, v198, 27, 1
	v_lshlrev_b32_e32 v2, 4, v198
	v_lshrrev_b32_e32 v0, 22, v0
	v_add_u32_e32 v0, v2, v0
	v_and_b32_e32 v0, 0xfffffc00, v0
	v_sub_u32_e32 v0, v2, v0
	v_lshrrev_b32_e32 v3, 4, v0
	s_add_u32 s29, s4, 0xd800000
	v_bitop3_b32 v0, v3, v0, 32 bitop3:0x6c
	s_addc_u32 s30, s5, 0
	v_ashrrev_i32_e32 v4, 31, v0
	s_add_u32 s31, s4, 0x3800000
	v_lshrrev_b32_e32 v4, 26, v4
	s_addc_u32 s54, s5, 0
	v_add_u32_e32 v4, v0, v4
	s_add_i32 s8, s10, s8
	v_lshlrev_b32_e32 v3, 3, v10
	v_ashrrev_i32_e32 v11, 6, v4
	v_and_b32_e32 v4, 0xc0, v4
	s_ashr_i32 s9, s8, 31
	v_and_b32_e32 v3, 0x3fff0, v3
	v_lshlrev_b32_e32 v5, 5, v10
	v_sub_u32_e32 v0, v0, v4
	s_lshr_b32 s9, s9, 26
	v_add_u32_e32 v3, v11, v3
	v_and_b32_e32 v12, 32, v5
	v_ashrrev_i16_sdwa v0, v230, sext(v0) dst_sel:DWORD dst_unused:UNUSED_PAD src0_sel:DWORD src1_sel:BYTE_0
	v_add_u32_e32 v2, 0x2000, v2
	s_add_i32 s9, s8, s9
	v_bfe_i32 v13, v0, 0, 16
	v_lshl_or_b32 v0, v3, 13, v12
	v_ashrrev_i32_e32 v3, 31, v2
	s_ashr_i32 s10, s9, 6
	s_and_b32 s9, s9, 0xffc0
	v_lshrrev_b32_e32 v3, 22, v3
	s_sub_i32 s8, s8, s9
	v_add_u32_e32 v3, v2, v3
	s_bfe_i32 s9, s8, 0x80000
	v_ashrrev_i32_e32 v14, 10, v3
	s_bfe_u32 s9, s9, 0x3000c
	v_mul_i32_i24_e32 v3, 0x400, v14
	s_add_i32 s9, s8, s9
	v_sub_u32_e32 v2, v2, v3
	s_bfe_i32 s11, s9, 0x80000
	s_and_b32 s9, s9, 0xf8
	v_lshrrev_b32_e32 v3, 4, v2
	s_sub_i32 s8, s8, s9
	v_bitop3_b32 v2, v3, v2, 32 bitop3:0x6c
	s_lshl_b32 s10, s10, 3
	s_sext_i32_i16 s11, s11
	s_sext_i32_i8 s8, s8
	v_ashrrev_i32_e32 v4, 31, v2
	s_lshr_b32 s12, s11, 3
	s_add_i32 s44, s10, s8
	v_lshrrev_b32_e32 v4, 26, v4
	s_ashr_i32 s15, s13, 6
	s_ashr_i32 s45, s44, 31
	s_bfe_i64 s[10:11], s[12:13], 0x100000
	s_ashr_i32 s14, s13, 8
	v_add_u32_e32 v4, v2, v4
	s_lshl_b32 s55, s15, 10
	s_lshl_b64 s[8:9], s[44:45], 22
	s_lshl_b64 s[10:11], s[10:11], 22
	v_lshlrev_b32_e32 v3, 3, v14
	v_ashrrev_i32_e32 v15, 6, v4
	v_and_b32_e32 v4, 0xc0, v4
	s_add_u32 s48, s31, s10
	v_and_b32_e32 v3, 0x3fff0, v3
	v_lshlrev_b32_e32 v5, 5, v14
	v_sub_u32_e32 v2, v2, v4
	s_addc_u32 s49, s54, s11
	s_add_i32 s45, s55, 0
	v_add_lshl_u32 v0, v0, v13, 1
	v_add_u32_e32 v3, v15, v3
	v_and_b32_e32 v16, 32, v5
	v_ashrrev_i16_sdwa v2, v230, sext(v2) dst_sel:DWORD dst_unused:UNUSED_PAD src0_sel:DWORD src1_sel:BYTE_0
	s_add_i32 m0, s45, 0x10000
	v_bfe_i32 v17, v2, 0, 16
	v_lshl_or_b32 v2, v3, 13, v16
	global_load_lds_dwordx4 v0, s[48:49]
	s_add_i32 m0, s45, 0x12000
	v_add_lshl_u32 v142, v2, v17, 1
	s_add_u32 s10, s48, 0x200000
	global_load_lds_dwordx4 v142, s[48:49]
	s_addc_u32 s11, s49, 0
	s_add_i32 m0, s45, 0x14000
	v_mov_b32_e32 v143, v1
	global_load_lds_dwordx4 v0, s[10:11]
	s_add_i32 m0, s45, 0x16000
	s_add_u32 s46, s29, s8
	s_addc_u32 s47, s30, s9
	s_add_i32 s56, s45, 0x2000
	global_load_lds_dwordx4 v142, s[10:11]
	s_mov_b32 m0, s45
	s_add_u32 s8, s46, 0x200000
	global_load_lds_dwordx4 v0, s[46:47]
	s_mov_b32 m0, s56
	s_addc_u32 s9, s47, 0
	s_add_i32 s57, s45, 0x4000
	global_load_lds_dwordx4 v142, s[46:47]
	s_mov_b32 m0, s57
	s_add_i32 s58, s45, 0x6000
	global_load_lds_dwordx4 v0, s[8:9]
	s_mov_b32 m0, s58
	s_cmp_eq_u32 s14, 1
	global_load_lds_dwordx4 v142, s[8:9]
	s_load_dword s59, s[94:95], 0x0
	s_load_dwordx2 s[8:9], s[2:3], 0xa8
	v_lshl_add_u64 v[8:9], s[48:49], 0, v[0:1]
	v_lshl_add_u64 v[6:7], s[48:49], 0, v[142:143]
	v_lshl_add_u64 v[2:3], s[46:47], 0, v[0:1]
	s_cselect_b64 s[10:11], -1, 0
	s_cmp_lg_u32 s14, 1
	v_lshl_add_u64 v[4:5], s[46:47], 0, v[142:143]
	s_cbranch_scc1 .LBB0_349
	s_setprio 1
	s_barrier

; #define PG8_STAGE(bufoff, gbase, voff) do { _Pragma("unroll") for (int _i = 0; _i < 2; ++_i) \
;         __builtin_amdgcn_global_load_lds((const unsigned*)((const char*)(gbase) + (voff)[_i]), (LAS unsigned*)(lds + (bufoff) + ldsw + _i * 8192), 16, 0, 0); } while (0)
; #define PG8_LDA(dst, b, h) do { _Pragma("unroll") for (int m = 0; m < 4; ++m) _Pragma("unroll") for (int k = 0; k < 2; ++k) dst[m][k] = *(const LAS bf16x8*)(lds + PG8_SA(b, h) + aoff + m * 2048 + k * 1024); } while (0)
; #define PG8_LDB(dst, b, h) do { _Pragma("unroll") for (int n = 0; n < 2; ++n) _Pragma("unroll") for (int k = 0; k < 2; ++k) dst[n][k] = *(const LAS bf16x8*)(lds + PG8_SB(b, h) + boff + n * 2048 + k * 1024); } while (0)
; #define PG8_MMA(ai, bj, At, Bt) do { __builtin_amdgcn_s_setprio(1); _Pragma("unroll") for (int m = 0; m < 4; ++m) _Pragma("unroll") for (int n = 0; n < 2; ++n) _Pragma("unroll") for (int k = 0; k < 2; ++k) \
;         acc[ai][bj][m][n] = __builtin_amdgcn_mfma_f32_16x16x32_bf16(Bt[n][k], At[m][k], acc[ai][bj][m][n], 0, 0, 0); __builtin_amdgcn_s_setprio(0); } while (0)
; #define PG8_WAIT_V(n) asm volatile("s_waitcnt vmcnt(" #n ")" ::: "memory")
; #define PG8_WAIT_L(n) asm volatile("s_waitcnt lgkmcnt(" #n ")" ::: "memory")
; #define PG8_BAR __builtin_amdgcn_s_barrier()
; #define PG8_SCHED __builtin_amdgcn_sched_barrier(0)
; template <class Epi, class Sched, bool ALIGN_EPI = false, bool SP2 = false>
; __device__ __forceinline__ void gemm_phase(LAS unsigned char* lds, const Gemm g, const Sched& S, const Epi& E, const int tid_) {
;     ...
;             PG8_LDB(B0, 0, 0); PG8_LDB(B1, 0, 1); PG8_SCHED; PG8_LDA(At, 0, 0); PG8_STAGE(PG8_SA(1, 1), a1 + hstep, voffA);
;             PG8_WAIT_V(8); PG8_WAIT_L(0); PG8_BAR; PG8_MMA(0, 0, At, B0); PG8_MMA(0, 1, At, B1); PG8_BAR; PG8_SCHED;
;             PG8_LDA(At, 0, 1); PG8_STAGE(PG8_SB(0, 0), b2, voffB); PG8_STAGE(PG8_SB(0, 1), b2 + hstep, voffB); PG8_STAGE(PG8_SA(0, 0), a2, voffA);
;             PG8_WAIT_V(8); PG8_WAIT_L(0); PG8_BAR; PG8_MMA(1, 0, At, B0); PG8_MMA(1, 1, At, B1); PG8_BAR; PG8_SCHED;
.LBB0_359:
	s_add_u32 s48, s46, 0x100
	s_addc_u32 s49, s47, 0
	s_add_i32 s68, 0, 0x10000
	s_cmpk_eq_i32 s67, 0x7c
	s_cselect_b32 s53, s17, s49
	s_cselect_b32 s52, s21, s48
	s_cselect_b32 s51, s15, s66
	s_cselect_b32 s50, s64, s65
	s_add_i32 s69, 0, 0x14000
	v_add_u32_e32 v148, s68, v157
	v_add_u32_e32 v168, s69, v157
	ds_read_b128 v[130:133], v148
	ds_read_b128 v[134:137], v148 offset:1024
	ds_read_b128 v[138:141], v148 offset:2048
	ds_read_b128 v[148:151], v148 offset:3072
	ds_read_b128 v[152:155], v168
	ds_read_b128 v[160:163], v168 offset:1024
	ds_read_b128 v[164:167], v168 offset:2048
	ds_read_b128 v[168:171], v168 offset:3072
	s_add_i32 m0, s45, 0xc000
	ds_read_b128 v[172:175], v159
	ds_read_b128 v[176:179], v159 offset:1024
	ds_read_b128 v[180:183], v159 offset:2048
	ds_read_b128 v[200:203], v159 offset:3072
	ds_read_b128 v[204:207], v159 offset:4096
	ds_read_b128 v[208:211], v159 offset:5120
	ds_read_b128 v[212:215], v159 offset:6144
	ds_read_b128 v[216:219], v159 offset:7168
	global_load_lds_dwordx4 v144, s[46:47]
	s_add_i32 m0, s45, 0xe000
	s_nop 0
	global_load_lds_dwordx4 v146, s[46:47]
	s_waitcnt vmcnt(8)
	s_waitcnt lgkmcnt(0)
	s_barrier
	s_waitcnt lgkmcnt(0)
	v_mfma_f32_16x16x32_bf16 v[126:129], v[130:133], v[172:175], v[126:129]
	v_mfma_f32_16x16x32_bf16 v[122:125], v[138:141], v[172:175], v[122:125]
	v_mfma_f32_16x16x32_bf16 v[118:121], v[130:133], v[180:183], v[118:121]
	v_mfma_f32_16x16x32_bf16 v[106:109], v[138:141], v[180:183], v[106:109]
	v_mfma_f32_16x16x32_bf16 v[102:105], v[130:133], v[204:207], v[102:105]
	v_mfma_f32_16x16x32_bf16 v[90:93], v[138:141], v[204:207], v[90:93]
	v_mfma_f32_16x16x32_bf16 v[86:89], v[130:133], v[212:215], v[86:89]
	v_mfma_f32_16x16x32_bf16 v[74:77], v[138:141], v[212:215], v[74:77]
	v_mfma_f32_16x16x32_bf16 v[126:129], v[134:137], v[176:179], v[126:129]
	v_mfma_f32_16x16x32_bf16 v[122:125], v[148:151], v[176:179], v[122:125]
	v_mfma_f32_16x16x32_bf16 v[118:121], v[134:137], v[200:203], v[118:121]
	v_mfma_f32_16x16x32_bf16 v[106:109], v[148:151], v[200:203], v[106:109]
	v_mfma_f32_16x16x32_bf16 v[102:105], v[134:137], v[208:211], v[102:105]
	v_mfma_f32_16x16x32_bf16 v[90:93], v[148:151], v[208:211], v[90:93]
	v_mfma_f32_16x16x32_bf16 v[86:89], v[134:137], v[216:219], v[86:89]
	v_mfma_f32_16x16x32_bf16 v[74:77], v[148:151], v[216:219], v[74:77]
	v_mfma_f32_16x16x32_bf16 v[114:117], v[152:155], v[172:175], v[114:117]
	v_mfma_f32_16x16x32_bf16 v[110:113], v[164:167], v[172:175], v[110:113]
	v_mfma_f32_16x16x32_bf16 v[98:101], v[152:155], v[180:183], v[98:101]
	v_mfma_f32_16x16x32_bf16 v[94:97], v[164:167], v[180:183], v[94:97]
	v_mfma_f32_16x16x32_bf16 v[82:85], v[152:155], v[204:207], v[82:85]
	v_mfma_f32_16x16x32_bf16 v[78:81], v[164:167], v[204:207], v[78:81]
	v_mfma_f32_16x16x32_bf16 v[70:73], v[152:155], v[212:215], v[70:73]
	v_mfma_f32_16x16x32_bf16 v[66:69], v[164:167], v[212:215], v[66:69]
	v_mfma_f32_16x16x32_bf16 v[114:117], v[160:163], v[176:179], v[114:117]
	v_mfma_f32_16x16x32_bf16 v[110:113], v[168:171], v[176:179], v[110:113]
	v_mfma_f32_16x16x32_bf16 v[98:101], v[160:163], v[200:203], v[98:101]
	v_mfma_f32_16x16x32_bf16 v[94:97], v[168:171], v[200:203], v[94:97]
	v_mfma_f32_16x16x32_bf16 v[82:85], v[160:163], v[208:211], v[82:85]
	v_mfma_f32_16x16x32_bf16 v[78:81], v[168:171], v[208:211], v[78:81]
	v_mfma_f32_16x16x32_bf16 v[70:73], v[160:163], v[216:219], v[70:73]
	v_mfma_f32_16x16x32_bf16 v[66:69], v[168:171], v[216:219], v[66:69]
	s_barrier
	s_add_i32 s46, s68, s55
	s_mov_b32 m0, s46
	ds_read_b128 v[172:175], v159 offset:16384
	ds_read_b128 v[176:179], v159 offset:17408
	ds_read_b128 v[180:183], v159 offset:18432
	ds_read_b128 v[200:203], v159 offset:19456
	ds_read_b128 v[204:207], v159 offset:20480
	ds_read_b128 v[208:211], v159 offset:21504
	ds_read_b128 v[212:215], v159 offset:22528
	ds_read_b128 v[216:219], v159 offset:23552
	global_load_lds_dwordx4 v0, s[50:51]
	s_add_i32 m0, s46, 0x2000
	s_add_u32 s46, s50, 0x200000
	v_lshl_add_u64 v[192:193], s[50:51], 0, v[142:143]
	s_addc_u32 s47, s51, 0
	s_add_i32 s68, s69, s55
	global_load_lds_dwordx4 v142, s[50:51]
	s_mov_b32 m0, s68
	s_nop 0
	global_load_lds_dwordx4 v0, s[46:47]
	s_add_i32 m0, s68, 0x2000
	s_nop 0
	global_load_lds_dwordx4 v142, s[46:47]
	s_mov_b32 m0, s45
	s_nop 0
	global_load_lds_dwordx4 v0, s[52:53]
	s_mov_b32 m0, s56
	s_nop 0
	global_load_lds_dwordx4 v142, s[52:53]
	s_waitcnt vmcnt(8)
	s_waitcnt lgkmcnt(0)
	s_barrier
	s_waitcnt lgkmcnt(0)
	v_mfma_f32_16x16x32_bf16 v[62:65], v[130:133], v[172:175], v[62:65]
	v_mfma_f32_16x16x32_bf16 v[58:61], v[138:141], v[172:175], v[58:61]
	v_mfma_f32_16x16x32_bf16 v[54:57], v[130:133], v[180:183], v[54:57]
	v_mfma_f32_16x16x32_bf16 v[42:45], v[138:141], v[180:183], v[42:45]
	v_mfma_f32_16x16x32_bf16 v[38:41], v[130:133], v[204:207], v[38:41]
	v_mfma_f32_16x16x32_bf16 v[26:29], v[138:141], v[204:207], v[26:29]
	v_mfma_f32_16x16x32_bf16 v[22:25], v[130:133], v[212:215], v[22:25]
	v_mfma_f32_16x16x32_bf16 v[10:13], v[138:141], v[212:215], v[10:13]
	v_mfma_f32_16x16x32_bf16 v[62:65], v[134:137], v[176:179], v[62:65]
	v_mfma_f32_16x16x32_bf16 v[58:61], v[148:151], v[176:179], v[58:61]
	v_mfma_f32_16x16x32_bf16 v[54:57], v[134:137], v[200:203], v[54:57]
	v_mfma_f32_16x16x32_bf16 v[42:45], v[148:151], v[200:203], v[42:45]
	v_mfma_f32_16x16x32_bf16 v[38:41], v[134:137], v[208:211], v[38:41]
	v_mfma_f32_16x16x32_bf16 v[26:29], v[148:151], v[208:211], v[26:29]
	v_mfma_f32_16x16x32_bf16 v[22:25], v[134:137], v[216:219], v[22:25]
	v_mfma_f32_16x16x32_bf16 v[10:13], v[148:151], v[216:219], v[10:13]
	v_mfma_f32_16x16x32_bf16 v[50:53], v[152:155], v[172:175], v[50:53]
	v_mfma_f32_16x16x32_bf16 v[46:49], v[164:167], v[172:175], v[46:49]
	v_mfma_f32_16x16x32_bf16 v[34:37], v[152:155], v[180:183], v[34:37]
	v_mfma_f32_16x16x32_bf16 v[30:33], v[164:167], v[180:183], v[30:33]
	v_mfma_f32_16x16x32_bf16 v[18:21], v[152:155], v[204:207], v[18:21]
	v_mfma_f32_16x16x32_bf16 v[14:17], v[164:167], v[204:207], v[14:17]
	v_mfma_f32_16x16x32_bf16 v[6:9], v[152:155], v[212:215], v[6:9]
	v_mfma_f32_16x16x32_bf16 v[2:5], v[164:167], v[212:215], v[2:5]
	v_mfma_f32_16x16x32_bf16 v[50:53], v[160:163], v[176:179], v[50:53]
	v_mfma_f32_16x16x32_bf16 v[46:49], v[168:171], v[176:179], v[46:49]
	v_mfma_f32_16x16x32_bf16 v[34:37], v[160:163], v[200:203], v[34:37]
	v_mfma_f32_16x16x32_bf16 v[30:33], v[168:171], v[200:203], v[30:33]
	v_mfma_f32_16x16x32_bf16 v[18:21], v[160:163], v[208:211], v[18:21]
	v_mfma_f32_16x16x32_bf16 v[14:17], v[168:171], v[208:211], v[14:17]
	v_mfma_f32_16x16x32_bf16 v[6:9], v[160:163], v[216:219], v[6:9]
	v_mfma_f32_16x16x32_bf16 v[2:5], v[168:171], v[216:219], v[2:5]
	s_barrier
; #define PG8_STAGE(bufoff, gbase, voff) do { _Pragma("unroll") for (int _i = 0; _i < 2; ++_i) \
;         __builtin_amdgcn_global_load_lds((const unsigned*)((const char*)(gbase) + (voff)[_i]), (LAS unsigned*)(lds + (bufoff) + ldsw + _i * 8192), 16, 0, 0); } while (0)
; #define PG8_LDA(dst, b, h) do { _Pragma("unroll") for (int m = 0; m < 4; ++m) _Pragma("unroll") for (int k = 0; k < 2; ++k) dst[m][k] = *(const LAS bf16x8*)(lds + PG8_SA(b, h) + aoff + m * 2048 + k * 1024); } while (0)
; #define PG8_LDB(dst, b, h) do { _Pragma("unroll") for (int n = 0; n < 2; ++n) _Pragma("unroll") for (int k = 0; k < 2; ++k) dst[n][k] = *(const LAS bf16x8*)(lds + PG8_SB(b, h) + boff + n * 2048 + k * 1024); } while (0)
; #define PG8_MMA(ai, bj, At, Bt) do { __builtin_amdgcn_s_setprio(1); _Pragma("unroll") for (int m = 0; m < 4; ++m) _Pragma("unroll") for (int n = 0; n < 2; ++n) _Pragma("unroll") for (int k = 0; k < 2; ++k) \
;         acc[ai][bj][m][n] = __builtin_amdgcn_mfma_f32_16x16x32_bf16(Bt[n][k], At[m][k], acc[ai][bj][m][n], 0, 0, 0); __builtin_amdgcn_s_setprio(0); } while (0)
; #define PG8_WAIT_V(n) asm volatile("s_waitcnt vmcnt(" #n ")" ::: "memory")
; #define PG8_WAIT_L(n) asm volatile("s_waitcnt lgkmcnt(" #n ")" ::: "memory")
; #define PG8_BAR __builtin_amdgcn_s_barrier()
; #define PG8_SCHED __builtin_amdgcn_sched_barrier(0)
; template <class Epi, class Sched, bool ALIGN_EPI = false, bool SP2 = false>
; __device__ __forceinline__ void gemm_phase(LAS unsigned char* lds, const Gemm g, const Sched& S, const Epi& E, const int tid_) {
;     ...
;             PG8_LDB(B0, 1, 0); PG8_LDB(B1, 1, 1); PG8_SCHED; PG8_LDA(At, 1, 0); PG8_STAGE(PG8_SA(0, 1), a2 + hstep, voffA);
;             PG8_WAIT_V(8); PG8_WAIT_L(0); PG8_BAR; PG8_MMA(0, 0, At, B0); PG8_MMA(0, 1, At, B1); PG8_BAR; PG8_SCHED;
;             PG8_LDA(At, 1, 1); PG8_STAGE(PG8_SB(1, 0), b3, voffB); PG8_STAGE(PG8_SB(1, 1), b3 + hstep, voffB); PG8_STAGE(PG8_SA(1, 0), a3, voffA);
;             PG8_WAIT_V(8); PG8_WAIT_L(0); PG8_BAR; PG8_MMA(1, 0, At, B0); PG8_MMA(1, 1, At, B1); PG8_BAR; PG8_SCHED;
	s_add_i32 s68, 0, 0x18000
	s_add_i32 s69, 0, 0x1c000
	v_add_u32_e32 v148, s68, v157
	v_add_u32_e32 v168, s69, v157
	ds_read_b128 v[130:133], v148
	ds_read_b128 v[134:137], v148 offset:1024
	ds_read_b128 v[138:141], v148 offset:2048
	ds_read_b128 v[148:151], v148 offset:3072
	ds_read_b128 v[152:155], v168
	ds_read_b128 v[160:163], v168 offset:1024
	ds_read_b128 v[164:167], v168 offset:2048
	ds_read_b128 v[168:171], v168 offset:3072
	s_add_u32 s46, s52, 0x200000
	s_addc_u32 s47, s53, 0
	s_mov_b32 m0, s57
	ds_read_b128 v[172:175], v159 offset:32768
	ds_read_b128 v[176:179], v159 offset:33792
	ds_read_b128 v[180:183], v159 offset:34816
	ds_read_b128 v[200:203], v159 offset:35840
	ds_read_b128 v[204:207], v159 offset:36864
	ds_read_b128 v[208:211], v159 offset:37888
	ds_read_b128 v[212:215], v159 offset:38912
	ds_read_b128 v[216:219], v159 offset:39936
	global_load_lds_dwordx4 v0, s[46:47]
	s_mov_b32 m0, s58
	s_nop 0
	global_load_lds_dwordx4 v142, s[46:47]
	s_waitcnt vmcnt(8)
	s_waitcnt lgkmcnt(0)
	s_barrier
	s_waitcnt lgkmcnt(0)
	v_mfma_f32_16x16x32_bf16 v[126:129], v[130:133], v[172:175], v[126:129]
	v_mfma_f32_16x16x32_bf16 v[122:125], v[138:141], v[172:175], v[122:125]
	v_mfma_f32_16x16x32_bf16 v[118:121], v[130:133], v[180:183], v[118:121]
	v_mfma_f32_16x16x32_bf16 v[106:109], v[138:141], v[180:183], v[106:109]
	v_mfma_f32_16x16x32_bf16 v[102:105], v[130:133], v[204:207], v[102:105]
	v_mfma_f32_16x16x32_bf16 v[90:93], v[138:141], v[204:207], v[90:93]
	v_mfma_f32_16x16x32_bf16 v[86:89], v[130:133], v[212:215], v[86:89]
	v_mfma_f32_16x16x32_bf16 v[74:77], v[138:141], v[212:215], v[74:77]
	v_mfma_f32_16x16x32_bf16 v[126:129], v[134:137], v[176:179], v[126:129]
	v_mfma_f32_16x16x32_bf16 v[122:125], v[148:151], v[176:179], v[122:125]
	v_mfma_f32_16x16x32_bf16 v[118:121], v[134:137], v[200:203], v[118:121]
	v_mfma_f32_16x16x32_bf16 v[106:109], v[148:151], v[200:203], v[106:109]
	v_mfma_f32_16x16x32_bf16 v[102:105], v[134:137], v[208:211], v[102:105]
	v_mfma_f32_16x16x32_bf16 v[90:93], v[148:151], v[208:211], v[90:93]
	v_mfma_f32_16x16x32_bf16 v[86:89], v[134:137], v[216:219], v[86:89]
	v_mfma_f32_16x16x32_bf16 v[74:77], v[148:151], v[216:219], v[74:77]
	v_mfma_f32_16x16x32_bf16 v[114:117], v[152:155], v[172:175], v[114:117]
	v_mfma_f32_16x16x32_bf16 v[110:113], v[164:167], v[172:175], v[110:113]
	v_mfma_f32_16x16x32_bf16 v[98:101], v[152:155], v[180:183], v[98:101]
	v_mfma_f32_16x16x32_bf16 v[94:97], v[164:167], v[180:183], v[94:97]
	v_mfma_f32_16x16x32_bf16 v[82:85], v[152:155], v[204:207], v[82:85]
	v_mfma_f32_16x16x32_bf16 v[78:81], v[164:167], v[204:207], v[78:81]
	v_mfma_f32_16x16x32_bf16 v[70:73], v[152:155], v[212:215], v[70:73]
	v_mfma_f32_16x16x32_bf16 v[66:69], v[164:167], v[212:215], v[66:69]
	v_mfma_f32_16x16x32_bf16 v[114:117], v[160:163], v[176:179], v[114:117]
	v_mfma_f32_16x16x32_bf16 v[110:113], v[168:171], v[176:179], v[110:113]
	v_mfma_f32_16x16x32_bf16 v[98:101], v[160:163], v[200:203], v[98:101]
	v_mfma_f32_16x16x32_bf16 v[94:97], v[168:171], v[200:203], v[94:97]
	v_mfma_f32_16x16x32_bf16 v[82:85], v[160:163], v[208:211], v[82:85]
	v_mfma_f32_16x16x32_bf16 v[78:81], v[168:171], v[208:211], v[78:81]
	v_mfma_f32_16x16x32_bf16 v[70:73], v[160:163], v[216:219], v[70:73]
	v_mfma_f32_16x16x32_bf16 v[66:69], v[168:171], v[216:219], v[66:69]
	s_barrier
	s_add_i32 s46, s68, s55
	s_add_i32 m0, s46, 0xffffff80
	ds_read_b128 v[172:175], v159 offset:49152
	ds_read_b128 v[176:179], v159 offset:50176
	ds_read_b128 v[180:183], v159 offset:51200
	ds_read_b128 v[200:203], v159 offset:52224
	ds_read_b128 v[204:207], v159 offset:53248
	ds_read_b128 v[208:211], v159 offset:54272
	ds_read_b128 v[212:215], v159 offset:55296
	ds_read_b128 v[216:219], v159 offset:56320
	global_load_lds_dwordx4 v0, s[50:51] offset:128
	s_add_i32 m0, s46, 0x2000
	s_add_u32 s46, s50, 0x200080
	v_lshl_add_u64 v[184:185], v[192:193], 0, s[96:97]
	s_addc_u32 s47, s51, 0
	s_add_i32 s50, s69, s55
	global_load_lds_dwordx4 v[184:185], off
	s_mov_b32 m0, s50
	s_nop 0
	global_load_lds_dwordx4 v0, s[46:47]
	s_add_i32 m0, s50, 0x2000
	s_nop 0
	global_load_lds_dwordx4 v142, s[46:47]
	s_add_i32 m0, s60, 0xffffff80
	s_nop 0
	global_load_lds_dwordx4 v0, s[52:53] offset:128
	s_add_i32 m0, s61, 0xffffff80
	s_nop 0
	global_load_lds_dwordx4 v142, s[52:53] offset:128
	s_waitcnt vmcnt(8)
	s_waitcnt lgkmcnt(0)
	s_barrier
	s_waitcnt lgkmcnt(0)
	v_mfma_f32_16x16x32_bf16 v[62:65], v[130:133], v[172:175], v[62:65]
	v_mfma_f32_16x16x32_bf16 v[58:61], v[138:141], v[172:175], v[58:61]
	v_mfma_f32_16x16x32_bf16 v[54:57], v[130:133], v[180:183], v[54:57]
	v_mfma_f32_16x16x32_bf16 v[42:45], v[138:141], v[180:183], v[42:45]
	v_mfma_f32_16x16x32_bf16 v[38:41], v[130:133], v[204:207], v[38:41]
	v_mfma_f32_16x16x32_bf16 v[26:29], v[138:141], v[204:207], v[26:29]
	v_mfma_f32_16x16x32_bf16 v[22:25], v[130:133], v[212:215], v[22:25]
	v_mfma_f32_16x16x32_bf16 v[10:13], v[138:141], v[212:215], v[10:13]
	v_mfma_f32_16x16x32_bf16 v[62:65], v[134:137], v[176:179], v[62:65]
	v_mfma_f32_16x16x32_bf16 v[58:61], v[148:151], v[176:179], v[58:61]
	v_mfma_f32_16x16x32_bf16 v[54:57], v[134:137], v[200:203], v[54:57]
	v_mfma_f32_16x16x32_bf16 v[42:45], v[148:151], v[200:203], v[42:45]
	v_mfma_f32_16x16x32_bf16 v[38:41], v[134:137], v[208:211], v[38:41]
	v_mfma_f32_16x16x32_bf16 v[26:29], v[148:151], v[208:211], v[26:29]
	v_mfma_f32_16x16x32_bf16 v[22:25], v[134:137], v[216:219], v[22:25]
	v_mfma_f32_16x16x32_bf16 v[10:13], v[148:151], v[216:219], v[10:13]
	v_mfma_f32_16x16x32_bf16 v[50:53], v[152:155], v[172:175], v[50:53]
	v_mfma_f32_16x16x32_bf16 v[46:49], v[164:167], v[172:175], v[46:49]
	v_mfma_f32_16x16x32_bf16 v[34:37], v[152:155], v[180:183], v[34:37]
	v_mfma_f32_16x16x32_bf16 v[30:33], v[164:167], v[180:183], v[30:33]
	v_mfma_f32_16x16x32_bf16 v[18:21], v[152:155], v[204:207], v[18:21]
	v_mfma_f32_16x16x32_bf16 v[14:17], v[164:167], v[204:207], v[14:17]
	v_mfma_f32_16x16x32_bf16 v[6:9], v[152:155], v[212:215], v[6:9]
	v_mfma_f32_16x16x32_bf16 v[2:5], v[164:167], v[212:215], v[2:5]
	v_mfma_f32_16x16x32_bf16 v[50:53], v[160:163], v[176:179], v[50:53]
	v_mfma_f32_16x16x32_bf16 v[46:49], v[168:171], v[176:179], v[46:49]
	v_mfma_f32_16x16x32_bf16 v[34:37], v[160:163], v[200:203], v[34:37]
	v_mfma_f32_16x16x32_bf16 v[30:33], v[168:171], v[200:203], v[30:33]
	v_mfma_f32_16x16x32_bf16 v[18:21], v[160:163], v[208:211], v[18:21]
	v_mfma_f32_16x16x32_bf16 v[14:17], v[168:171], v[208:211], v[14:17]
	v_mfma_f32_16x16x32_bf16 v[6:9], v[160:163], v[216:219], v[6:9]
	v_mfma_f32_16x16x32_bf16 v[2:5], v[168:171], v[216:219], v[2:5]
	s_barrier
	s_add_i32 s67, s67, 2
	s_add_u32 s65, s65, 0x100
	s_addc_u32 s66, s66, 0
	s_cmpk_gt_u32 s67, 0x7d
	s_mov_b64 s[46:47], s[48:49]
	s_cbranch_scc0 .LBB0_359
	s_andn2_b64 vcc, s[12:13], s[40:41]
	s_cbranch_vccz .LBB0_362
	s_barrier
